# gemm_wide x4: LDS-DMA staging, swizzled LDS, ds_read prefetched one k-step ahead
# speedup vs baseline: 1.0770x; 1.0770x over previous
; DI int tidx() { int t = threadIdx.x; asm volatile("" : "+v"(t)); return t; }
; DI void gemm_wide(const bf16_t* __restrict__ W, int ldw, const bf16_t* __restrict__ X, int ldx, int nkt,
;                   f32x16 (&acc)[4][2], bf16_t* lds) {
;   const int tid = tidx(), lane = tid & 63, wv = tid >> 6, wn = wv & 1, wm = wv >> 1;
;   const int lr = lane & 31, lh = lane >> 5;
;   const int lrow = tid >> 3, lkc = (tid & 7) * 8;
;   const bf16_t* wp = W + (size_t)lrow * ldw + lkc;
;   const bf16_t* xp = X + (size_t)lrow * ldx + lkc;
;   const size_t wst = (size_t)64 * ldw, xst = (size_t)64 * ldx;
;   u32x4 rw0, rw1, rw2, rw3, rx0, rx1, rx2, rx3;
;     ...
;   u32x4 sw0, sw1, sw2, sw3, sx0, sx1, sx2, sx3;
;     ...
;   __syncthreads();
;   GW_GLOAD(0)
;   GW_LSTORE(0)
;   GW_GLOAD(1)
;   GW_GLOAD_B(nkt > 2 ? 2 : nkt - 1)
;   __syncthreads();
.LBB0_267:
	s_mul_i32 s0, s9, 0x88000
	s_mul_hi_i32 s1, s9, 0x88000
	s_add_u32 s0, s4, s0
	s_addc_u32 s1, s5, s1
	s_mul_i32 s28, s8, 0x88000
	s_mul_hi_i32 s29, s8, 0x88000
	s_add_u32 s28, s14, s28
	s_addc_u32 s29, s15, s29
	v_and_b32_e32 v128, 63, v195
	v_lshrrev_b32_e32 v129, 6, v195
	v_and_b32_e32 v130, 31, v128
	v_lshrrev_b32_e32 v131, 5, v128
	v_bfe_u32 v132, v130, 1, 3
	v_lshlrev_b32_e32 v133, 7, v130
	v_xor_b32_e32 v134, v131, v132
	v_lshl_add_u32 v135, v134, 4, v133
	v_and_b32_e32 v136, 1, v129
	v_lshlrev_b32_e32 v136, 14, v136
	v_lshrrev_b32_e32 v137, 1, v129
	v_lshlrev_b32_e32 v137, 13, v137
	v_add_u32_e32 v137, 0x10000, v137
	v_readfirstlane_b32 s98, v129
	v_add_u32_e32 v176, v136, v135
	v_xor_b32_e32 v177, 32, v176
	v_xor_b32_e32 v178, 64, v176
	v_xor_b32_e32 v179, 0x60, v176
	v_add_u32_e32 v180, v137, v135
	v_xor_b32_e32 v181, 32, v180
	v_xor_b32_e32 v182, 64, v180
	v_xor_b32_e32 v183, 0x60, v180
	s_lshl_b32 s98, s98, 12
	s_movk_i32 s100, 2176
	v_lshrrev_b32_e32 v138, 3, v128
	v_lshl_add_u32 v138, v129, 5, v138
	v_mul_lo_u32 v139, v138, s100
	v_and_b32_e32 v140, 7, v128
	v_lshrrev_b32_e32 v141, 4, v128
	v_xor_b32_e32 v142, v140, v141
	v_xor_b32_e32 v143, 4, v142
	v_lshl_add_u32 v184, v142, 4, v139
	v_lshl_add_u32 v185, v143, 4, v139
	v_add_u32_e32 v185, 0x4400, v185
	v_add_u32_e32 v186, 0x8800, v184
	v_add_u32_e32 v187, 0x8800, v185
	v_and_b32_e32 v140, 3, v129
	v_lshl_add_u32 v140, v140, 6, v128
	v_mul_lo_u32 v189, v140, s100
	s_cmp_lt_u32 s98, 0x4000
	s_cselect_b32 s100, s0, s28
	s_cselect_b32 s101, s1, s29
	s_add_u32 s100, s100, 0x100
	s_addc_u32 s101, s101, 0
	s_barrier
	s_mov_b32 m0, s98
	s_nop 0
	global_load_lds_dwordx4 v184, s[0:1]
	s_add_u32 m0, s98, 0x400
	s_nop 0
	global_load_lds_dwordx4 v185, s[0:1]
	s_add_u32 m0, s98, 0x800
	s_nop 0
	global_load_lds_dwordx4 v186, s[0:1]
	s_add_u32 m0, s98, 0xc00
	s_nop 0
	global_load_lds_dwordx4 v187, s[0:1]
	s_add_u32 s0, s0, 0x80
	s_addc_u32 s1, s1, 0
	s_add_u32 m0, s98, 0x10000
	s_nop 0
	global_load_lds_dwordx4 v184, s[28:29]
	s_add_u32 m0, s98, 0x10400
	s_nop 0
	global_load_lds_dwordx4 v185, s[28:29]
	s_add_u32 m0, s98, 0x10800
	s_nop 0
	global_load_lds_dwordx4 v186, s[28:29]
	s_add_u32 m0, s98, 0x10c00
	s_nop 0
	global_load_lds_dwordx4 v187, s[28:29]
	s_add_u32 s28, s28, 0x80
	s_addc_u32 s29, s29, 0
	s_add_u32 m0, s98, 0x8000
	s_nop 0
	global_load_lds_dwordx4 v184, s[0:1]
	s_add_u32 m0, s98, 0x8400
	s_nop 0
	global_load_lds_dwordx4 v185, s[0:1]
	s_add_u32 m0, s98, 0x8800
	s_nop 0
	global_load_lds_dwordx4 v186, s[0:1]
	s_add_u32 m0, s98, 0x8c00
	s_nop 0
	global_load_lds_dwordx4 v187, s[0:1]
	s_add_u32 s0, s0, 0x80
	s_addc_u32 s1, s1, 0
	v_mov_b64_e32 v[112:113], 0
	v_mov_b64_e32 v[114:115], 0
	v_mov_b64_e32 v[116:117], 0
	v_mov_b64_e32 v[118:119], 0
	v_mov_b64_e32 v[120:121], 0
	v_mov_b64_e32 v[122:123], 0
	v_mov_b64_e32 v[124:125], 0
	v_mov_b64_e32 v[126:127], 0
	v_mov_b64_e32 v[80:81], 0
	v_mov_b64_e32 v[82:83], 0
	v_mov_b64_e32 v[84:85], 0
	v_mov_b64_e32 v[86:87], 0
	v_mov_b64_e32 v[88:89], 0
	v_mov_b64_e32 v[90:91], 0
	v_mov_b64_e32 v[92:93], 0
	v_mov_b64_e32 v[94:95], 0
	v_mov_b64_e32 v[96:97], 0
	v_mov_b64_e32 v[98:99], 0
	v_mov_b64_e32 v[100:101], 0
	v_mov_b64_e32 v[102:103], 0
	v_mov_b64_e32 v[104:105], 0
	v_mov_b64_e32 v[106:107], 0
	v_mov_b64_e32 v[108:109], 0
	v_mov_b64_e32 v[110:111], 0
	v_mov_b64_e32 v[64:65], 0
	v_mov_b64_e32 v[66:67], 0
	v_mov_b64_e32 v[68:69], 0
	v_mov_b64_e32 v[70:71], 0
	v_mov_b64_e32 v[72:73], 0
	v_mov_b64_e32 v[74:75], 0
	v_mov_b64_e32 v[76:77], 0
	v_mov_b64_e32 v[78:79], 0
	v_mov_b64_e32 v[48:49], 0
	v_mov_b64_e32 v[50:51], 0
	v_mov_b64_e32 v[52:53], 0
	v_mov_b64_e32 v[54:55], 0
	v_mov_b64_e32 v[56:57], 0
	v_mov_b64_e32 v[58:59], 0
	v_mov_b64_e32 v[60:61], 0
	v_mov_b64_e32 v[62:63], 0
	v_mov_b64_e32 v[16:17], 0
	v_mov_b64_e32 v[18:19], 0
	v_mov_b64_e32 v[20:21], 0
	v_mov_b64_e32 v[22:23], 0
	v_mov_b64_e32 v[24:25], 0
	v_mov_b64_e32 v[26:27], 0
	v_mov_b64_e32 v[28:29], 0
	v_mov_b64_e32 v[30:31], 0
	v_mov_b64_e32 v[32:33], 0
	v_mov_b64_e32 v[34:35], 0
	v_mov_b64_e32 v[36:37], 0
	v_mov_b64_e32 v[38:39], 0
	v_mov_b64_e32 v[40:41], 0
	v_mov_b64_e32 v[42:43], 0
	v_mov_b64_e32 v[44:45], 0
	v_mov_b64_e32 v[46:47], 0
	v_mov_b64_e32 v[0:1], 0
	v_mov_b64_e32 v[2:3], 0
	v_mov_b64_e32 v[4:5], 0
	v_mov_b64_e32 v[6:7], 0
	v_mov_b64_e32 v[8:9], 0
	v_mov_b64_e32 v[10:11], 0
	v_mov_b64_e32 v[12:13], 0
	v_mov_b64_e32 v[14:15], 0
	s_waitcnt vmcnt(4)
	s_barrier
	ds_read_b128 v[144:147], v180 offset:0
	ds_read_b128 v[128:131], v176 offset:0
	ds_read_b128 v[148:151], v180 offset:4096
	ds_read_b128 v[132:135], v176 offset:4096
	ds_read_b128 v[136:139], v176 offset:8192
	ds_read_b128 v[140:143], v176 offset:12288
	s_movk_i32 s99, 7
; DI void gemm_wide(const bf16_t* __restrict__ W, int ldw, const bf16_t* __restrict__ X, int ldx, int nkt,
;                   f32x16 (&acc)[4][2], bf16_t* lds) {
;     ...
;   for (int kt = 0; kt < nkt; kt += 2) {
;     __builtin_amdgcn_sched_barrier(0);
;     GW_ST2(1, 0, rw0, rw1)                         GW_KS(kt, 0)
;     GW_ST2(1, 128 * LDT, rw2, rw3)                 GW_KS(kt, 1)
;     GW_ST2(1, WT_E, rx0, rx1)                      GW_KS(kt, 2)
;     GW_ST2(1, WT_E + 128 * LDT, rx2, rx3)          GW_KS(kt, 3)
;     __builtin_amdgcn_sched_barrier(0);
;     GW_GLOAD(kt + 3 < nkt ? kt + 3 : nkt - 1)
;     __syncthreads();
;     __builtin_amdgcn_sched_barrier(0);
;     GW_ST2(0, 0, sw0, sw1)                         GW_KS(kt + 1, 0)
;     GW_ST2(0, 128 * LDT, sw2, sw3)                 GW_KS(kt + 1, 1)
;     GW_ST2(0, WT_E, sx0, sx1)                      GW_KS(kt + 1, 2)
;     GW_ST2(0, WT_E + 128 * LDT, sx2, sx3)          GW_KS(kt + 1, 3)
;     __builtin_amdgcn_sched_barrier(0);
;     GW_GLOAD_B(kt + 4 < nkt ? kt + 4 : nkt - 1)
;     __syncthreads();
;   }
.Lgw_inproj_loop:
	s_waitcnt lgkmcnt(4)
	v_mfma_f32_32x32x16_bf16 v[112:127], v[128:131], v[144:147], v[112:127]
	s_add_u32 m0, s98, 0x18000
	ds_read_b128 v[168:171], v181 offset:0
	s_waitcnt lgkmcnt(4)
	v_mfma_f32_32x32x16_bf16 v[80:95], v[128:131], v[148:151], v[80:95]
	global_load_lds_dwordx4 v184, s[28:29]
	ds_read_b128 v[152:155], v177 offset:0
	s_waitcnt lgkmcnt(4)
	v_mfma_f32_32x32x16_bf16 v[96:111], v[132:135], v[144:147], v[96:111]
	s_add_u32 m0, s98, 0x18400
	ds_read_b128 v[172:175], v181 offset:4096
	v_mfma_f32_32x32x16_bf16 v[64:79], v[132:135], v[148:151], v[64:79]
	global_load_lds_dwordx4 v185, s[28:29]
	ds_read_b128 v[156:159], v177 offset:4096
	s_waitcnt lgkmcnt(5)
	v_mfma_f32_32x32x16_bf16 v[48:63], v[136:139], v[144:147], v[48:63]
	s_add_u32 m0, s98, 0x18800
	ds_read_b128 v[160:163], v177 offset:8192
	v_mfma_f32_32x32x16_bf16 v[16:31], v[136:139], v[148:151], v[16:31]
	global_load_lds_dwordx4 v186, s[28:29]
	ds_read_b128 v[164:167], v177 offset:12288
	s_waitcnt lgkmcnt(6)
	v_mfma_f32_32x32x16_bf16 v[32:47], v[140:143], v[144:147], v[32:47]
	s_add_u32 m0, s98, 0x18c00
	v_mfma_f32_32x32x16_bf16 v[0:15], v[140:143], v[148:151], v[0:15]
	global_load_lds_dwordx4 v187, s[28:29]
	s_add_u32 s28, s28, 0x80
	s_addc_u32 s29, s29, 0
	s_waitcnt lgkmcnt(4)
	v_mfma_f32_32x32x16_bf16 v[112:127], v[152:155], v[168:171], v[112:127]
	ds_read_b128 v[144:147], v182 offset:0
	s_waitcnt lgkmcnt(4)
	v_mfma_f32_32x32x16_bf16 v[80:95], v[152:155], v[172:175], v[80:95]
	ds_read_b128 v[128:131], v178 offset:0
	s_waitcnt lgkmcnt(4)
	v_mfma_f32_32x32x16_bf16 v[96:111], v[156:159], v[168:171], v[96:111]
	ds_read_b128 v[148:151], v182 offset:4096
	v_mfma_f32_32x32x16_bf16 v[64:79], v[156:159], v[172:175], v[64:79]
	ds_read_b128 v[132:135], v178 offset:4096
	s_waitcnt lgkmcnt(5)
	v_mfma_f32_32x32x16_bf16 v[48:63], v[160:163], v[168:171], v[48:63]
	ds_read_b128 v[136:139], v178 offset:8192
	v_mfma_f32_32x32x16_bf16 v[16:31], v[160:163], v[172:175], v[16:31]
	ds_read_b128 v[140:143], v178 offset:12288
	s_waitcnt lgkmcnt(6)
	v_mfma_f32_32x32x16_bf16 v[32:47], v[164:167], v[168:171], v[32:47]
	v_mfma_f32_32x32x16_bf16 v[0:15], v[164:167], v[172:175], v[0:15]
	s_waitcnt lgkmcnt(4)
	v_mfma_f32_32x32x16_bf16 v[112:127], v[128:131], v[144:147], v[112:127]
	ds_read_b128 v[168:171], v183 offset:0
	ds_read_b128 v[152:155], v179 offset:0
	s_waitcnt lgkmcnt(5)
	v_mfma_f32_32x32x16_bf16 v[80:95], v[128:131], v[148:151], v[80:95]
	ds_read_b128 v[172:175], v183 offset:4096
	ds_read_b128 v[156:159], v179 offset:4096
	s_waitcnt lgkmcnt(6)
	v_mfma_f32_32x32x16_bf16 v[96:111], v[132:135], v[144:147], v[96:111]
	ds_read_b128 v[160:163], v179 offset:8192
	ds_read_b128 v[164:167], v179 offset:12288
	v_mfma_f32_32x32x16_bf16 v[64:79], v[132:135], v[148:151], v[64:79]
	s_waitcnt lgkmcnt(7)
	v_mfma_f32_32x32x16_bf16 v[48:63], v[136:139], v[144:147], v[48:63]
	v_mfma_f32_32x32x16_bf16 v[16:31], v[136:139], v[148:151], v[16:31]
	s_waitcnt lgkmcnt(6)
	v_mfma_f32_32x32x16_bf16 v[32:47], v[140:143], v[144:147], v[32:47]
	v_mfma_f32_32x32x16_bf16 v[0:15], v[140:143], v[148:151], v[0:15]
	s_waitcnt vmcnt(0) lgkmcnt(0)
	s_barrier
	v_mfma_f32_32x32x16_bf16 v[112:127], v[152:155], v[168:171], v[112:127]
	s_mov_b32 m0, s98
	ds_read_b128 v[144:147], v180 offset:32768
	v_mfma_f32_32x32x16_bf16 v[80:95], v[152:155], v[172:175], v[80:95]
	ds_read_b128 v[128:131], v176 offset:32768
	global_load_lds_dwordx4 v184, s[0:1]
	v_mfma_f32_32x32x16_bf16 v[96:111], v[156:159], v[168:171], v[96:111]
	s_add_u32 m0, s98, 0x400
	ds_read_b128 v[148:151], v180 offset:36864
	v_mfma_f32_32x32x16_bf16 v[64:79], v[156:159], v[172:175], v[64:79]
	ds_read_b128 v[132:135], v176 offset:36864
	global_load_lds_dwordx4 v185, s[0:1]
	v_mfma_f32_32x32x16_bf16 v[48:63], v[160:163], v[168:171], v[48:63]
	s_add_u32 m0, s98, 0x800
	ds_read_b128 v[136:139], v176 offset:40960
	v_mfma_f32_32x32x16_bf16 v[16:31], v[160:163], v[172:175], v[16:31]
	ds_read_b128 v[140:143], v176 offset:45056
	global_load_lds_dwordx4 v186, s[0:1]
	v_mfma_f32_32x32x16_bf16 v[32:47], v[164:167], v[168:171], v[32:47]
	s_add_u32 m0, s98, 0xc00
	v_mfma_f32_32x32x16_bf16 v[0:15], v[164:167], v[172:175], v[0:15]
	global_load_lds_dwordx4 v187, s[0:1]
	s_add_u32 s0, s0, 0x80
	s_addc_u32 s1, s1, 0
	s_waitcnt lgkmcnt(4)
	v_mfma_f32_32x32x16_bf16 v[112:127], v[128:131], v[144:147], v[112:127]
	s_add_u32 m0, s98, 0x10000
	ds_read_b128 v[168:171], v181 offset:32768
	s_waitcnt lgkmcnt(4)
	v_mfma_f32_32x32x16_bf16 v[80:95], v[128:131], v[148:151], v[80:95]
	global_load_lds_dwordx4 v184, s[28:29]
	ds_read_b128 v[152:155], v177 offset:32768
	s_waitcnt lgkmcnt(4)
	v_mfma_f32_32x32x16_bf16 v[96:111], v[132:135], v[144:147], v[96:111]
	s_add_u32 m0, s98, 0x10400
	ds_read_b128 v[172:175], v181 offset:36864
	v_mfma_f32_32x32x16_bf16 v[64:79], v[132:135], v[148:151], v[64:79]
	global_load_lds_dwordx4 v185, s[28:29]
	ds_read_b128 v[156:159], v177 offset:36864
	s_waitcnt lgkmcnt(5)
	v_mfma_f32_32x32x16_bf16 v[48:63], v[136:139], v[144:147], v[48:63]
	s_add_u32 m0, s98, 0x10800
	ds_read_b128 v[160:163], v177 offset:40960
	v_mfma_f32_32x32x16_bf16 v[16:31], v[136:139], v[148:151], v[16:31]
	global_load_lds_dwordx4 v186, s[28:29]
	ds_read_b128 v[164:167], v177 offset:45056
	s_waitcnt lgkmcnt(6)
	v_mfma_f32_32x32x16_bf16 v[32:47], v[140:143], v[144:147], v[32:47]
	s_add_u32 m0, s98, 0x10c00
	v_mfma_f32_32x32x16_bf16 v[0:15], v[140:143], v[148:151], v[0:15]
	global_load_lds_dwordx4 v187, s[28:29]
	s_add_u32 s28, s28, 0x80
	s_addc_u32 s29, s29, 0
	s_waitcnt lgkmcnt(4)
	v_mfma_f32_32x32x16_bf16 v[112:127], v[152:155], v[168:171], v[112:127]
	ds_read_b128 v[144:147], v182 offset:32768
	s_waitcnt lgkmcnt(4)
; DI void gemm_wide(const bf16_t* __restrict__ W, int ldw, const bf16_t* __restrict__ X, int ldx, int nkt,
;                   f32x16 (&acc)[4][2], bf16_t* lds) {
;     ...
;   for (int kt = 0; kt < nkt; kt += 2) {
;     __builtin_amdgcn_sched_barrier(0);
;     GW_ST2(1, 0, rw0, rw1)                         GW_KS(kt, 0)
;     GW_ST2(1, 128 * LDT, rw2, rw3)                 GW_KS(kt, 1)
;     GW_ST2(1, WT_E, rx0, rx1)                      GW_KS(kt, 2)
;     GW_ST2(1, WT_E + 128 * LDT, rx2, rx3)          GW_KS(kt, 3)
;     __builtin_amdgcn_sched_barrier(0);
;     GW_GLOAD(kt + 3 < nkt ? kt + 3 : nkt - 1)
;     __syncthreads();
;     __builtin_amdgcn_sched_barrier(0);
;     GW_ST2(0, 0, sw0, sw1)                         GW_KS(kt + 1, 0)
;     GW_ST2(0, 128 * LDT, sw2, sw3)                 GW_KS(kt + 1, 1)
;     GW_ST2(0, WT_E, sx0, sx1)                      GW_KS(kt + 1, 2)
;     GW_ST2(0, WT_E + 128 * LDT, sx2, sx3)          GW_KS(kt + 1, 3)
;     __builtin_amdgcn_sched_barrier(0);
;     GW_GLOAD_B(kt + 4 < nkt ? kt + 4 : nkt - 1)
;     __syncthreads();
;   }
	v_mfma_f32_32x32x16_bf16 v[80:95], v[152:155], v[172:175], v[80:95]
	ds_read_b128 v[128:131], v178 offset:32768
	s_waitcnt lgkmcnt(4)
	v_mfma_f32_32x32x16_bf16 v[96:111], v[156:159], v[168:171], v[96:111]
	ds_read_b128 v[148:151], v182 offset:36864
	v_mfma_f32_32x32x16_bf16 v[64:79], v[156:159], v[172:175], v[64:79]
	ds_read_b128 v[132:135], v178 offset:36864
	s_waitcnt lgkmcnt(5)
	v_mfma_f32_32x32x16_bf16 v[48:63], v[160:163], v[168:171], v[48:63]
	ds_read_b128 v[136:139], v178 offset:40960
	v_mfma_f32_32x32x16_bf16 v[16:31], v[160:163], v[172:175], v[16:31]
	ds_read_b128 v[140:143], v178 offset:45056
	s_waitcnt lgkmcnt(6)
	v_mfma_f32_32x32x16_bf16 v[32:47], v[164:167], v[168:171], v[32:47]
	v_mfma_f32_32x32x16_bf16 v[0:15], v[164:167], v[172:175], v[0:15]
	s_waitcnt lgkmcnt(4)
	v_mfma_f32_32x32x16_bf16 v[112:127], v[128:131], v[144:147], v[112:127]
	ds_read_b128 v[168:171], v183 offset:32768
	ds_read_b128 v[152:155], v179 offset:32768
	s_waitcnt lgkmcnt(5)
	v_mfma_f32_32x32x16_bf16 v[80:95], v[128:131], v[148:151], v[80:95]
	ds_read_b128 v[172:175], v183 offset:36864
	ds_read_b128 v[156:159], v179 offset:36864
	s_waitcnt lgkmcnt(6)
	v_mfma_f32_32x32x16_bf16 v[96:111], v[132:135], v[144:147], v[96:111]
	ds_read_b128 v[160:163], v179 offset:40960
	ds_read_b128 v[164:167], v179 offset:45056
	v_mfma_f32_32x32x16_bf16 v[64:79], v[132:135], v[148:151], v[64:79]
	s_waitcnt lgkmcnt(7)
	v_mfma_f32_32x32x16_bf16 v[48:63], v[136:139], v[144:147], v[48:63]
	v_mfma_f32_32x32x16_bf16 v[16:31], v[136:139], v[148:151], v[16:31]
	s_waitcnt lgkmcnt(6)
	v_mfma_f32_32x32x16_bf16 v[32:47], v[140:143], v[144:147], v[32:47]
	v_mfma_f32_32x32x16_bf16 v[0:15], v[140:143], v[148:151], v[0:15]
	s_waitcnt vmcnt(0) lgkmcnt(0)
	s_barrier
	v_mfma_f32_32x32x16_bf16 v[112:127], v[152:155], v[168:171], v[112:127]
	s_add_u32 m0, s98, 0x8000
	ds_read_b128 v[144:147], v180 offset:0
	v_mfma_f32_32x32x16_bf16 v[80:95], v[152:155], v[172:175], v[80:95]
	ds_read_b128 v[128:131], v176 offset:0
	global_load_lds_dwordx4 v184, s[0:1]
	v_mfma_f32_32x32x16_bf16 v[96:111], v[156:159], v[168:171], v[96:111]
	s_add_u32 m0, s98, 0x8400
	ds_read_b128 v[148:151], v180 offset:4096
	v_mfma_f32_32x32x16_bf16 v[64:79], v[156:159], v[172:175], v[64:79]
	ds_read_b128 v[132:135], v176 offset:4096
	global_load_lds_dwordx4 v185, s[0:1]
	v_mfma_f32_32x32x16_bf16 v[48:63], v[160:163], v[168:171], v[48:63]
	s_add_u32 m0, s98, 0x8800
	ds_read_b128 v[136:139], v176 offset:8192
	v_mfma_f32_32x32x16_bf16 v[16:31], v[160:163], v[172:175], v[16:31]
	ds_read_b128 v[140:143], v176 offset:12288
	global_load_lds_dwordx4 v186, s[0:1]
	v_mfma_f32_32x32x16_bf16 v[32:47], v[164:167], v[168:171], v[32:47]
	s_add_u32 m0, s98, 0x8c00
	v_mfma_f32_32x32x16_bf16 v[0:15], v[164:167], v[172:175], v[0:15]
	global_load_lds_dwordx4 v187, s[0:1]
	s_add_u32 s0, s0, 0x80
	s_addc_u32 s1, s1, 0
	s_sub_u32 s99, s99, 1
	s_cmp_lg_u32 s99, 0
	s_cbranch_scc1 .Lgw_inproj_loop
	s_waitcnt lgkmcnt(4)
	v_mfma_f32_32x32x16_bf16 v[112:127], v[128:131], v[144:147], v[112:127]
	s_add_u32 m0, s98, 0x18000
	ds_read_b128 v[168:171], v181 offset:0
	s_waitcnt lgkmcnt(4)
	v_mfma_f32_32x32x16_bf16 v[80:95], v[128:131], v[148:151], v[80:95]
	global_load_lds_dwordx4 v184, s[28:29]
	ds_read_b128 v[152:155], v177 offset:0
	s_waitcnt lgkmcnt(4)
	v_mfma_f32_32x32x16_bf16 v[96:111], v[132:135], v[144:147], v[96:111]
	s_add_u32 m0, s98, 0x18400
	ds_read_b128 v[172:175], v181 offset:4096
	v_mfma_f32_32x32x16_bf16 v[64:79], v[132:135], v[148:151], v[64:79]
	global_load_lds_dwordx4 v185, s[28:29]
	ds_read_b128 v[156:159], v177 offset:4096
	s_waitcnt lgkmcnt(5)
	v_mfma_f32_32x32x16_bf16 v[48:63], v[136:139], v[144:147], v[48:63]
	s_add_u32 m0, s98, 0x18800
	ds_read_b128 v[160:163], v177 offset:8192
	v_mfma_f32_32x32x16_bf16 v[16:31], v[136:139], v[148:151], v[16:31]
	global_load_lds_dwordx4 v186, s[28:29]
	ds_read_b128 v[164:167], v177 offset:12288
	s_waitcnt lgkmcnt(6)
	v_mfma_f32_32x32x16_bf16 v[32:47], v[140:143], v[144:147], v[32:47]
	s_add_u32 m0, s98, 0x18c00
	v_mfma_f32_32x32x16_bf16 v[0:15], v[140:143], v[148:151], v[0:15]
	global_load_lds_dwordx4 v187, s[28:29]
	s_add_u32 s28, s28, 0x80
	s_addc_u32 s29, s29, 0
	s_waitcnt lgkmcnt(4)
	v_mfma_f32_32x32x16_bf16 v[112:127], v[152:155], v[168:171], v[112:127]
	ds_read_b128 v[144:147], v182 offset:0
	s_waitcnt lgkmcnt(4)
	v_mfma_f32_32x32x16_bf16 v[80:95], v[152:155], v[172:175], v[80:95]
	ds_read_b128 v[128:131], v178 offset:0
	s_waitcnt lgkmcnt(4)
	v_mfma_f32_32x32x16_bf16 v[96:111], v[156:159], v[168:171], v[96:111]
	ds_read_b128 v[148:151], v182 offset:4096
	v_mfma_f32_32x32x16_bf16 v[64:79], v[156:159], v[172:175], v[64:79]
	ds_read_b128 v[132:135], v178 offset:4096
	s_waitcnt lgkmcnt(5)
	v_mfma_f32_32x32x16_bf16 v[48:63], v[160:163], v[168:171], v[48:63]
	ds_read_b128 v[136:139], v178 offset:8192
	v_mfma_f32_32x32x16_bf16 v[16:31], v[160:163], v[172:175], v[16:31]
	ds_read_b128 v[140:143], v178 offset:12288
	s_waitcnt lgkmcnt(6)
	v_mfma_f32_32x32x16_bf16 v[32:47], v[164:167], v[168:171], v[32:47]
	v_mfma_f32_32x32x16_bf16 v[0:15], v[164:167], v[172:175], v[0:15]
	s_waitcnt lgkmcnt(4)
	v_mfma_f32_32x32x16_bf16 v[112:127], v[128:131], v[144:147], v[112:127]
	ds_read_b128 v[168:171], v183 offset:0
	ds_read_b128 v[152:155], v179 offset:0
	s_waitcnt lgkmcnt(5)
	v_mfma_f32_32x32x16_bf16 v[80:95], v[128:131], v[148:151], v[80:95]
	ds_read_b128 v[172:175], v183 offset:4096
	ds_read_b128 v[156:159], v179 offset:4096
	s_waitcnt lgkmcnt(6)
	v_mfma_f32_32x32x16_bf16 v[96:111], v[132:135], v[144:147], v[96:111]
	ds_read_b128 v[160:163], v179 offset:8192
	ds_read_b128 v[164:167], v179 offset:12288
	v_mfma_f32_32x32x16_bf16 v[64:79], v[132:135], v[148:151], v[64:79]
	s_waitcnt lgkmcnt(7)
	v_mfma_f32_32x32x16_bf16 v[48:63], v[136:139], v[144:147], v[48:63]
	v_mfma_f32_32x32x16_bf16 v[16:31], v[136:139], v[148:151], v[16:31]
	s_waitcnt lgkmcnt(6)
	v_mfma_f32_32x32x16_bf16 v[32:47], v[140:143], v[144:147], v[32:47]
	v_mfma_f32_32x32x16_bf16 v[0:15], v[140:143], v[148:151], v[0:15]
	s_waitcnt vmcnt(0) lgkmcnt(0)
	s_barrier
; DI void gemm_wide(const bf16_t* __restrict__ W, int ldw, const bf16_t* __restrict__ X, int ldx, int nkt,
;                   f32x16 (&acc)[4][2], bf16_t* lds) {
;     ...
;   for (int kt = 0; kt < nkt; kt += 2) {
;     __builtin_amdgcn_sched_barrier(0);
;     GW_ST2(1, 0, rw0, rw1)                         GW_KS(kt, 0)
;     GW_ST2(1, 128 * LDT, rw2, rw3)                 GW_KS(kt, 1)
;     GW_ST2(1, WT_E, rx0, rx1)                      GW_KS(kt, 2)
;     GW_ST2(1, WT_E + 128 * LDT, rx2, rx3)          GW_KS(kt, 3)
;     __builtin_amdgcn_sched_barrier(0);
;     GW_GLOAD(kt + 3 < nkt ? kt + 3 : nkt - 1)
;     __syncthreads();
;     __builtin_amdgcn_sched_barrier(0);
;     GW_ST2(0, 0, sw0, sw1)                         GW_KS(kt + 1, 0)
;     GW_ST2(0, 128 * LDT, sw2, sw3)                 GW_KS(kt + 1, 1)
;     GW_ST2(0, WT_E, sx0, sx1)                      GW_KS(kt + 1, 2)
;     GW_ST2(0, WT_E + 128 * LDT, sx2, sx3)          GW_KS(kt + 1, 3)
;     __builtin_amdgcn_sched_barrier(0);
;     GW_GLOAD_B(kt + 4 < nkt ? kt + 4 : nkt - 1)
;     __syncthreads();
;   }
; DI bool epi_inproj_chunk(const P& p, int layer, int ch, int m0w, f32x16 (&a0)[2], f32x16 (&a1)[2], bf16_t* stg, int cp,
;                          bf16_t*& rdst, int& rldd, int& rcoff, float rs0, float rs1) {
;     ...
;   if (ch < 8) { type = NORM; dst = (bf16_t*)(ws + O_AQ); coff = ch * 64; gain = gains; scl = QSCL; }
;   else if (ch < 16) { type = NORM; dst = (bf16_t*)(ws + O_AK); coff = (ch - 8) * 64; gain = gains + 64; }
;   else if (ch < 24) { type = TRANS; dst = (bf16_t*)(ws + O_AVT); nh = 4; dv = 128; hd = (ch - 16) >> 1; doff = ((ch - 16) & 1) * 64; }
;   else if (ch < 32) { type = NORM; dst = (bf16_t*)(ws + O_BQ); coff = (ch - 24) * 64; gain = gains + 128; scl = QSCL; }
;   else if (ch < 34) { type = NORM; dst = (bf16_t*)(ws + O_BK); ldd = 128; coff = (ch - 32) * 64; gain = gains + 192; }
;   else if (ch < 36) { type = TRANS; dst = (bf16_t*)(ws + O_BVT); hd = ch - 34; }
;   else if (ch < 44) { type = NORM; dst = (bf16_t*)(ws + O_CQ); coff = (ch - 36) * 64; gain = gains + 256; scl = QSCL; }
;   else if (ch < 46) { type = RAW; dst = (bf16_t*)(ws + O_CK); ldd = 128; coff = (ch - 44) * 64; }
;   else if (ch < 48) { type = RAW; dst = (bf16_t*)(ws + O_CV); ldd = 128; coff = (ch - 46) * 64; }
;   else if (ch < 50) { type = NORM; dst = (bf16_t*)(ws + O_KS); ldd = 128; coff = (ch - 48) * 64; gain = gains + 384; }
	v_mfma_f32_32x32x16_bf16 v[112:127], v[152:155], v[168:171], v[112:127]
	ds_read_b128 v[144:147], v180 offset:32768
	v_mfma_f32_32x32x16_bf16 v[80:95], v[152:155], v[172:175], v[80:95]
	ds_read_b128 v[128:131], v176 offset:32768
	v_mfma_f32_32x32x16_bf16 v[96:111], v[156:159], v[168:171], v[96:111]
	ds_read_b128 v[148:151], v180 offset:36864
	v_mfma_f32_32x32x16_bf16 v[64:79], v[156:159], v[172:175], v[64:79]
	ds_read_b128 v[132:135], v176 offset:36864
	v_mfma_f32_32x32x16_bf16 v[48:63], v[160:163], v[168:171], v[48:63]
	ds_read_b128 v[136:139], v176 offset:40960
	v_mfma_f32_32x32x16_bf16 v[16:31], v[160:163], v[172:175], v[16:31]
	ds_read_b128 v[140:143], v176 offset:45056
	v_mfma_f32_32x32x16_bf16 v[32:47], v[164:167], v[168:171], v[32:47]
	v_mfma_f32_32x32x16_bf16 v[0:15], v[164:167], v[172:175], v[0:15]
	s_waitcnt lgkmcnt(4)
	v_mfma_f32_32x32x16_bf16 v[112:127], v[128:131], v[144:147], v[112:127]
	ds_read_b128 v[168:171], v181 offset:32768
	s_waitcnt lgkmcnt(4)
	v_mfma_f32_32x32x16_bf16 v[80:95], v[128:131], v[148:151], v[80:95]
	ds_read_b128 v[152:155], v177 offset:32768
	s_waitcnt lgkmcnt(4)
	v_mfma_f32_32x32x16_bf16 v[96:111], v[132:135], v[144:147], v[96:111]
	ds_read_b128 v[172:175], v181 offset:36864
	v_mfma_f32_32x32x16_bf16 v[64:79], v[132:135], v[148:151], v[64:79]
	ds_read_b128 v[156:159], v177 offset:36864
	s_waitcnt lgkmcnt(5)
	v_mfma_f32_32x32x16_bf16 v[48:63], v[136:139], v[144:147], v[48:63]
	ds_read_b128 v[160:163], v177 offset:40960
	v_mfma_f32_32x32x16_bf16 v[16:31], v[136:139], v[148:151], v[16:31]
	ds_read_b128 v[164:167], v177 offset:45056
	s_waitcnt lgkmcnt(6)
	v_mfma_f32_32x32x16_bf16 v[32:47], v[140:143], v[144:147], v[32:47]
	v_mfma_f32_32x32x16_bf16 v[0:15], v[140:143], v[148:151], v[0:15]
	s_waitcnt lgkmcnt(4)
	v_mfma_f32_32x32x16_bf16 v[112:127], v[152:155], v[168:171], v[112:127]
	ds_read_b128 v[144:147], v182 offset:32768
	s_waitcnt lgkmcnt(4)
	v_mfma_f32_32x32x16_bf16 v[80:95], v[152:155], v[172:175], v[80:95]
	ds_read_b128 v[128:131], v178 offset:32768
	s_waitcnt lgkmcnt(4)
	v_mfma_f32_32x32x16_bf16 v[96:111], v[156:159], v[168:171], v[96:111]
	ds_read_b128 v[148:151], v182 offset:36864
	v_mfma_f32_32x32x16_bf16 v[64:79], v[156:159], v[172:175], v[64:79]
	ds_read_b128 v[132:135], v178 offset:36864
	s_waitcnt lgkmcnt(5)
	v_mfma_f32_32x32x16_bf16 v[48:63], v[160:163], v[168:171], v[48:63]
	ds_read_b128 v[136:139], v178 offset:40960
	v_mfma_f32_32x32x16_bf16 v[16:31], v[160:163], v[172:175], v[16:31]
	ds_read_b128 v[140:143], v178 offset:45056
	s_waitcnt lgkmcnt(6)
	v_mfma_f32_32x32x16_bf16 v[32:47], v[164:167], v[168:171], v[32:47]
	v_mfma_f32_32x32x16_bf16 v[0:15], v[164:167], v[172:175], v[0:15]
	s_waitcnt lgkmcnt(4)
	v_mfma_f32_32x32x16_bf16 v[112:127], v[128:131], v[144:147], v[112:127]
	ds_read_b128 v[168:171], v183 offset:32768
	ds_read_b128 v[152:155], v179 offset:32768
	s_waitcnt lgkmcnt(5)
	v_mfma_f32_32x32x16_bf16 v[80:95], v[128:131], v[148:151], v[80:95]
	ds_read_b128 v[172:175], v183 offset:36864
	ds_read_b128 v[156:159], v179 offset:36864
	s_waitcnt lgkmcnt(6)
	v_mfma_f32_32x32x16_bf16 v[96:111], v[132:135], v[144:147], v[96:111]
	ds_read_b128 v[160:163], v179 offset:40960
	ds_read_b128 v[164:167], v179 offset:45056
	v_mfma_f32_32x32x16_bf16 v[64:79], v[132:135], v[148:151], v[64:79]
	s_waitcnt lgkmcnt(7)
	v_mfma_f32_32x32x16_bf16 v[48:63], v[136:139], v[144:147], v[48:63]
	v_mfma_f32_32x32x16_bf16 v[16:31], v[136:139], v[148:151], v[16:31]
	s_waitcnt lgkmcnt(6)
	v_mfma_f32_32x32x16_bf16 v[32:47], v[140:143], v[144:147], v[32:47]
	v_mfma_f32_32x32x16_bf16 v[0:15], v[140:143], v[148:151], v[0:15]
	s_waitcnt vmcnt(0) lgkmcnt(0)
	s_barrier
	v_mfma_f32_32x32x16_bf16 v[112:127], v[152:155], v[168:171], v[112:127]
	v_mfma_f32_32x32x16_bf16 v[80:95], v[152:155], v[172:175], v[80:95]
	v_mfma_f32_32x32x16_bf16 v[96:111], v[156:159], v[168:171], v[96:111]
	v_mfma_f32_32x32x16_bf16 v[64:79], v[156:159], v[172:175], v[64:79]
	v_mfma_f32_32x32x16_bf16 v[48:63], v[160:163], v[168:171], v[48:63]
	v_mfma_f32_32x32x16_bf16 v[16:31], v[160:163], v[172:175], v[16:31]
	v_mfma_f32_32x32x16_bf16 v[32:47], v[164:167], v[168:171], v[32:47]
	v_mfma_f32_32x32x16_bf16 v[0:15], v[164:167], v[172:175], v[0:15]
	s_nop 15
	s_waitcnt vmcnt(9)
	v_mov_b32_e32 v130, v195
	s_lshl_b32 s66, s9, 2
	v_ashrrev_i32_e32 v131, 6, v130
	v_lshlrev_b32_e32 v128, 1, v131
	v_and_or_b32 v154, v128, 2, s66
	s_waitcnt vmcnt(0)
	v_mov_b32_e32 v142, v195
	v_cmp_lt_i32_e32 vcc, 7, v154
	s_mov_b64 s[40:41], 0
	s_and_saveexec_b64 s[0:1], vcc
	s_xor_b64 s[0:1], exec, s[0:1]
	s_cbranch_execz .LBB0_325
	s_cmp_gt_u32 s66, 15
	s_cbranch_scc0 .LBB0_286
	s_cmp_gt_u32 s66, 23
	s_cbranch_scc0 .LBB0_287
	s_cmp_gt_u32 s66, 31
	s_cbranch_scc0 .LBB0_289
	v_cmp_lt_u32_e32 vcc, 33, v154
	s_and_saveexec_b64 s[30:31], vcc
	s_xor_b64 s[30:31], exec, s[30:31]
	s_cbranch_execz .LBB0_316
	s_cmp_gt_u32 s66, 35
	s_cbranch_scc0 .LBB0_290
	s_cmp_gt_u32 s66, 43
	s_cbranch_scc0 .LBB0_291
	v_cmp_lt_u32_e32 vcc, 45, v154
	s_mov_b64 s[44:45], 0
	s_and_saveexec_b64 s[38:39], vcc
	s_xor_b64 s[40:41], exec, s[38:39]
	s_cbranch_execz .LBB0_309
	s_mov_b64 s[38:39], -1
	s_mov_b64 s[62:63], 0
	s_cmp_gt_u32 s66, 47
	s_mov_b64 s[46:47], 0
	s_cbranch_scc0 .LBB0_306
	v_cmp_lt_u32_e32 vcc, 49, v154
	s_and_saveexec_b64 s[38:39], vcc
	s_xor_b64 s[44:45], exec, s[38:39]
	s_cbranch_execz .LBB0_303
	s_cmp_gt_u32 s66, 51
	s_cbranch_scc0 .LBB0_292
	v_cmp_lt_u32_e32 vcc, 53, v154
	s_mov_b64 s[28:29], 0
	s_and_saveexec_b64 s[38:39], vcc
	s_xor_b64 s[50:51], exec, s[38:39]
	s_cbranch_execz .LBB0_298
	s_mov_b64 s[38:39], -1
	s_mov_b64 s[34:35], 0
	s_cmp_gt_u32 s66, 55
	s_cbranch_scc0 .LBB0_295
	s_mov_b64 s[48:49], 0
	s_cmpk_gt_u32 s66, 0x67
	s_cbranch_scc0 .LBB0_284
	s_movk_i32 s38, 0x68
	v_cmp_eq_u32_e32 vcc, s38, v154
	s_mov_b64 s[38:39], 0
	s_and_b64 s[46:47], vcc, exec

; DI int tidx() { int t = threadIdx.x; asm volatile("" : "+v"(t)); return t; }
; DI void gemm_wide(const bf16_t* __restrict__ W, int ldw, const bf16_t* __restrict__ X, int ldx, int nkt,
;                   f32x16 (&acc)[4][2], bf16_t* lds) {
;   const int tid = tidx(), lane = tid & 63, wv = tid >> 6, wn = wv & 1, wm = wv >> 1;
;   const int lr = lane & 31, lh = lane >> 5;
;   const int lrow = tid >> 3, lkc = (tid & 7) * 8;
;   const bf16_t* wp = W + (size_t)lrow * ldw + lkc;
;   const bf16_t* xp = X + (size_t)lrow * ldx + lkc;
;   const size_t wst = (size_t)64 * ldw, xst = (size_t)64 * ldx;
;   u32x4 rw0, rw1, rw2, rw3, rx0, rx1, rx2, rx3;
;     ...
;   u32x4 sw0, sw1, sw2, sw3, sx0, sx1, sx2, sx3;
;     ...
;   __syncthreads();
;   GW_GLOAD(0)
;   GW_LSTORE(0)
;   GW_GLOAD(1)
;   GW_GLOAD_B(nkt > 2 ? 2 : nkt - 1)
;   __syncthreads();
; DI void phase_resid(const P& p, const bf16_t* W, const bf16_t* X, int K, bf16_t* sm, const Geo& ge, bool last) {
;     ...
;   while (tw.next(mt_, nt_)) {
;     f32x16 acc[4][2]; zero_acc8(acc);
;     const int ldk = K + 64;
;     gemm_wide(W + (size_t)nt_ * 256 * ldk, ldk, X + (size_t)mt_ * 256 * ldk, ldk, K / 64, acc, sm);
.LBB0_1104:
	s_cmp_gt_i32 s8, 63
	s_cselect_b64 s[0:1], -1, 0
	s_cmp_lt_i32 s8, 64
	s_mov_b64 s[4:5], -1
	s_mov_b32 s9, s54
	s_cbranch_scc0 .LBB0_1126
	s_ashr_i32 s9, s8, 3
	s_cmp_lt_i32 s9, 4
	s_cbranch_scc0 .LBB0_1125
	s_and_b32 s5, s8, 7
	s_or_b32 s4, s5, s55
	s_mul_i32 s26, s9, 0x88000
	s_mul_hi_i32 s25, s9, 0x88000
	s_add_u32 s26, s6, s26
	s_addc_u32 s27, s7, s25
	s_mul_i32 s25, s4, 0x88000
	s_add_u32 s28, s56, s25
	s_addc_u32 s29, s57, 0
	v_and_b32_e32 v128, 63, v195
	v_lshrrev_b32_e32 v129, 6, v195
	v_and_b32_e32 v130, 31, v128
	v_lshrrev_b32_e32 v131, 5, v128
	v_bfe_u32 v132, v130, 1, 3
	v_lshlrev_b32_e32 v133, 7, v130
	v_xor_b32_e32 v134, v131, v132
	v_lshl_add_u32 v135, v134, 4, v133
	v_and_b32_e32 v136, 1, v129
	v_lshlrev_b32_e32 v136, 14, v136
	v_lshrrev_b32_e32 v137, 1, v129
	v_lshlrev_b32_e32 v137, 13, v137
	v_add_u32_e32 v137, 0x10000, v137
	v_readfirstlane_b32 s98, v129
	v_add_u32_e32 v176, v136, v135
	v_xor_b32_e32 v177, 32, v176
	v_xor_b32_e32 v178, 64, v176
	v_xor_b32_e32 v179, 0x60, v176
	v_add_u32_e32 v180, v137, v135
	v_xor_b32_e32 v181, 32, v180
	v_xor_b32_e32 v182, 64, v180
	v_xor_b32_e32 v183, 0x60, v180
	s_lshl_b32 s98, s98, 12
	s_movk_i32 s100, 2176
	v_lshrrev_b32_e32 v138, 3, v128
	v_lshl_add_u32 v138, v129, 5, v138
	v_mul_lo_u32 v139, v138, s100
	v_and_b32_e32 v140, 7, v128
	v_lshrrev_b32_e32 v141, 4, v128
	v_xor_b32_e32 v142, v140, v141
	v_xor_b32_e32 v143, 4, v142
	v_lshl_add_u32 v184, v142, 4, v139
	v_lshl_add_u32 v185, v143, 4, v139
	v_add_u32_e32 v185, 0x4400, v185
	v_add_u32_e32 v186, 0x8800, v184
	v_add_u32_e32 v187, 0x8800, v185
	v_and_b32_e32 v140, 3, v129
	v_lshl_add_u32 v140, v140, 6, v128
	v_mul_lo_u32 v189, v140, s100
	s_cmp_lt_u32 s98, 0x4000
	s_cselect_b32 s100, s26, s28
	s_cselect_b32 s101, s27, s29
	s_add_u32 s100, s100, 0x100
	s_addc_u32 s101, s101, 0
	s_barrier
	s_mov_b32 m0, s98
	s_nop 0
	global_load_lds_dwordx4 v184, s[26:27]
	s_add_u32 m0, s98, 0x400
	s_nop 0
	global_load_lds_dwordx4 v185, s[26:27]
	s_add_u32 m0, s98, 0x800
	s_nop 0
	global_load_lds_dwordx4 v186, s[26:27]
	s_add_u32 m0, s98, 0xc00
	s_nop 0
	global_load_lds_dwordx4 v187, s[26:27]
	s_add_u32 s26, s26, 0x80
	s_addc_u32 s27, s27, 0
	s_add_u32 m0, s98, 0x10000
	s_nop 0
	global_load_lds_dwordx4 v184, s[28:29]
	s_add_u32 m0, s98, 0x10400
	s_nop 0
	global_load_lds_dwordx4 v185, s[28:29]
	s_add_u32 m0, s98, 0x10800
	s_nop 0
	global_load_lds_dwordx4 v186, s[28:29]
	s_add_u32 m0, s98, 0x10c00
	s_nop 0
	global_load_lds_dwordx4 v187, s[28:29]
	s_add_u32 s28, s28, 0x80
	s_addc_u32 s29, s29, 0
	s_add_u32 m0, s98, 0x8000
	s_nop 0
	global_load_lds_dwordx4 v184, s[26:27]
	s_add_u32 m0, s98, 0x8400
	s_nop 0
	global_load_lds_dwordx4 v185, s[26:27]
	s_add_u32 m0, s98, 0x8800
	s_nop 0
	global_load_lds_dwordx4 v186, s[26:27]
	s_add_u32 m0, s98, 0x8c00
	s_nop 0
	global_load_lds_dwordx4 v187, s[26:27]
	s_add_u32 s26, s26, 0x80
	s_addc_u32 s27, s27, 0
	v_mov_b64_e32 v[112:113], 0
	v_mov_b64_e32 v[114:115], 0
	v_mov_b64_e32 v[116:117], 0
	v_mov_b64_e32 v[118:119], 0
	v_mov_b64_e32 v[120:121], 0
	v_mov_b64_e32 v[122:123], 0
	v_mov_b64_e32 v[124:125], 0
	v_mov_b64_e32 v[126:127], 0
	v_mov_b64_e32 v[80:81], 0
	v_mov_b64_e32 v[82:83], 0
	v_mov_b64_e32 v[84:85], 0
	v_mov_b64_e32 v[86:87], 0
	v_mov_b64_e32 v[88:89], 0
	v_mov_b64_e32 v[90:91], 0
	v_mov_b64_e32 v[92:93], 0
	v_mov_b64_e32 v[94:95], 0
	v_mov_b64_e32 v[96:97], 0
	v_mov_b64_e32 v[98:99], 0
	v_mov_b64_e32 v[100:101], 0
	v_mov_b64_e32 v[102:103], 0
	v_mov_b64_e32 v[104:105], 0
	v_mov_b64_e32 v[106:107], 0
	v_mov_b64_e32 v[108:109], 0
	v_mov_b64_e32 v[110:111], 0
	v_mov_b64_e32 v[64:65], 0
	v_mov_b64_e32 v[66:67], 0
	v_mov_b64_e32 v[68:69], 0
	v_mov_b64_e32 v[70:71], 0
	v_mov_b64_e32 v[72:73], 0
	v_mov_b64_e32 v[74:75], 0
	v_mov_b64_e32 v[76:77], 0
	v_mov_b64_e32 v[78:79], 0
	v_mov_b64_e32 v[48:49], 0
	v_mov_b64_e32 v[50:51], 0
	v_mov_b64_e32 v[52:53], 0
	v_mov_b64_e32 v[54:55], 0
	v_mov_b64_e32 v[56:57], 0
	v_mov_b64_e32 v[58:59], 0
	v_mov_b64_e32 v[60:61], 0
	v_mov_b64_e32 v[62:63], 0
	v_mov_b64_e32 v[16:17], 0
	v_mov_b64_e32 v[18:19], 0
	v_mov_b64_e32 v[20:21], 0
	v_mov_b64_e32 v[22:23], 0
	v_mov_b64_e32 v[24:25], 0
	v_mov_b64_e32 v[26:27], 0
	v_mov_b64_e32 v[28:29], 0
	v_mov_b64_e32 v[30:31], 0
	v_mov_b64_e32 v[32:33], 0
	v_mov_b64_e32 v[34:35], 0
	v_mov_b64_e32 v[36:37], 0
	v_mov_b64_e32 v[38:39], 0
	v_mov_b64_e32 v[40:41], 0
	v_mov_b64_e32 v[42:43], 0
	v_mov_b64_e32 v[44:45], 0
	v_mov_b64_e32 v[46:47], 0
	v_mov_b64_e32 v[0:1], 0
	v_mov_b64_e32 v[2:3], 0
	v_mov_b64_e32 v[4:5], 0
	v_mov_b64_e32 v[6:7], 0
	v_mov_b64_e32 v[8:9], 0
	v_mov_b64_e32 v[10:11], 0
	v_mov_b64_e32 v[12:13], 0
	v_mov_b64_e32 v[14:15], 0
	s_waitcnt vmcnt(4)
	s_barrier
	ds_read_b128 v[144:147], v180 offset:0
	ds_read_b128 v[128:131], v176 offset:0
	ds_read_b128 v[148:151], v180 offset:4096
	ds_read_b128 v[132:135], v176 offset:4096
	ds_read_b128 v[136:139], v176 offset:8192
	ds_read_b128 v[140:143], v176 offset:12288
	s_movk_i32 s99, 7
; DI void gemm_wide(const bf16_t* __restrict__ W, int ldw, const bf16_t* __restrict__ X, int ldx, int nkt,
;                   f32x16 (&acc)[4][2], bf16_t* lds) {
;     ...
;   for (int kt = 0; kt < nkt; kt += 2) {
;     __builtin_amdgcn_sched_barrier(0);
;     GW_ST2(1, 0, rw0, rw1)                         GW_KS(kt, 0)
;     GW_ST2(1, 128 * LDT, rw2, rw3)                 GW_KS(kt, 1)
;     GW_ST2(1, WT_E, rx0, rx1)                      GW_KS(kt, 2)
;     GW_ST2(1, WT_E + 128 * LDT, rx2, rx3)          GW_KS(kt, 3)
;     __builtin_amdgcn_sched_barrier(0);
;     GW_GLOAD(kt + 3 < nkt ? kt + 3 : nkt - 1)
;     __syncthreads();
;     __builtin_amdgcn_sched_barrier(0);
;     GW_ST2(0, 0, sw0, sw1)                         GW_KS(kt + 1, 0)
;     GW_ST2(0, 128 * LDT, sw2, sw3)                 GW_KS(kt + 1, 1)
;     GW_ST2(0, WT_E, sx0, sx1)                      GW_KS(kt + 1, 2)
;     GW_ST2(0, WT_E + 128 * LDT, sx2, sx3)          GW_KS(kt + 1, 3)
;     __builtin_amdgcn_sched_barrier(0);
;     GW_GLOAD_B(kt + 4 < nkt ? kt + 4 : nkt - 1)
;     __syncthreads();
;   }
.Lgw_out_loop:
	s_waitcnt lgkmcnt(4)
	v_mfma_f32_32x32x16_bf16 v[112:127], v[128:131], v[144:147], v[112:127]
	s_add_u32 m0, s98, 0x18000
	ds_read_b128 v[168:171], v181 offset:0
	s_waitcnt lgkmcnt(4)
	v_mfma_f32_32x32x16_bf16 v[80:95], v[128:131], v[148:151], v[80:95]
	global_load_lds_dwordx4 v184, s[28:29]
	ds_read_b128 v[152:155], v177 offset:0
	s_waitcnt lgkmcnt(4)
	v_mfma_f32_32x32x16_bf16 v[96:111], v[132:135], v[144:147], v[96:111]
	s_add_u32 m0, s98, 0x18400
	ds_read_b128 v[172:175], v181 offset:4096
	v_mfma_f32_32x32x16_bf16 v[64:79], v[132:135], v[148:151], v[64:79]
	global_load_lds_dwordx4 v185, s[28:29]
	ds_read_b128 v[156:159], v177 offset:4096
	s_waitcnt lgkmcnt(5)
	v_mfma_f32_32x32x16_bf16 v[48:63], v[136:139], v[144:147], v[48:63]
	s_add_u32 m0, s98, 0x18800
	ds_read_b128 v[160:163], v177 offset:8192
	v_mfma_f32_32x32x16_bf16 v[16:31], v[136:139], v[148:151], v[16:31]
	global_load_lds_dwordx4 v186, s[28:29]
	ds_read_b128 v[164:167], v177 offset:12288
	s_waitcnt lgkmcnt(6)
	v_mfma_f32_32x32x16_bf16 v[32:47], v[140:143], v[144:147], v[32:47]
	s_add_u32 m0, s98, 0x18c00
	v_mfma_f32_32x32x16_bf16 v[0:15], v[140:143], v[148:151], v[0:15]
	global_load_lds_dwordx4 v187, s[28:29]
	s_add_u32 s28, s28, 0x80
	s_addc_u32 s29, s29, 0
	s_waitcnt lgkmcnt(4)
	v_mfma_f32_32x32x16_bf16 v[112:127], v[152:155], v[168:171], v[112:127]
	ds_read_b128 v[144:147], v182 offset:0
	s_waitcnt lgkmcnt(4)
	v_mfma_f32_32x32x16_bf16 v[80:95], v[152:155], v[172:175], v[80:95]
	ds_read_b128 v[128:131], v178 offset:0
	s_waitcnt lgkmcnt(4)
	v_mfma_f32_32x32x16_bf16 v[96:111], v[156:159], v[168:171], v[96:111]
	ds_read_b128 v[148:151], v182 offset:4096
	v_mfma_f32_32x32x16_bf16 v[64:79], v[156:159], v[172:175], v[64:79]
	ds_read_b128 v[132:135], v178 offset:4096
	s_waitcnt lgkmcnt(5)
	v_mfma_f32_32x32x16_bf16 v[48:63], v[160:163], v[168:171], v[48:63]
	ds_read_b128 v[136:139], v178 offset:8192
	v_mfma_f32_32x32x16_bf16 v[16:31], v[160:163], v[172:175], v[16:31]
	ds_read_b128 v[140:143], v178 offset:12288
	s_waitcnt lgkmcnt(6)
	v_mfma_f32_32x32x16_bf16 v[32:47], v[164:167], v[168:171], v[32:47]
	v_mfma_f32_32x32x16_bf16 v[0:15], v[164:167], v[172:175], v[0:15]
	s_waitcnt lgkmcnt(4)
	v_mfma_f32_32x32x16_bf16 v[112:127], v[128:131], v[144:147], v[112:127]
	ds_read_b128 v[168:171], v183 offset:0
	ds_read_b128 v[152:155], v179 offset:0
	s_waitcnt lgkmcnt(5)
	v_mfma_f32_32x32x16_bf16 v[80:95], v[128:131], v[148:151], v[80:95]
	ds_read_b128 v[172:175], v183 offset:4096
	ds_read_b128 v[156:159], v179 offset:4096
	s_waitcnt lgkmcnt(6)
	v_mfma_f32_32x32x16_bf16 v[96:111], v[132:135], v[144:147], v[96:111]
	ds_read_b128 v[160:163], v179 offset:8192
	ds_read_b128 v[164:167], v179 offset:12288
	v_mfma_f32_32x32x16_bf16 v[64:79], v[132:135], v[148:151], v[64:79]
	s_waitcnt lgkmcnt(7)
	v_mfma_f32_32x32x16_bf16 v[48:63], v[136:139], v[144:147], v[48:63]
	v_mfma_f32_32x32x16_bf16 v[16:31], v[136:139], v[148:151], v[16:31]
	s_waitcnt lgkmcnt(6)
	v_mfma_f32_32x32x16_bf16 v[32:47], v[140:143], v[144:147], v[32:47]
	v_mfma_f32_32x32x16_bf16 v[0:15], v[140:143], v[148:151], v[0:15]
	s_waitcnt vmcnt(0) lgkmcnt(0)
	s_barrier
	v_mfma_f32_32x32x16_bf16 v[112:127], v[152:155], v[168:171], v[112:127]
	s_mov_b32 m0, s98
	ds_read_b128 v[144:147], v180 offset:32768
	v_mfma_f32_32x32x16_bf16 v[80:95], v[152:155], v[172:175], v[80:95]
	ds_read_b128 v[128:131], v176 offset:32768
	global_load_lds_dwordx4 v184, s[26:27]
	v_mfma_f32_32x32x16_bf16 v[96:111], v[156:159], v[168:171], v[96:111]
	s_add_u32 m0, s98, 0x400
	ds_read_b128 v[148:151], v180 offset:36864
	v_mfma_f32_32x32x16_bf16 v[64:79], v[156:159], v[172:175], v[64:79]
	ds_read_b128 v[132:135], v176 offset:36864
	global_load_lds_dwordx4 v185, s[26:27]
	v_mfma_f32_32x32x16_bf16 v[48:63], v[160:163], v[168:171], v[48:63]
	s_add_u32 m0, s98, 0x800
	ds_read_b128 v[136:139], v176 offset:40960
	v_mfma_f32_32x32x16_bf16 v[16:31], v[160:163], v[172:175], v[16:31]
	ds_read_b128 v[140:143], v176 offset:45056
	global_load_lds_dwordx4 v186, s[26:27]
	v_mfma_f32_32x32x16_bf16 v[32:47], v[164:167], v[168:171], v[32:47]
	s_add_u32 m0, s98, 0xc00
	v_mfma_f32_32x32x16_bf16 v[0:15], v[164:167], v[172:175], v[0:15]
	global_load_lds_dwordx4 v187, s[26:27]
	s_add_u32 s26, s26, 0x80
	s_addc_u32 s27, s27, 0
	s_waitcnt lgkmcnt(4)
	v_mfma_f32_32x32x16_bf16 v[112:127], v[128:131], v[144:147], v[112:127]
	s_add_u32 m0, s98, 0x10000
	ds_read_b128 v[168:171], v181 offset:32768
	s_waitcnt lgkmcnt(4)
	v_mfma_f32_32x32x16_bf16 v[80:95], v[128:131], v[148:151], v[80:95]
	global_load_lds_dwordx4 v184, s[28:29]
	ds_read_b128 v[152:155], v177 offset:32768
	s_waitcnt lgkmcnt(4)
	v_mfma_f32_32x32x16_bf16 v[96:111], v[132:135], v[144:147], v[96:111]
	s_add_u32 m0, s98, 0x10400
	ds_read_b128 v[172:175], v181 offset:36864
	v_mfma_f32_32x32x16_bf16 v[64:79], v[132:135], v[148:151], v[64:79]
	global_load_lds_dwordx4 v185, s[28:29]
	ds_read_b128 v[156:159], v177 offset:36864
	s_waitcnt lgkmcnt(5)
	v_mfma_f32_32x32x16_bf16 v[48:63], v[136:139], v[144:147], v[48:63]
	s_add_u32 m0, s98, 0x10800
	ds_read_b128 v[160:163], v177 offset:40960
	v_mfma_f32_32x32x16_bf16 v[16:31], v[136:139], v[148:151], v[16:31]
	global_load_lds_dwordx4 v186, s[28:29]
	ds_read_b128 v[164:167], v177 offset:45056
	s_waitcnt lgkmcnt(6)
	v_mfma_f32_32x32x16_bf16 v[32:47], v[140:143], v[144:147], v[32:47]
	s_add_u32 m0, s98, 0x10c00
	v_mfma_f32_32x32x16_bf16 v[0:15], v[140:143], v[148:151], v[0:15]
	global_load_lds_dwordx4 v187, s[28:29]
	s_add_u32 s28, s28, 0x80
	s_addc_u32 s29, s29, 0
	s_waitcnt lgkmcnt(4)
	v_mfma_f32_32x32x16_bf16 v[112:127], v[152:155], v[168:171], v[112:127]
	ds_read_b128 v[144:147], v182 offset:32768
	s_waitcnt lgkmcnt(4)
; DI void gemm_wide(const bf16_t* __restrict__ W, int ldw, const bf16_t* __restrict__ X, int ldx, int nkt,
;                   f32x16 (&acc)[4][2], bf16_t* lds) {
;     ...
;   for (int kt = 0; kt < nkt; kt += 2) {
;     __builtin_amdgcn_sched_barrier(0);
;     GW_ST2(1, 0, rw0, rw1)                         GW_KS(kt, 0)
;     GW_ST2(1, 128 * LDT, rw2, rw3)                 GW_KS(kt, 1)
;     GW_ST2(1, WT_E, rx0, rx1)                      GW_KS(kt, 2)
;     GW_ST2(1, WT_E + 128 * LDT, rx2, rx3)          GW_KS(kt, 3)
;     __builtin_amdgcn_sched_barrier(0);
;     GW_GLOAD(kt + 3 < nkt ? kt + 3 : nkt - 1)
;     __syncthreads();
;     __builtin_amdgcn_sched_barrier(0);
;     GW_ST2(0, 0, sw0, sw1)                         GW_KS(kt + 1, 0)
;     GW_ST2(0, 128 * LDT, sw2, sw3)                 GW_KS(kt + 1, 1)
;     GW_ST2(0, WT_E, sx0, sx1)                      GW_KS(kt + 1, 2)
;     GW_ST2(0, WT_E + 128 * LDT, sx2, sx3)          GW_KS(kt + 1, 3)
;     __builtin_amdgcn_sched_barrier(0);
;     GW_GLOAD_B(kt + 4 < nkt ? kt + 4 : nkt - 1)
;     __syncthreads();
;   }
	v_mfma_f32_32x32x16_bf16 v[80:95], v[152:155], v[172:175], v[80:95]
	ds_read_b128 v[128:131], v178 offset:32768
	s_waitcnt lgkmcnt(4)
	v_mfma_f32_32x32x16_bf16 v[96:111], v[156:159], v[168:171], v[96:111]
	ds_read_b128 v[148:151], v182 offset:36864
	v_mfma_f32_32x32x16_bf16 v[64:79], v[156:159], v[172:175], v[64:79]
	ds_read_b128 v[132:135], v178 offset:36864
	s_waitcnt lgkmcnt(5)
	v_mfma_f32_32x32x16_bf16 v[48:63], v[160:163], v[168:171], v[48:63]
	ds_read_b128 v[136:139], v178 offset:40960
	v_mfma_f32_32x32x16_bf16 v[16:31], v[160:163], v[172:175], v[16:31]
	ds_read_b128 v[140:143], v178 offset:45056
	s_waitcnt lgkmcnt(6)
	v_mfma_f32_32x32x16_bf16 v[32:47], v[164:167], v[168:171], v[32:47]
	v_mfma_f32_32x32x16_bf16 v[0:15], v[164:167], v[172:175], v[0:15]
	s_waitcnt lgkmcnt(4)
	v_mfma_f32_32x32x16_bf16 v[112:127], v[128:131], v[144:147], v[112:127]
	ds_read_b128 v[168:171], v183 offset:32768
	ds_read_b128 v[152:155], v179 offset:32768
	s_waitcnt lgkmcnt(5)
	v_mfma_f32_32x32x16_bf16 v[80:95], v[128:131], v[148:151], v[80:95]
	ds_read_b128 v[172:175], v183 offset:36864
	ds_read_b128 v[156:159], v179 offset:36864
	s_waitcnt lgkmcnt(6)
	v_mfma_f32_32x32x16_bf16 v[96:111], v[132:135], v[144:147], v[96:111]
	ds_read_b128 v[160:163], v179 offset:40960
	ds_read_b128 v[164:167], v179 offset:45056
	v_mfma_f32_32x32x16_bf16 v[64:79], v[132:135], v[148:151], v[64:79]
	s_waitcnt lgkmcnt(7)
	v_mfma_f32_32x32x16_bf16 v[48:63], v[136:139], v[144:147], v[48:63]
	v_mfma_f32_32x32x16_bf16 v[16:31], v[136:139], v[148:151], v[16:31]
	s_waitcnt lgkmcnt(6)
	v_mfma_f32_32x32x16_bf16 v[32:47], v[140:143], v[144:147], v[32:47]
	v_mfma_f32_32x32x16_bf16 v[0:15], v[140:143], v[148:151], v[0:15]
	s_waitcnt vmcnt(0) lgkmcnt(0)
	s_barrier
	v_mfma_f32_32x32x16_bf16 v[112:127], v[152:155], v[168:171], v[112:127]
	s_add_u32 m0, s98, 0x8000
	ds_read_b128 v[144:147], v180 offset:0
	v_mfma_f32_32x32x16_bf16 v[80:95], v[152:155], v[172:175], v[80:95]
	ds_read_b128 v[128:131], v176 offset:0
	global_load_lds_dwordx4 v184, s[26:27]
	v_mfma_f32_32x32x16_bf16 v[96:111], v[156:159], v[168:171], v[96:111]
	s_add_u32 m0, s98, 0x8400
	ds_read_b128 v[148:151], v180 offset:4096
	v_mfma_f32_32x32x16_bf16 v[64:79], v[156:159], v[172:175], v[64:79]
	ds_read_b128 v[132:135], v176 offset:4096
	global_load_lds_dwordx4 v185, s[26:27]
	v_mfma_f32_32x32x16_bf16 v[48:63], v[160:163], v[168:171], v[48:63]
	s_add_u32 m0, s98, 0x8800
	ds_read_b128 v[136:139], v176 offset:8192
	v_mfma_f32_32x32x16_bf16 v[16:31], v[160:163], v[172:175], v[16:31]
	ds_read_b128 v[140:143], v176 offset:12288
	global_load_lds_dwordx4 v186, s[26:27]
	v_mfma_f32_32x32x16_bf16 v[32:47], v[164:167], v[168:171], v[32:47]
	s_add_u32 m0, s98, 0x8c00
	v_mfma_f32_32x32x16_bf16 v[0:15], v[164:167], v[172:175], v[0:15]
	global_load_lds_dwordx4 v187, s[26:27]
	s_add_u32 s26, s26, 0x80
	s_addc_u32 s27, s27, 0
	s_sub_u32 s99, s99, 1
	s_cmp_lg_u32 s99, 0
	s_cbranch_scc1 .Lgw_out_loop
	s_waitcnt lgkmcnt(4)
	v_mfma_f32_32x32x16_bf16 v[112:127], v[128:131], v[144:147], v[112:127]
	s_add_u32 m0, s98, 0x18000
	ds_read_b128 v[168:171], v181 offset:0
	s_waitcnt lgkmcnt(4)
	v_mfma_f32_32x32x16_bf16 v[80:95], v[128:131], v[148:151], v[80:95]
	global_load_lds_dwordx4 v184, s[28:29]
	ds_read_b128 v[152:155], v177 offset:0
	s_waitcnt lgkmcnt(4)
	v_mfma_f32_32x32x16_bf16 v[96:111], v[132:135], v[144:147], v[96:111]
	s_add_u32 m0, s98, 0x18400
	ds_read_b128 v[172:175], v181 offset:4096
	v_mfma_f32_32x32x16_bf16 v[64:79], v[132:135], v[148:151], v[64:79]
	global_load_lds_dwordx4 v185, s[28:29]
	ds_read_b128 v[156:159], v177 offset:4096
	s_waitcnt lgkmcnt(5)
	v_mfma_f32_32x32x16_bf16 v[48:63], v[136:139], v[144:147], v[48:63]
	s_add_u32 m0, s98, 0x18800
	ds_read_b128 v[160:163], v177 offset:8192
	v_mfma_f32_32x32x16_bf16 v[16:31], v[136:139], v[148:151], v[16:31]
	global_load_lds_dwordx4 v186, s[28:29]
	ds_read_b128 v[164:167], v177 offset:12288
	s_waitcnt lgkmcnt(6)
	v_mfma_f32_32x32x16_bf16 v[32:47], v[140:143], v[144:147], v[32:47]
	s_add_u32 m0, s98, 0x18c00
	v_mfma_f32_32x32x16_bf16 v[0:15], v[140:143], v[148:151], v[0:15]
	global_load_lds_dwordx4 v187, s[28:29]
	s_add_u32 s28, s28, 0x80
	s_addc_u32 s29, s29, 0
	s_waitcnt lgkmcnt(4)
	v_mfma_f32_32x32x16_bf16 v[112:127], v[152:155], v[168:171], v[112:127]
	ds_read_b128 v[144:147], v182 offset:0
	s_waitcnt lgkmcnt(4)
	v_mfma_f32_32x32x16_bf16 v[80:95], v[152:155], v[172:175], v[80:95]
	ds_read_b128 v[128:131], v178 offset:0
	s_waitcnt lgkmcnt(4)
	v_mfma_f32_32x32x16_bf16 v[96:111], v[156:159], v[168:171], v[96:111]
	ds_read_b128 v[148:151], v182 offset:4096
	v_mfma_f32_32x32x16_bf16 v[64:79], v[156:159], v[172:175], v[64:79]
	ds_read_b128 v[132:135], v178 offset:4096
	s_waitcnt lgkmcnt(5)
	v_mfma_f32_32x32x16_bf16 v[48:63], v[160:163], v[168:171], v[48:63]
	ds_read_b128 v[136:139], v178 offset:8192
	v_mfma_f32_32x32x16_bf16 v[16:31], v[160:163], v[172:175], v[16:31]
	ds_read_b128 v[140:143], v178 offset:12288
	s_waitcnt lgkmcnt(6)
	v_mfma_f32_32x32x16_bf16 v[32:47], v[164:167], v[168:171], v[32:47]
	v_mfma_f32_32x32x16_bf16 v[0:15], v[164:167], v[172:175], v[0:15]
	s_waitcnt lgkmcnt(4)
	v_mfma_f32_32x32x16_bf16 v[112:127], v[128:131], v[144:147], v[112:127]
	ds_read_b128 v[168:171], v183 offset:0
	ds_read_b128 v[152:155], v179 offset:0
	s_waitcnt lgkmcnt(5)
	v_mfma_f32_32x32x16_bf16 v[80:95], v[128:131], v[148:151], v[80:95]
	ds_read_b128 v[172:175], v183 offset:4096
	ds_read_b128 v[156:159], v179 offset:4096
	s_waitcnt lgkmcnt(6)
	v_mfma_f32_32x32x16_bf16 v[96:111], v[132:135], v[144:147], v[96:111]
	ds_read_b128 v[160:163], v179 offset:8192
	ds_read_b128 v[164:167], v179 offset:12288
	v_mfma_f32_32x32x16_bf16 v[64:79], v[132:135], v[148:151], v[64:79]
	s_waitcnt lgkmcnt(7)
	v_mfma_f32_32x32x16_bf16 v[48:63], v[136:139], v[144:147], v[48:63]
	v_mfma_f32_32x32x16_bf16 v[16:31], v[136:139], v[148:151], v[16:31]
	s_waitcnt lgkmcnt(6)
	v_mfma_f32_32x32x16_bf16 v[32:47], v[140:143], v[144:147], v[32:47]
	v_mfma_f32_32x32x16_bf16 v[0:15], v[140:143], v[148:151], v[0:15]
	s_waitcnt vmcnt(0) lgkmcnt(0)
	s_barrier
; DI void gemm_wide(const bf16_t* __restrict__ W, int ldw, const bf16_t* __restrict__ X, int ldx, int nkt,
;                   f32x16 (&acc)[4][2], bf16_t* lds) {
;     ...
;   for (int kt = 0; kt < nkt; kt += 2) {
;     __builtin_amdgcn_sched_barrier(0);
;     GW_ST2(1, 0, rw0, rw1)                         GW_KS(kt, 0)
;     GW_ST2(1, 128 * LDT, rw2, rw3)                 GW_KS(kt, 1)
;     GW_ST2(1, WT_E, rx0, rx1)                      GW_KS(kt, 2)
;     GW_ST2(1, WT_E + 128 * LDT, rx2, rx3)          GW_KS(kt, 3)
;     __builtin_amdgcn_sched_barrier(0);
;     GW_GLOAD(kt + 3 < nkt ? kt + 3 : nkt - 1)
;     __syncthreads();
;     __builtin_amdgcn_sched_barrier(0);
;     GW_ST2(0, 0, sw0, sw1)                         GW_KS(kt + 1, 0)
;     GW_ST2(0, 128 * LDT, sw2, sw3)                 GW_KS(kt + 1, 1)
;     GW_ST2(0, WT_E, sx0, sx1)                      GW_KS(kt + 1, 2)
;     GW_ST2(0, WT_E + 128 * LDT, sx2, sx3)          GW_KS(kt + 1, 3)
;     __builtin_amdgcn_sched_barrier(0);
;     GW_GLOAD_B(kt + 4 < nkt ? kt + 4 : nkt - 1)
;     __syncthreads();
;   }
; DI void phase_resid(const P& p, const bf16_t* W, const bf16_t* X, int K, bf16_t* sm, const Geo& ge, bool last) {
;     ...
;     float* stg = (float*)sm + wv * (64 * 68);
;     const int m0w = mt_ * 256 + wm * 64, n0w = nt_ * 256 + wn * 128;
; #pragma unroll
;     for (int cp = 0; cp < 2; ++cp) {
; #pragma unroll 4
;       for (int it = 0; it < 8; ++it) {
;         const int row = it * 8 + (lane >> 3), c8 = (lane & 7) * 8;
;         const u32x4 raw = *(const u32x4*)(xb + (size_t)(m0w + row) * LDK1 + n0w + cp * 64 + c8);
	v_mfma_f32_32x32x16_bf16 v[112:127], v[152:155], v[168:171], v[112:127]
	ds_read_b128 v[144:147], v180 offset:32768
	v_mfma_f32_32x32x16_bf16 v[80:95], v[152:155], v[172:175], v[80:95]
	ds_read_b128 v[128:131], v176 offset:32768
	v_mfma_f32_32x32x16_bf16 v[96:111], v[156:159], v[168:171], v[96:111]
	ds_read_b128 v[148:151], v180 offset:36864
	v_mfma_f32_32x32x16_bf16 v[64:79], v[156:159], v[172:175], v[64:79]
	ds_read_b128 v[132:135], v176 offset:36864
	v_mfma_f32_32x32x16_bf16 v[48:63], v[160:163], v[168:171], v[48:63]
	ds_read_b128 v[136:139], v176 offset:40960
	v_mfma_f32_32x32x16_bf16 v[16:31], v[160:163], v[172:175], v[16:31]
	ds_read_b128 v[140:143], v176 offset:45056
	v_mfma_f32_32x32x16_bf16 v[32:47], v[164:167], v[168:171], v[32:47]
	v_mfma_f32_32x32x16_bf16 v[0:15], v[164:167], v[172:175], v[0:15]
	s_waitcnt lgkmcnt(4)
	v_mfma_f32_32x32x16_bf16 v[112:127], v[128:131], v[144:147], v[112:127]
	ds_read_b128 v[168:171], v181 offset:32768
	s_waitcnt lgkmcnt(4)
	v_mfma_f32_32x32x16_bf16 v[80:95], v[128:131], v[148:151], v[80:95]
	ds_read_b128 v[152:155], v177 offset:32768
	s_waitcnt lgkmcnt(4)
	v_mfma_f32_32x32x16_bf16 v[96:111], v[132:135], v[144:147], v[96:111]
	ds_read_b128 v[172:175], v181 offset:36864
	v_mfma_f32_32x32x16_bf16 v[64:79], v[132:135], v[148:151], v[64:79]
	ds_read_b128 v[156:159], v177 offset:36864
	s_waitcnt lgkmcnt(5)
	v_mfma_f32_32x32x16_bf16 v[48:63], v[136:139], v[144:147], v[48:63]
	ds_read_b128 v[160:163], v177 offset:40960
	v_mfma_f32_32x32x16_bf16 v[16:31], v[136:139], v[148:151], v[16:31]
	ds_read_b128 v[164:167], v177 offset:45056
	s_waitcnt lgkmcnt(6)
	v_mfma_f32_32x32x16_bf16 v[32:47], v[140:143], v[144:147], v[32:47]
	v_mfma_f32_32x32x16_bf16 v[0:15], v[140:143], v[148:151], v[0:15]
	s_waitcnt lgkmcnt(4)
	v_mfma_f32_32x32x16_bf16 v[112:127], v[152:155], v[168:171], v[112:127]
	ds_read_b128 v[144:147], v182 offset:32768
	s_waitcnt lgkmcnt(4)
	v_mfma_f32_32x32x16_bf16 v[80:95], v[152:155], v[172:175], v[80:95]
	ds_read_b128 v[128:131], v178 offset:32768
	s_waitcnt lgkmcnt(4)
	v_mfma_f32_32x32x16_bf16 v[96:111], v[156:159], v[168:171], v[96:111]
	ds_read_b128 v[148:151], v182 offset:36864
	v_mfma_f32_32x32x16_bf16 v[64:79], v[156:159], v[172:175], v[64:79]
	ds_read_b128 v[132:135], v178 offset:36864
	s_waitcnt lgkmcnt(5)
	v_mfma_f32_32x32x16_bf16 v[48:63], v[160:163], v[168:171], v[48:63]
	ds_read_b128 v[136:139], v178 offset:40960
	v_mfma_f32_32x32x16_bf16 v[16:31], v[160:163], v[172:175], v[16:31]
	ds_read_b128 v[140:143], v178 offset:45056
	s_waitcnt lgkmcnt(6)
	v_mfma_f32_32x32x16_bf16 v[32:47], v[164:167], v[168:171], v[32:47]
	v_mfma_f32_32x32x16_bf16 v[0:15], v[164:167], v[172:175], v[0:15]
	s_waitcnt lgkmcnt(4)
	v_mfma_f32_32x32x16_bf16 v[112:127], v[128:131], v[144:147], v[112:127]
	ds_read_b128 v[168:171], v183 offset:32768
	ds_read_b128 v[152:155], v179 offset:32768
	s_waitcnt lgkmcnt(5)
	v_mfma_f32_32x32x16_bf16 v[80:95], v[128:131], v[148:151], v[80:95]
	ds_read_b128 v[172:175], v183 offset:36864
	ds_read_b128 v[156:159], v179 offset:36864
	s_waitcnt lgkmcnt(6)
	v_mfma_f32_32x32x16_bf16 v[96:111], v[132:135], v[144:147], v[96:111]
	ds_read_b128 v[160:163], v179 offset:40960
	ds_read_b128 v[164:167], v179 offset:45056
	v_mfma_f32_32x32x16_bf16 v[64:79], v[132:135], v[148:151], v[64:79]
	s_waitcnt lgkmcnt(7)
	v_mfma_f32_32x32x16_bf16 v[48:63], v[136:139], v[144:147], v[48:63]
	v_mfma_f32_32x32x16_bf16 v[16:31], v[136:139], v[148:151], v[16:31]
	s_waitcnt lgkmcnt(6)
	v_mfma_f32_32x32x16_bf16 v[32:47], v[140:143], v[144:147], v[32:47]
	v_mfma_f32_32x32x16_bf16 v[0:15], v[140:143], v[148:151], v[0:15]
	s_waitcnt vmcnt(0) lgkmcnt(0)
	s_barrier
	v_mfma_f32_32x32x16_bf16 v[112:127], v[152:155], v[168:171], v[112:127]
	v_mfma_f32_32x32x16_bf16 v[80:95], v[152:155], v[172:175], v[80:95]
	v_mfma_f32_32x32x16_bf16 v[96:111], v[156:159], v[168:171], v[96:111]
	v_mfma_f32_32x32x16_bf16 v[64:79], v[156:159], v[172:175], v[64:79]
	v_mfma_f32_32x32x16_bf16 v[48:63], v[160:163], v[168:171], v[48:63]
	v_mfma_f32_32x32x16_bf16 v[16:31], v[160:163], v[172:175], v[16:31]
	v_mfma_f32_32x32x16_bf16 v[32:47], v[164:167], v[168:171], v[32:47]
	v_mfma_f32_32x32x16_bf16 v[0:15], v[164:167], v[172:175], v[0:15]
	s_nop 15
	s_waitcnt vmcnt(1)
	v_lshl_or_b32 v134, s9, 8, v235
	v_ashrrev_i32_e32 v135, 31, v134
	s_lshl_b32 s25, s5, 8
	v_lshl_add_u64 v[130:131], v[134:135], 1, v[196:197]
	v_add_u32_e32 v137, s25, v238
	s_mov_b32 s5, 0
	v_mov_b32_e32 v128, v237

; DI int tidx() { int t = threadIdx.x; asm volatile("" : "+v"(t)); return t; }
; DI void gemm_wide(const bf16_t* __restrict__ W, int ldw, const bf16_t* __restrict__ X, int ldx, int nkt,
;                   f32x16 (&acc)[4][2], bf16_t* lds) {
;   const int tid = tidx(), lane = tid & 63, wv = tid >> 6, wn = wv & 1, wm = wv >> 1;
;   const int lr = lane & 31, lh = lane >> 5;
;   const int lrow = tid >> 3, lkc = (tid & 7) * 8;
;   const bf16_t* wp = W + (size_t)lrow * ldw + lkc;
;   const bf16_t* xp = X + (size_t)lrow * ldx + lkc;
;   const size_t wst = (size_t)64 * ldw, xst = (size_t)64 * ldx;
;   u32x4 rw0, rw1, rw2, rw3, rx0, rx1, rx2, rx3;
;     ...
;   u32x4 sw0, sw1, sw2, sw3, sx0, sx1, sx2, sx3;
;     ...
;   __syncthreads();
;   GW_GLOAD(0)
;   GW_LSTORE(0)
;   GW_GLOAD(1)
;   GW_GLOAD_B(nkt > 2 ? 2 : nkt - 1)
;   __syncthreads();
; DI void phase_up(const P& p, int layer, bf16_t* sm, const Geo& ge) {
;     ...
;   while (tw.next(mt_, nt_)) {
;     if (mt_ != mt_have) {
;       rs0 = row_rstd(part, mt_ * 256 + wm * 64 + lr);
;       rs1 = row_rstd(part, mt_ * 256 + wm * 64 + 32 + lr);
;       mt_have = mt_;
;     }
;     f32x16 acc[4][2]; zero_acc8(acc);
;     gemm_wide(W + (size_t)nt_ * 256 * LDK1, LDK1, X + (size_t)mt_ * 256 * LDK1, LDK1, 16, acc, sm);
.LBB0_1145:
	s_lshl_b32 s0, s4, 3
	s_ashr_i32 s1, s5, 3
	s_add_i32 s0, s1, s0
	s_mul_i32 s8, s0, 0x88000
	s_mul_hi_i32 s1, s0, 0x88000
	s_add_u32 s8, s2, s8
	s_addc_u32 s9, s3, s1
	s_mul_i32 s1, s6, 0x88000
	s_add_u32 s26, s14, s1
	s_addc_u32 s27, s15, 0
	v_and_b32_e32 v128, 63, v195
	v_lshrrev_b32_e32 v129, 6, v195
	v_and_b32_e32 v130, 31, v128
	v_lshrrev_b32_e32 v131, 5, v128
	v_bfe_u32 v132, v130, 1, 3
	v_lshlrev_b32_e32 v133, 7, v130
	v_xor_b32_e32 v134, v131, v132
	v_lshl_add_u32 v135, v134, 4, v133
	v_and_b32_e32 v136, 1, v129
	v_lshlrev_b32_e32 v136, 14, v136
	v_lshrrev_b32_e32 v137, 1, v129
	v_lshlrev_b32_e32 v137, 13, v137
	v_add_u32_e32 v137, 0x10000, v137
	v_readfirstlane_b32 s98, v129
	v_add_u32_e32 v176, v136, v135
	v_xor_b32_e32 v177, 32, v176
	v_xor_b32_e32 v178, 64, v176
	v_xor_b32_e32 v179, 0x60, v176
	v_add_u32_e32 v180, v137, v135
	v_xor_b32_e32 v181, 32, v180
	v_xor_b32_e32 v182, 64, v180
	v_xor_b32_e32 v183, 0x60, v180
	s_lshl_b32 s98, s98, 12
	s_movk_i32 s100, 2176
	v_lshrrev_b32_e32 v138, 3, v128
	v_lshl_add_u32 v138, v129, 5, v138
	v_mul_lo_u32 v139, v138, s100
	v_and_b32_e32 v140, 7, v128
	v_lshrrev_b32_e32 v141, 4, v128
	v_xor_b32_e32 v142, v140, v141
	v_xor_b32_e32 v143, 4, v142
	v_lshl_add_u32 v184, v142, 4, v139
	v_lshl_add_u32 v185, v143, 4, v139
	v_add_u32_e32 v185, 0x4400, v185
	v_add_u32_e32 v186, 0x8800, v184
	v_add_u32_e32 v187, 0x8800, v185
	v_and_b32_e32 v140, 3, v129
	v_lshl_add_u32 v140, v140, 6, v128
	v_mul_lo_u32 v189, v140, s100
	s_cmp_lt_u32 s98, 0x4000
	s_cselect_b32 s100, s8, s26
	s_cselect_b32 s101, s9, s27
	s_add_u32 s100, s100, 0x100
	s_addc_u32 s101, s101, 0
	s_barrier
	s_mov_b32 m0, s98
	s_nop 0
	global_load_lds_dwordx4 v184, s[8:9]
	s_add_u32 m0, s98, 0x400
	s_nop 0
	global_load_lds_dwordx4 v185, s[8:9]
	s_add_u32 m0, s98, 0x800
	s_nop 0
	global_load_lds_dwordx4 v186, s[8:9]
	s_add_u32 m0, s98, 0xc00
	s_nop 0
	global_load_lds_dwordx4 v187, s[8:9]
	s_add_u32 s8, s8, 0x80
	s_addc_u32 s9, s9, 0
	s_add_u32 m0, s98, 0x10000
	s_nop 0
	global_load_lds_dwordx4 v184, s[26:27]
	s_add_u32 m0, s98, 0x10400
	s_nop 0
	global_load_lds_dwordx4 v185, s[26:27]
	s_add_u32 m0, s98, 0x10800
	s_nop 0
	global_load_lds_dwordx4 v186, s[26:27]
	s_add_u32 m0, s98, 0x10c00
	s_nop 0
	global_load_lds_dwordx4 v187, s[26:27]
	s_add_u32 s26, s26, 0x80
	s_addc_u32 s27, s27, 0
	s_add_u32 m0, s98, 0x8000
	s_nop 0
	global_load_lds_dwordx4 v184, s[8:9]
	s_add_u32 m0, s98, 0x8400
	s_nop 0
	global_load_lds_dwordx4 v185, s[8:9]
	s_add_u32 m0, s98, 0x8800
	s_nop 0
	global_load_lds_dwordx4 v186, s[8:9]
	s_add_u32 m0, s98, 0x8c00
	s_nop 0
	global_load_lds_dwordx4 v187, s[8:9]
	s_add_u32 s8, s8, 0x80
	s_addc_u32 s9, s9, 0
	v_mov_b64_e32 v[112:113], 0
	v_mov_b64_e32 v[114:115], 0
	v_mov_b64_e32 v[116:117], 0
	v_mov_b64_e32 v[118:119], 0
	v_mov_b64_e32 v[120:121], 0
	v_mov_b64_e32 v[122:123], 0
	v_mov_b64_e32 v[124:125], 0
	v_mov_b64_e32 v[126:127], 0
	v_mov_b64_e32 v[64:65], 0
	v_mov_b64_e32 v[66:67], 0
	v_mov_b64_e32 v[68:69], 0
	v_mov_b64_e32 v[70:71], 0
	v_mov_b64_e32 v[72:73], 0
	v_mov_b64_e32 v[74:75], 0
	v_mov_b64_e32 v[76:77], 0
	v_mov_b64_e32 v[78:79], 0
	v_mov_b64_e32 v[96:97], 0
	v_mov_b64_e32 v[98:99], 0
	v_mov_b64_e32 v[100:101], 0
	v_mov_b64_e32 v[102:103], 0
	v_mov_b64_e32 v[104:105], 0
	v_mov_b64_e32 v[106:107], 0
	v_mov_b64_e32 v[108:109], 0
	v_mov_b64_e32 v[110:111], 0
	v_mov_b64_e32 v[32:33], 0
	v_mov_b64_e32 v[34:35], 0
	v_mov_b64_e32 v[36:37], 0
	v_mov_b64_e32 v[38:39], 0
	v_mov_b64_e32 v[40:41], 0
	v_mov_b64_e32 v[42:43], 0
	v_mov_b64_e32 v[44:45], 0
	v_mov_b64_e32 v[46:47], 0
	v_mov_b64_e32 v[80:81], 0
	v_mov_b64_e32 v[82:83], 0
	v_mov_b64_e32 v[84:85], 0
	v_mov_b64_e32 v[86:87], 0
	v_mov_b64_e32 v[88:89], 0
	v_mov_b64_e32 v[90:91], 0
	v_mov_b64_e32 v[92:93], 0
	v_mov_b64_e32 v[94:95], 0
	v_mov_b64_e32 v[16:17], 0
	v_mov_b64_e32 v[18:19], 0
	v_mov_b64_e32 v[20:21], 0
	v_mov_b64_e32 v[22:23], 0
	v_mov_b64_e32 v[24:25], 0
	v_mov_b64_e32 v[26:27], 0
	v_mov_b64_e32 v[28:29], 0
	v_mov_b64_e32 v[30:31], 0
	v_mov_b64_e32 v[48:49], 0
	v_mov_b64_e32 v[50:51], 0
	v_mov_b64_e32 v[52:53], 0
	v_mov_b64_e32 v[54:55], 0
	v_mov_b64_e32 v[56:57], 0
	v_mov_b64_e32 v[58:59], 0
	v_mov_b64_e32 v[60:61], 0
	v_mov_b64_e32 v[62:63], 0
	v_mov_b64_e32 v[0:1], 0
	v_mov_b64_e32 v[2:3], 0
	v_mov_b64_e32 v[4:5], 0
	v_mov_b64_e32 v[6:7], 0
	v_mov_b64_e32 v[8:9], 0
	v_mov_b64_e32 v[10:11], 0
	v_mov_b64_e32 v[12:13], 0
	v_mov_b64_e32 v[14:15], 0
	s_waitcnt vmcnt(4)
	s_barrier
	ds_read_b128 v[144:147], v180 offset:0
	ds_read_b128 v[128:131], v176 offset:0
	ds_read_b128 v[148:151], v180 offset:4096
	ds_read_b128 v[132:135], v176 offset:4096
	ds_read_b128 v[136:139], v176 offset:8192
	ds_read_b128 v[140:143], v176 offset:12288
	s_movk_i32 s99, 7
; DI void gemm_wide(const bf16_t* __restrict__ W, int ldw, const bf16_t* __restrict__ X, int ldx, int nkt,
;                   f32x16 (&acc)[4][2], bf16_t* lds) {
;     ...
;   for (int kt = 0; kt < nkt; kt += 2) {
;     __builtin_amdgcn_sched_barrier(0);
;     GW_ST2(1, 0, rw0, rw1)                         GW_KS(kt, 0)
;     GW_ST2(1, 128 * LDT, rw2, rw3)                 GW_KS(kt, 1)
;     GW_ST2(1, WT_E, rx0, rx1)                      GW_KS(kt, 2)
;     GW_ST2(1, WT_E + 128 * LDT, rx2, rx3)          GW_KS(kt, 3)
;     __builtin_amdgcn_sched_barrier(0);
;     GW_GLOAD(kt + 3 < nkt ? kt + 3 : nkt - 1)
;     __syncthreads();
;     __builtin_amdgcn_sched_barrier(0);
;     GW_ST2(0, 0, sw0, sw1)                         GW_KS(kt + 1, 0)
;     GW_ST2(0, 128 * LDT, sw2, sw3)                 GW_KS(kt + 1, 1)
;     GW_ST2(0, WT_E, sx0, sx1)                      GW_KS(kt + 1, 2)
;     GW_ST2(0, WT_E + 128 * LDT, sx2, sx3)          GW_KS(kt + 1, 3)
;     __builtin_amdgcn_sched_barrier(0);
;     GW_GLOAD_B(kt + 4 < nkt ? kt + 4 : nkt - 1)
;     __syncthreads();
;   }
.Lgw_up_loop:
	s_waitcnt lgkmcnt(4)
	v_mfma_f32_32x32x16_bf16 v[112:127], v[128:131], v[144:147], v[112:127]
	s_add_u32 m0, s98, 0x18000
	ds_read_b128 v[168:171], v181 offset:0
	s_waitcnt lgkmcnt(4)
	v_mfma_f32_32x32x16_bf16 v[64:79], v[128:131], v[148:151], v[64:79]
	global_load_lds_dwordx4 v184, s[26:27]
	ds_read_b128 v[152:155], v177 offset:0
	s_waitcnt lgkmcnt(4)
	v_mfma_f32_32x32x16_bf16 v[96:111], v[132:135], v[144:147], v[96:111]
	s_add_u32 m0, s98, 0x18400
	ds_read_b128 v[172:175], v181 offset:4096
	v_mfma_f32_32x32x16_bf16 v[32:47], v[132:135], v[148:151], v[32:47]
	global_load_lds_dwordx4 v185, s[26:27]
	ds_read_b128 v[156:159], v177 offset:4096
	s_waitcnt lgkmcnt(5)
	v_mfma_f32_32x32x16_bf16 v[80:95], v[136:139], v[144:147], v[80:95]
	s_add_u32 m0, s98, 0x18800
	ds_read_b128 v[160:163], v177 offset:8192
	v_mfma_f32_32x32x16_bf16 v[16:31], v[136:139], v[148:151], v[16:31]
	global_load_lds_dwordx4 v186, s[26:27]
	ds_read_b128 v[164:167], v177 offset:12288
	s_waitcnt lgkmcnt(6)
	v_mfma_f32_32x32x16_bf16 v[48:63], v[140:143], v[144:147], v[48:63]
	s_add_u32 m0, s98, 0x18c00
	v_mfma_f32_32x32x16_bf16 v[0:15], v[140:143], v[148:151], v[0:15]
	global_load_lds_dwordx4 v187, s[26:27]
	s_add_u32 s26, s26, 0x80
	s_addc_u32 s27, s27, 0
	s_waitcnt lgkmcnt(4)
	v_mfma_f32_32x32x16_bf16 v[112:127], v[152:155], v[168:171], v[112:127]
	ds_read_b128 v[144:147], v182 offset:0
	s_waitcnt lgkmcnt(4)
	v_mfma_f32_32x32x16_bf16 v[64:79], v[152:155], v[172:175], v[64:79]
	ds_read_b128 v[128:131], v178 offset:0
	s_waitcnt lgkmcnt(4)
	v_mfma_f32_32x32x16_bf16 v[96:111], v[156:159], v[168:171], v[96:111]
	ds_read_b128 v[148:151], v182 offset:4096
	v_mfma_f32_32x32x16_bf16 v[32:47], v[156:159], v[172:175], v[32:47]
	ds_read_b128 v[132:135], v178 offset:4096
	s_waitcnt lgkmcnt(5)
	v_mfma_f32_32x32x16_bf16 v[80:95], v[160:163], v[168:171], v[80:95]
	ds_read_b128 v[136:139], v178 offset:8192
	v_mfma_f32_32x32x16_bf16 v[16:31], v[160:163], v[172:175], v[16:31]
	ds_read_b128 v[140:143], v178 offset:12288
	s_waitcnt lgkmcnt(6)
	v_mfma_f32_32x32x16_bf16 v[48:63], v[164:167], v[168:171], v[48:63]
	v_mfma_f32_32x32x16_bf16 v[0:15], v[164:167], v[172:175], v[0:15]
	s_waitcnt lgkmcnt(4)
	v_mfma_f32_32x32x16_bf16 v[112:127], v[128:131], v[144:147], v[112:127]
	ds_read_b128 v[168:171], v183 offset:0
	ds_read_b128 v[152:155], v179 offset:0
	s_waitcnt lgkmcnt(5)
	v_mfma_f32_32x32x16_bf16 v[64:79], v[128:131], v[148:151], v[64:79]
	ds_read_b128 v[172:175], v183 offset:4096
	ds_read_b128 v[156:159], v179 offset:4096
	s_waitcnt lgkmcnt(6)
	v_mfma_f32_32x32x16_bf16 v[96:111], v[132:135], v[144:147], v[96:111]
	ds_read_b128 v[160:163], v179 offset:8192
	ds_read_b128 v[164:167], v179 offset:12288
	v_mfma_f32_32x32x16_bf16 v[32:47], v[132:135], v[148:151], v[32:47]
	s_waitcnt lgkmcnt(7)
	v_mfma_f32_32x32x16_bf16 v[80:95], v[136:139], v[144:147], v[80:95]
	v_mfma_f32_32x32x16_bf16 v[16:31], v[136:139], v[148:151], v[16:31]
	s_waitcnt lgkmcnt(6)
	v_mfma_f32_32x32x16_bf16 v[48:63], v[140:143], v[144:147], v[48:63]
	v_mfma_f32_32x32x16_bf16 v[0:15], v[140:143], v[148:151], v[0:15]
	s_waitcnt vmcnt(0) lgkmcnt(0)
	s_barrier
	v_mfma_f32_32x32x16_bf16 v[112:127], v[152:155], v[168:171], v[112:127]
	s_mov_b32 m0, s98
	ds_read_b128 v[144:147], v180 offset:32768
	v_mfma_f32_32x32x16_bf16 v[64:79], v[152:155], v[172:175], v[64:79]
	ds_read_b128 v[128:131], v176 offset:32768
	global_load_lds_dwordx4 v184, s[8:9]
	v_mfma_f32_32x32x16_bf16 v[96:111], v[156:159], v[168:171], v[96:111]
	s_add_u32 m0, s98, 0x400
	ds_read_b128 v[148:151], v180 offset:36864
	v_mfma_f32_32x32x16_bf16 v[32:47], v[156:159], v[172:175], v[32:47]
	ds_read_b128 v[132:135], v176 offset:36864
	global_load_lds_dwordx4 v185, s[8:9]
	v_mfma_f32_32x32x16_bf16 v[80:95], v[160:163], v[168:171], v[80:95]
	s_add_u32 m0, s98, 0x800
	ds_read_b128 v[136:139], v176 offset:40960
	v_mfma_f32_32x32x16_bf16 v[16:31], v[160:163], v[172:175], v[16:31]
	ds_read_b128 v[140:143], v176 offset:45056
	global_load_lds_dwordx4 v186, s[8:9]
	v_mfma_f32_32x32x16_bf16 v[48:63], v[164:167], v[168:171], v[48:63]
	s_add_u32 m0, s98, 0xc00
	v_mfma_f32_32x32x16_bf16 v[0:15], v[164:167], v[172:175], v[0:15]
	global_load_lds_dwordx4 v187, s[8:9]
	s_add_u32 s8, s8, 0x80
	s_addc_u32 s9, s9, 0
	s_waitcnt lgkmcnt(4)
	v_mfma_f32_32x32x16_bf16 v[112:127], v[128:131], v[144:147], v[112:127]
	s_add_u32 m0, s98, 0x10000
	ds_read_b128 v[168:171], v181 offset:32768
	s_waitcnt lgkmcnt(4)
	v_mfma_f32_32x32x16_bf16 v[64:79], v[128:131], v[148:151], v[64:79]
	global_load_lds_dwordx4 v184, s[26:27]
	ds_read_b128 v[152:155], v177 offset:32768
	s_waitcnt lgkmcnt(4)
	v_mfma_f32_32x32x16_bf16 v[96:111], v[132:135], v[144:147], v[96:111]
	s_add_u32 m0, s98, 0x10400
	ds_read_b128 v[172:175], v181 offset:36864
	v_mfma_f32_32x32x16_bf16 v[32:47], v[132:135], v[148:151], v[32:47]
	global_load_lds_dwordx4 v185, s[26:27]
	ds_read_b128 v[156:159], v177 offset:36864
	s_waitcnt lgkmcnt(5)
	v_mfma_f32_32x32x16_bf16 v[80:95], v[136:139], v[144:147], v[80:95]
	s_add_u32 m0, s98, 0x10800
	ds_read_b128 v[160:163], v177 offset:40960
	v_mfma_f32_32x32x16_bf16 v[16:31], v[136:139], v[148:151], v[16:31]
	global_load_lds_dwordx4 v186, s[26:27]
	ds_read_b128 v[164:167], v177 offset:45056
	s_waitcnt lgkmcnt(6)
	v_mfma_f32_32x32x16_bf16 v[48:63], v[140:143], v[144:147], v[48:63]
	s_add_u32 m0, s98, 0x10c00
	v_mfma_f32_32x32x16_bf16 v[0:15], v[140:143], v[148:151], v[0:15]
	global_load_lds_dwordx4 v187, s[26:27]
	s_add_u32 s26, s26, 0x80
	s_addc_u32 s27, s27, 0
	s_waitcnt lgkmcnt(4)
	v_mfma_f32_32x32x16_bf16 v[112:127], v[152:155], v[168:171], v[112:127]
	ds_read_b128 v[144:147], v182 offset:32768
	s_waitcnt lgkmcnt(4)
; DI void gemm_wide(const bf16_t* __restrict__ W, int ldw, const bf16_t* __restrict__ X, int ldx, int nkt,
;                   f32x16 (&acc)[4][2], bf16_t* lds) {
;     ...
;   for (int kt = 0; kt < nkt; kt += 2) {
;     __builtin_amdgcn_sched_barrier(0);
;     GW_ST2(1, 0, rw0, rw1)                         GW_KS(kt, 0)
;     GW_ST2(1, 128 * LDT, rw2, rw3)                 GW_KS(kt, 1)
;     GW_ST2(1, WT_E, rx0, rx1)                      GW_KS(kt, 2)
;     GW_ST2(1, WT_E + 128 * LDT, rx2, rx3)          GW_KS(kt, 3)
;     __builtin_amdgcn_sched_barrier(0);
;     GW_GLOAD(kt + 3 < nkt ? kt + 3 : nkt - 1)
;     __syncthreads();
;     __builtin_amdgcn_sched_barrier(0);
;     GW_ST2(0, 0, sw0, sw1)                         GW_KS(kt + 1, 0)
;     GW_ST2(0, 128 * LDT, sw2, sw3)                 GW_KS(kt + 1, 1)
;     GW_ST2(0, WT_E, sx0, sx1)                      GW_KS(kt + 1, 2)
;     GW_ST2(0, WT_E + 128 * LDT, sx2, sx3)          GW_KS(kt + 1, 3)
;     __builtin_amdgcn_sched_barrier(0);
;     GW_GLOAD_B(kt + 4 < nkt ? kt + 4 : nkt - 1)
;     __syncthreads();
;   }
	v_mfma_f32_32x32x16_bf16 v[64:79], v[152:155], v[172:175], v[64:79]
	ds_read_b128 v[128:131], v178 offset:32768
	s_waitcnt lgkmcnt(4)
	v_mfma_f32_32x32x16_bf16 v[96:111], v[156:159], v[168:171], v[96:111]
	ds_read_b128 v[148:151], v182 offset:36864
	v_mfma_f32_32x32x16_bf16 v[32:47], v[156:159], v[172:175], v[32:47]
	ds_read_b128 v[132:135], v178 offset:36864
	s_waitcnt lgkmcnt(5)
	v_mfma_f32_32x32x16_bf16 v[80:95], v[160:163], v[168:171], v[80:95]
	ds_read_b128 v[136:139], v178 offset:40960
	v_mfma_f32_32x32x16_bf16 v[16:31], v[160:163], v[172:175], v[16:31]
	ds_read_b128 v[140:143], v178 offset:45056
	s_waitcnt lgkmcnt(6)
	v_mfma_f32_32x32x16_bf16 v[48:63], v[164:167], v[168:171], v[48:63]
	v_mfma_f32_32x32x16_bf16 v[0:15], v[164:167], v[172:175], v[0:15]
	s_waitcnt lgkmcnt(4)
	v_mfma_f32_32x32x16_bf16 v[112:127], v[128:131], v[144:147], v[112:127]
	ds_read_b128 v[168:171], v183 offset:32768
	ds_read_b128 v[152:155], v179 offset:32768
	s_waitcnt lgkmcnt(5)
	v_mfma_f32_32x32x16_bf16 v[64:79], v[128:131], v[148:151], v[64:79]
	ds_read_b128 v[172:175], v183 offset:36864
	ds_read_b128 v[156:159], v179 offset:36864
	s_waitcnt lgkmcnt(6)
	v_mfma_f32_32x32x16_bf16 v[96:111], v[132:135], v[144:147], v[96:111]
	ds_read_b128 v[160:163], v179 offset:40960
	ds_read_b128 v[164:167], v179 offset:45056
	v_mfma_f32_32x32x16_bf16 v[32:47], v[132:135], v[148:151], v[32:47]
	s_waitcnt lgkmcnt(7)
	v_mfma_f32_32x32x16_bf16 v[80:95], v[136:139], v[144:147], v[80:95]
	v_mfma_f32_32x32x16_bf16 v[16:31], v[136:139], v[148:151], v[16:31]
	s_waitcnt lgkmcnt(6)
	v_mfma_f32_32x32x16_bf16 v[48:63], v[140:143], v[144:147], v[48:63]
	v_mfma_f32_32x32x16_bf16 v[0:15], v[140:143], v[148:151], v[0:15]
	s_waitcnt vmcnt(0) lgkmcnt(0)
	s_barrier
	v_mfma_f32_32x32x16_bf16 v[112:127], v[152:155], v[168:171], v[112:127]
	s_add_u32 m0, s98, 0x8000
	ds_read_b128 v[144:147], v180 offset:0
	v_mfma_f32_32x32x16_bf16 v[64:79], v[152:155], v[172:175], v[64:79]
	ds_read_b128 v[128:131], v176 offset:0
	global_load_lds_dwordx4 v184, s[8:9]
	v_mfma_f32_32x32x16_bf16 v[96:111], v[156:159], v[168:171], v[96:111]
	s_add_u32 m0, s98, 0x8400
	ds_read_b128 v[148:151], v180 offset:4096
	v_mfma_f32_32x32x16_bf16 v[32:47], v[156:159], v[172:175], v[32:47]
	ds_read_b128 v[132:135], v176 offset:4096
	global_load_lds_dwordx4 v185, s[8:9]
	v_mfma_f32_32x32x16_bf16 v[80:95], v[160:163], v[168:171], v[80:95]
	s_add_u32 m0, s98, 0x8800
	ds_read_b128 v[136:139], v176 offset:8192
	v_mfma_f32_32x32x16_bf16 v[16:31], v[160:163], v[172:175], v[16:31]
	ds_read_b128 v[140:143], v176 offset:12288
	global_load_lds_dwordx4 v186, s[8:9]
	v_mfma_f32_32x32x16_bf16 v[48:63], v[164:167], v[168:171], v[48:63]
	s_add_u32 m0, s98, 0x8c00
	v_mfma_f32_32x32x16_bf16 v[0:15], v[164:167], v[172:175], v[0:15]
	global_load_lds_dwordx4 v187, s[8:9]
	s_add_u32 s8, s8, 0x80
	s_addc_u32 s9, s9, 0
	s_sub_u32 s99, s99, 1
	s_cmp_lg_u32 s99, 0
	s_cbranch_scc1 .Lgw_up_loop
	s_waitcnt lgkmcnt(4)
	v_mfma_f32_32x32x16_bf16 v[112:127], v[128:131], v[144:147], v[112:127]
	s_add_u32 m0, s98, 0x18000
	ds_read_b128 v[168:171], v181 offset:0
	s_waitcnt lgkmcnt(4)
	v_mfma_f32_32x32x16_bf16 v[64:79], v[128:131], v[148:151], v[64:79]
	global_load_lds_dwordx4 v184, s[26:27]
	ds_read_b128 v[152:155], v177 offset:0
	s_waitcnt lgkmcnt(4)
	v_mfma_f32_32x32x16_bf16 v[96:111], v[132:135], v[144:147], v[96:111]
	s_add_u32 m0, s98, 0x18400
	ds_read_b128 v[172:175], v181 offset:4096
	v_mfma_f32_32x32x16_bf16 v[32:47], v[132:135], v[148:151], v[32:47]
	global_load_lds_dwordx4 v185, s[26:27]
	ds_read_b128 v[156:159], v177 offset:4096
	s_waitcnt lgkmcnt(5)
	v_mfma_f32_32x32x16_bf16 v[80:95], v[136:139], v[144:147], v[80:95]
	s_add_u32 m0, s98, 0x18800
	ds_read_b128 v[160:163], v177 offset:8192
	v_mfma_f32_32x32x16_bf16 v[16:31], v[136:139], v[148:151], v[16:31]
	global_load_lds_dwordx4 v186, s[26:27]
	ds_read_b128 v[164:167], v177 offset:12288
	s_waitcnt lgkmcnt(6)
	v_mfma_f32_32x32x16_bf16 v[48:63], v[140:143], v[144:147], v[48:63]
	s_add_u32 m0, s98, 0x18c00
	v_mfma_f32_32x32x16_bf16 v[0:15], v[140:143], v[148:151], v[0:15]
	global_load_lds_dwordx4 v187, s[26:27]
	s_add_u32 s26, s26, 0x80
	s_addc_u32 s27, s27, 0
	s_waitcnt lgkmcnt(4)
	v_mfma_f32_32x32x16_bf16 v[112:127], v[152:155], v[168:171], v[112:127]
	ds_read_b128 v[144:147], v182 offset:0
	s_waitcnt lgkmcnt(4)
	v_mfma_f32_32x32x16_bf16 v[64:79], v[152:155], v[172:175], v[64:79]
	ds_read_b128 v[128:131], v178 offset:0
	s_waitcnt lgkmcnt(4)
	v_mfma_f32_32x32x16_bf16 v[96:111], v[156:159], v[168:171], v[96:111]
	ds_read_b128 v[148:151], v182 offset:4096
	v_mfma_f32_32x32x16_bf16 v[32:47], v[156:159], v[172:175], v[32:47]
	ds_read_b128 v[132:135], v178 offset:4096
	s_waitcnt lgkmcnt(5)
	v_mfma_f32_32x32x16_bf16 v[80:95], v[160:163], v[168:171], v[80:95]
	ds_read_b128 v[136:139], v178 offset:8192
	v_mfma_f32_32x32x16_bf16 v[16:31], v[160:163], v[172:175], v[16:31]
	ds_read_b128 v[140:143], v178 offset:12288
	s_waitcnt lgkmcnt(6)
	v_mfma_f32_32x32x16_bf16 v[48:63], v[164:167], v[168:171], v[48:63]
	v_mfma_f32_32x32x16_bf16 v[0:15], v[164:167], v[172:175], v[0:15]
	s_waitcnt lgkmcnt(4)
	v_mfma_f32_32x32x16_bf16 v[112:127], v[128:131], v[144:147], v[112:127]
	ds_read_b128 v[168:171], v183 offset:0
	ds_read_b128 v[152:155], v179 offset:0
	s_waitcnt lgkmcnt(5)
	v_mfma_f32_32x32x16_bf16 v[64:79], v[128:131], v[148:151], v[64:79]
	ds_read_b128 v[172:175], v183 offset:4096
	ds_read_b128 v[156:159], v179 offset:4096
	s_waitcnt lgkmcnt(6)
	v_mfma_f32_32x32x16_bf16 v[96:111], v[132:135], v[144:147], v[96:111]
	ds_read_b128 v[160:163], v179 offset:8192
	ds_read_b128 v[164:167], v179 offset:12288
	v_mfma_f32_32x32x16_bf16 v[32:47], v[132:135], v[148:151], v[32:47]
	s_waitcnt lgkmcnt(7)
	v_mfma_f32_32x32x16_bf16 v[80:95], v[136:139], v[144:147], v[80:95]
	v_mfma_f32_32x32x16_bf16 v[16:31], v[136:139], v[148:151], v[16:31]
	s_waitcnt lgkmcnt(6)
	v_mfma_f32_32x32x16_bf16 v[48:63], v[140:143], v[144:147], v[48:63]
	v_mfma_f32_32x32x16_bf16 v[0:15], v[140:143], v[148:151], v[0:15]
	s_waitcnt vmcnt(0) lgkmcnt(0)
	s_barrier
; DI unsigned pack2(float a, float b) { f32x2_t v = {a, b}; bf16x2_t r = __builtin_convertvector(v, bf16x2_t); return __builtin_bit_cast(unsigned, r); }
; DI void gemm_wide(const bf16_t* __restrict__ W, int ldw, const bf16_t* __restrict__ X, int ldx, int nkt,
;                   f32x16 (&acc)[4][2], bf16_t* lds) {
;     ...
;   for (int kt = 0; kt < nkt; kt += 2) {
;     __builtin_amdgcn_sched_barrier(0);
;     GW_ST2(1, 0, rw0, rw1)                         GW_KS(kt, 0)
;     GW_ST2(1, 128 * LDT, rw2, rw3)                 GW_KS(kt, 1)
;     GW_ST2(1, WT_E, rx0, rx1)                      GW_KS(kt, 2)
;     GW_ST2(1, WT_E + 128 * LDT, rx2, rx3)          GW_KS(kt, 3)
;     __builtin_amdgcn_sched_barrier(0);
;     GW_GLOAD(kt + 3 < nkt ? kt + 3 : nkt - 1)
;     __syncthreads();
;     __builtin_amdgcn_sched_barrier(0);
;     GW_ST2(0, 0, sw0, sw1)                         GW_KS(kt + 1, 0)
;     GW_ST2(0, 128 * LDT, sw2, sw3)                 GW_KS(kt + 1, 1)
;     GW_ST2(0, WT_E, sx0, sx1)                      GW_KS(kt + 1, 2)
;     GW_ST2(0, WT_E + 128 * LDT, sx2, sx3)          GW_KS(kt + 1, 3)
;     __builtin_amdgcn_sched_barrier(0);
;     GW_GLOAD_B(kt + 4 < nkt ? kt + 4 : nkt - 1)
;     __syncthreads();
;   }
; DI void phase_up(const P& p, int layer, bf16_t* sm, const Geo& ge) {
;     ...
; #pragma unroll
;     for (int mt = 0; mt < 2; ++mt) {
;       const float rs = mt ? rs1 : rs0;
; #pragma unroll
;       for (int nt = 0; nt < 4; ++nt)
; #pragma unroll
;         for (int qd = 0; qd < 4; ++qd) {
;           const int n = nt_ * 256 + wn * 128 + nt * 32 + 8 * qd + 4 * lh;
;           float a = fmaxf(acc[nt][mt][4 * qd] * rs, 0.f), b = fmaxf(acc[nt][mt][4 * qd + 1] * rs, 0.f);
;           float c = fmaxf(acc[nt][mt][4 * qd + 2] * rs, 0.f), d = fmaxf(acc[nt][mt][4 * qd + 3] * rs, 0.f);
;           *(uint2*)(stg + (mt * 32 + lr) * 136 + nt * 32 + 8 * qd + 4 * lh) = make_uint2(pack2(a * a, b * b), pack2(c * c, d * d));
;         }
;     }
	v_mfma_f32_32x32x16_bf16 v[112:127], v[152:155], v[168:171], v[112:127]
	ds_read_b128 v[144:147], v180 offset:32768
	v_mfma_f32_32x32x16_bf16 v[64:79], v[152:155], v[172:175], v[64:79]
	ds_read_b128 v[128:131], v176 offset:32768
	v_mfma_f32_32x32x16_bf16 v[96:111], v[156:159], v[168:171], v[96:111]
	ds_read_b128 v[148:151], v180 offset:36864
	v_mfma_f32_32x32x16_bf16 v[32:47], v[156:159], v[172:175], v[32:47]
	ds_read_b128 v[132:135], v176 offset:36864
	v_mfma_f32_32x32x16_bf16 v[80:95], v[160:163], v[168:171], v[80:95]
	ds_read_b128 v[136:139], v176 offset:40960
	v_mfma_f32_32x32x16_bf16 v[16:31], v[160:163], v[172:175], v[16:31]
	ds_read_b128 v[140:143], v176 offset:45056
	v_mfma_f32_32x32x16_bf16 v[48:63], v[164:167], v[168:171], v[48:63]
	v_mfma_f32_32x32x16_bf16 v[0:15], v[164:167], v[172:175], v[0:15]
	s_waitcnt lgkmcnt(4)
	v_mfma_f32_32x32x16_bf16 v[112:127], v[128:131], v[144:147], v[112:127]
	ds_read_b128 v[168:171], v181 offset:32768
	s_waitcnt lgkmcnt(4)
	v_mfma_f32_32x32x16_bf16 v[64:79], v[128:131], v[148:151], v[64:79]
	ds_read_b128 v[152:155], v177 offset:32768
	s_waitcnt lgkmcnt(4)
	v_mfma_f32_32x32x16_bf16 v[96:111], v[132:135], v[144:147], v[96:111]
	ds_read_b128 v[172:175], v181 offset:36864
	v_mfma_f32_32x32x16_bf16 v[32:47], v[132:135], v[148:151], v[32:47]
	ds_read_b128 v[156:159], v177 offset:36864
	s_waitcnt lgkmcnt(5)
	v_mfma_f32_32x32x16_bf16 v[80:95], v[136:139], v[144:147], v[80:95]
	ds_read_b128 v[160:163], v177 offset:40960
	v_mfma_f32_32x32x16_bf16 v[16:31], v[136:139], v[148:151], v[16:31]
	ds_read_b128 v[164:167], v177 offset:45056
	s_waitcnt lgkmcnt(6)
	v_mfma_f32_32x32x16_bf16 v[48:63], v[140:143], v[144:147], v[48:63]
	v_mfma_f32_32x32x16_bf16 v[0:15], v[140:143], v[148:151], v[0:15]
	s_waitcnt lgkmcnt(4)
	v_mfma_f32_32x32x16_bf16 v[112:127], v[152:155], v[168:171], v[112:127]
	ds_read_b128 v[144:147], v182 offset:32768
	s_waitcnt lgkmcnt(4)
	v_mfma_f32_32x32x16_bf16 v[64:79], v[152:155], v[172:175], v[64:79]
	ds_read_b128 v[128:131], v178 offset:32768
	s_waitcnt lgkmcnt(4)
	v_mfma_f32_32x32x16_bf16 v[96:111], v[156:159], v[168:171], v[96:111]
	ds_read_b128 v[148:151], v182 offset:36864
	v_mfma_f32_32x32x16_bf16 v[32:47], v[156:159], v[172:175], v[32:47]
	ds_read_b128 v[132:135], v178 offset:36864
	s_waitcnt lgkmcnt(5)
	v_mfma_f32_32x32x16_bf16 v[80:95], v[160:163], v[168:171], v[80:95]
	ds_read_b128 v[136:139], v178 offset:40960
	v_mfma_f32_32x32x16_bf16 v[16:31], v[160:163], v[172:175], v[16:31]
	ds_read_b128 v[140:143], v178 offset:45056
	s_waitcnt lgkmcnt(6)
	v_mfma_f32_32x32x16_bf16 v[48:63], v[164:167], v[168:171], v[48:63]
	v_mfma_f32_32x32x16_bf16 v[0:15], v[164:167], v[172:175], v[0:15]
	s_waitcnt lgkmcnt(4)
	v_mfma_f32_32x32x16_bf16 v[112:127], v[128:131], v[144:147], v[112:127]
	ds_read_b128 v[168:171], v183 offset:32768
	ds_read_b128 v[152:155], v179 offset:32768
	s_waitcnt lgkmcnt(5)
	v_mfma_f32_32x32x16_bf16 v[64:79], v[128:131], v[148:151], v[64:79]
	ds_read_b128 v[172:175], v183 offset:36864
	ds_read_b128 v[156:159], v179 offset:36864
	s_waitcnt lgkmcnt(6)
	v_mfma_f32_32x32x16_bf16 v[96:111], v[132:135], v[144:147], v[96:111]
	ds_read_b128 v[160:163], v179 offset:40960
	ds_read_b128 v[164:167], v179 offset:45056
	v_mfma_f32_32x32x16_bf16 v[32:47], v[132:135], v[148:151], v[32:47]
	s_waitcnt lgkmcnt(7)
	v_mfma_f32_32x32x16_bf16 v[80:95], v[136:139], v[144:147], v[80:95]
	v_mfma_f32_32x32x16_bf16 v[16:31], v[136:139], v[148:151], v[16:31]
	s_waitcnt lgkmcnt(6)
	v_mfma_f32_32x32x16_bf16 v[48:63], v[140:143], v[144:147], v[48:63]
	v_mfma_f32_32x32x16_bf16 v[0:15], v[140:143], v[148:151], v[0:15]
	s_waitcnt vmcnt(0) lgkmcnt(0)
	s_barrier
	v_mfma_f32_32x32x16_bf16 v[112:127], v[152:155], v[168:171], v[112:127]
	v_mfma_f32_32x32x16_bf16 v[64:79], v[152:155], v[172:175], v[64:79]
	v_mfma_f32_32x32x16_bf16 v[96:111], v[156:159], v[168:171], v[96:111]
	v_mfma_f32_32x32x16_bf16 v[32:47], v[156:159], v[172:175], v[32:47]
	v_mfma_f32_32x32x16_bf16 v[80:95], v[160:163], v[168:171], v[80:95]
	v_mfma_f32_32x32x16_bf16 v[16:31], v[160:163], v[172:175], v[16:31]
	v_mfma_f32_32x32x16_bf16 v[48:63], v[164:167], v[168:171], v[48:63]
	v_mfma_f32_32x32x16_bf16 v[0:15], v[164:167], v[172:175], v[0:15]
	s_nop 15
	v_mul_f32_e32 v48, v199, v48
	v_mul_f32_e32 v49, v199, v49
	v_mul_f32_e32 v50, v199, v50
	v_mul_f32_e32 v51, v199, v51
	v_max_f32_e32 v48, 0, v48
	v_max_f32_e32 v49, 0, v49
	v_max_f32_e32 v50, 0, v50
	v_max_f32_e32 v51, 0, v51
	v_pk_mul_f32 v[48:49], v[48:49], v[48:49]
	v_pk_mul_f32 v[50:51], v[50:51], v[50:51]
	v_cvt_pk_bf16_f32 v48, v48, v49
	v_cvt_pk_bf16_f32 v49, v50, v51
	v_mul_f32_e32 v50, v199, v52
	v_mul_f32_e32 v51, v199, v53
	v_mul_f32_e32 v52, v199, v54
	v_mul_f32_e32 v53, v199, v55
	v_max_f32_e32 v50, 0, v50
	v_max_f32_e32 v51, 0, v51
	v_max_f32_e32 v52, 0, v52
	v_max_f32_e32 v53, 0, v53
	v_pk_mul_f32 v[50:51], v[50:51], v[50:51]
	v_pk_mul_f32 v[52:53], v[52:53], v[52:53]
	v_cvt_pk_bf16_f32 v50, v50, v51
	v_cvt_pk_bf16_f32 v51, v52, v53
	ds_write2_b64 v219, v[48:49], v[50:51] offset0:24 offset1:26
	v_mul_f32_e32 v48, v199, v56
	v_mul_f32_e32 v49, v199, v57
	v_mul_f32_e32 v50, v199, v58
	v_mul_f32_e32 v51, v199, v59
	v_max_f32_e32 v48, 0, v48
	v_max_f32_e32 v49, 0, v49
	v_max_f32_e32 v50, 0, v50
	v_max_f32_e32 v51, 0, v51
	v_pk_mul_f32 v[48:49], v[48:49], v[48:49]
	v_pk_mul_f32 v[50:51], v[50:51], v[50:51]
	v_cvt_pk_bf16_f32 v48, v48, v49
	v_cvt_pk_bf16_f32 v49, v50, v51
	v_mul_f32_e32 v50, v199, v60
	v_mul_f32_e32 v51, v199, v61
	v_mul_f32_e32 v52, v199, v62
	v_mul_f32_e32 v53, v199, v63
	v_max_f32_e32 v50, 0, v50
	v_max_f32_e32 v51, 0, v51
	v_max_f32_e32 v52, 0, v52
	v_max_f32_e32 v53, 0, v53
; DI unsigned pack2(float a, float b) { f32x2_t v = {a, b}; bf16x2_t r = __builtin_convertvector(v, bf16x2_t); return __builtin_bit_cast(unsigned, r); }
; DI void phase_up(const P& p, int layer, bf16_t* sm, const Geo& ge) {
;     ...
; #pragma unroll
;     for (int mt = 0; mt < 2; ++mt) {
;       const float rs = mt ? rs1 : rs0;
; #pragma unroll
;       for (int nt = 0; nt < 4; ++nt)
; #pragma unroll
;         for (int qd = 0; qd < 4; ++qd) {
;           const int n = nt_ * 256 + wn * 128 + nt * 32 + 8 * qd + 4 * lh;
;           float a = fmaxf(acc[nt][mt][4 * qd] * rs, 0.f), b = fmaxf(acc[nt][mt][4 * qd + 1] * rs, 0.f);
;           float c = fmaxf(acc[nt][mt][4 * qd + 2] * rs, 0.f), d = fmaxf(acc[nt][mt][4 * qd + 3] * rs, 0.f);
;           *(uint2*)(stg + (mt * 32 + lr) * 136 + nt * 32 + 8 * qd + 4 * lh) = make_uint2(pack2(a * a, b * b), pack2(c * c, d * d));
;         }
;     }
	v_pk_mul_f32 v[50:51], v[50:51], v[50:51]
	v_pk_mul_f32 v[52:53], v[52:53], v[52:53]
	v_cvt_pk_bf16_f32 v50, v50, v51
	v_cvt_pk_bf16_f32 v51, v52, v53
	v_mul_f32_e32 v0, v198, v0
	v_mul_f32_e32 v1, v198, v1
	v_mul_f32_e32 v2, v198, v2
	v_mul_f32_e32 v3, v198, v3
	v_mul_f32_e32 v112, v199, v112
	v_mul_f32_e32 v113, v199, v113
	v_mul_f32_e32 v114, v199, v114
	v_mul_f32_e32 v115, v199, v115
	v_mul_f32_e32 v96, v199, v96
	v_mul_f32_e32 v97, v199, v97
	v_mul_f32_e32 v98, v199, v98
	v_mul_f32_e32 v99, v199, v99
	v_mul_f32_e32 v80, v199, v80
	v_mul_f32_e32 v81, v199, v81
	v_mul_f32_e32 v82, v199, v82
	v_mul_f32_e32 v83, v199, v83
	ds_write2_b64 v219, v[48:49], v[50:51] offset0:28 offset1:30
	v_mul_f32_e32 v48, v198, v64
	v_mul_f32_e32 v49, v198, v65
	v_mul_f32_e32 v50, v198, v66
	v_mul_f32_e32 v51, v198, v67
	v_mul_f32_e32 v32, v198, v32
	v_mul_f32_e32 v33, v198, v33
	v_mul_f32_e32 v34, v198, v34
	v_mul_f32_e32 v35, v198, v35
	v_mul_f32_e32 v16, v198, v16
	v_mul_f32_e32 v17, v198, v17
	v_mul_f32_e32 v18, v198, v18
	v_mul_f32_e32 v19, v198, v19
	v_max_f32_e32 v0, 0, v0
	v_max_f32_e32 v1, 0, v1
	v_max_f32_e32 v2, 0, v2
	v_max_f32_e32 v3, 0, v3
	v_max_f32_e32 v112, 0, v112
	v_max_f32_e32 v113, 0, v113
	v_max_f32_e32 v114, 0, v114
	v_max_f32_e32 v115, 0, v115
	v_max_f32_e32 v96, 0, v96
	v_max_f32_e32 v97, 0, v97
	v_max_f32_e32 v98, 0, v98
	v_max_f32_e32 v99, 0, v99
	v_max_f32_e32 v80, 0, v80
	v_max_f32_e32 v81, 0, v81
	v_max_f32_e32 v82, 0, v82
	v_max_f32_e32 v83, 0, v83
	v_max_f32_e32 v48, 0, v48
	v_max_f32_e32 v49, 0, v49
	v_max_f32_e32 v50, 0, v50
	v_max_f32_e32 v51, 0, v51
	v_max_f32_e32 v32, 0, v32
	v_max_f32_e32 v33, 0, v33
	v_max_f32_e32 v34, 0, v34
	v_max_f32_e32 v35, 0, v35
	v_max_f32_e32 v16, 0, v16
	v_max_f32_e32 v17, 0, v17
	v_max_f32_e32 v18, 0, v18
	v_max_f32_e32 v19, 0, v19
	v_pk_mul_f32 v[0:1], v[0:1], v[0:1]
	v_pk_mul_f32 v[2:3], v[2:3], v[2:3]
	v_pk_mul_f32 v[112:113], v[112:113], v[112:113]
	v_pk_mul_f32 v[114:115], v[114:115], v[114:115]
	v_pk_mul_f32 v[96:97], v[96:97], v[96:97]
	v_pk_mul_f32 v[98:99], v[98:99], v[98:99]
	v_pk_mul_f32 v[80:81], v[80:81], v[80:81]
	v_pk_mul_f32 v[82:83], v[82:83], v[82:83]
	v_pk_mul_f32 v[48:49], v[48:49], v[48:49]
	v_pk_mul_f32 v[50:51], v[50:51], v[50:51]
	v_pk_mul_f32 v[32:33], v[32:33], v[32:33]
	v_pk_mul_f32 v[34:35], v[34:35], v[34:35]
	v_pk_mul_f32 v[16:17], v[16:17], v[16:17]
	v_pk_mul_f32 v[18:19], v[18:19], v[18:19]
	v_cvt_pk_bf16_f32 v0, v0, v1
	v_cvt_pk_bf16_f32 v1, v2, v3
	v_mul_f32_e32 v2, v198, v4
	v_mul_f32_e32 v3, v198, v5
	v_mul_f32_e32 v4, v198, v6
	v_mul_f32_e32 v5, v198, v7
	v_cvt_pk_bf16_f32 v112, v112, v113
	v_cvt_pk_bf16_f32 v113, v114, v115
	v_mul_f32_e32 v114, v199, v116
	v_mul_f32_e32 v115, v199, v117
	v_mul_f32_e32 v116, v199, v118
	v_mul_f32_e32 v117, v199, v119
	v_cvt_pk_bf16_f32 v96, v96, v97
	v_cvt_pk_bf16_f32 v97, v98, v99
	v_mul_f32_e32 v98, v199, v100
	v_mul_f32_e32 v99, v199, v101
	v_mul_f32_e32 v100, v199, v102
	v_mul_f32_e32 v101, v199, v103
	v_cvt_pk_bf16_f32 v80, v80, v81
	v_cvt_pk_bf16_f32 v81, v82, v83
	v_mul_f32_e32 v82, v199, v84
	v_mul_f32_e32 v83, v199, v85
	v_mul_f32_e32 v84, v199, v86
	v_mul_f32_e32 v85, v199, v87
	v_cvt_pk_bf16_f32 v48, v48, v49
	v_cvt_pk_bf16_f32 v49, v50, v51
	v_mul_f32_e32 v50, v198, v68
	v_mul_f32_e32 v51, v198, v69
	v_mul_f32_e32 v52, v198, v70
	v_mul_f32_e32 v53, v198, v71
	v_cvt_pk_bf16_f32 v32, v32, v33
	v_cvt_pk_bf16_f32 v33, v34, v35
	v_mul_f32_e32 v34, v198, v36
	v_mul_f32_e32 v35, v198, v37
	v_mul_f32_e32 v36, v198, v38
	v_mul_f32_e32 v37, v198, v39
	v_cvt_pk_bf16_f32 v16, v16, v17
	v_cvt_pk_bf16_f32 v17, v18, v19
	v_mul_f32_e32 v18, v198, v20
	v_mul_f32_e32 v19, v198, v21
	v_mul_f32_e32 v20, v198, v22
	v_mul_f32_e32 v21, v198, v23
	v_max_f32_e32 v2, 0, v2
	v_max_f32_e32 v3, 0, v3
	v_max_f32_e32 v4, 0, v4
	v_max_f32_e32 v5, 0, v5
	v_max_f32_e32 v114, 0, v114
	v_max_f32_e32 v115, 0, v115
	v_max_f32_e32 v116, 0, v116
	v_max_f32_e32 v117, 0, v117
	v_max_f32_e32 v98, 0, v98
	v_max_f32_e32 v99, 0, v99
	v_max_f32_e32 v100, 0, v100
	v_max_f32_e32 v101, 0, v101
	v_max_f32_e32 v82, 0, v82
	v_max_f32_e32 v83, 0, v83
	v_max_f32_e32 v84, 0, v84
	v_max_f32_e32 v85, 0, v85
	v_max_f32_e32 v50, 0, v50
	v_max_f32_e32 v51, 0, v51
	v_max_f32_e32 v52, 0, v52
	v_max_f32_e32 v53, 0, v53
	v_max_f32_e32 v34, 0, v34
	v_max_f32_e32 v35, 0, v35
	v_max_f32_e32 v36, 0, v36
	v_max_f32_e32 v37, 0, v37
	v_max_f32_e32 v18, 0, v18
	v_max_f32_e32 v19, 0, v19
	v_max_f32_e32 v20, 0, v20
	v_max_f32_e32 v21, 0, v21
	v_pk_mul_f32 v[2:3], v[2:3], v[2:3]
	v_pk_mul_f32 v[4:5], v[4:5], v[4:5]
	v_pk_mul_f32 v[114:115], v[114:115], v[114:115]
	v_pk_mul_f32 v[116:117], v[116:117], v[116:117]
	v_pk_mul_f32 v[98:99], v[98:99], v[98:99]
	v_pk_mul_f32 v[100:101], v[100:101], v[100:101]
	v_pk_mul_f32 v[82:83], v[82:83], v[82:83]
	v_pk_mul_f32 v[84:85], v[84:85], v[84:85]
	v_pk_mul_f32 v[50:51], v[50:51], v[50:51]
	v_pk_mul_f32 v[52:53], v[52:53], v[52:53]
	v_add_u32_e32 v54, 0x2000, v219
	v_pk_mul_f32 v[34:35], v[34:35], v[34:35]
	v_pk_mul_f32 v[36:37], v[36:37], v[36:37]
	v_pk_mul_f32 v[18:19], v[18:19], v[18:19]
	v_pk_mul_f32 v[20:21], v[20:21], v[20:21]
	v_cvt_pk_bf16_f32 v2, v2, v3
	v_cvt_pk_bf16_f32 v3, v4, v5
	v_cvt_pk_bf16_f32 v114, v114, v115
	v_cvt_pk_bf16_f32 v115, v116, v117
	v_cvt_pk_bf16_f32 v98, v98, v99
	v_cvt_pk_bf16_f32 v99, v100, v101
	v_cvt_pk_bf16_f32 v82, v82, v83
	v_cvt_pk_bf16_f32 v83, v84, v85
	v_cvt_pk_bf16_f32 v50, v50, v51
	v_cvt_pk_bf16_f32 v51, v52, v53
	v_cvt_pk_bf16_f32 v34, v34, v35
	v_cvt_pk_bf16_f32 v35, v36, v37
	v_cvt_pk_bf16_f32 v18, v18, v19
	v_cvt_pk_bf16_f32 v19, v20, v21
	ds_write2_b64 v54, v[0:1], v[2:3] offset0:88 offset1:90
; DI int tidx() { int t = threadIdx.x; asm volatile("" : "+v"(t)); return t; }
; DI unsigned pack2(float a, float b) { f32x2_t v = {a, b}; bf16x2_t r = __builtin_convertvector(v, bf16x2_t); return __builtin_bit_cast(unsigned, r); }
; template <bool NT = false>
; DI void stage_rows_store(const bf16_t* stg, bf16_t* dst, size_t ldd, int m0w) {
;   const int lane = tidx() & 63;
; #pragma unroll
;   for (int it = 0; it < 16; ++it) {
;     const int row = it * 4 + (lane >> 4), c16 = lane & 15;
;     const u32x4 v = *(const u32x4*)(stg + row * 136 + c16 * 8);
;     u32x4* d = (u32x4*)(dst + (size_t)(m0w + row) * ldd + c16 * 8);
;     if (NT) __builtin_nontemporal_store(v, d);
;     else *d = v;
;   }
; DI void phase_up(const P& p, int layer, bf16_t* sm, const Geo& ge) {
;     ...
; #pragma unroll
;     for (int mt = 0; mt < 2; ++mt) {
;       const float rs = mt ? rs1 : rs0;
; #pragma unroll
;       for (int nt = 0; nt < 4; ++nt)
; #pragma unroll
;         for (int qd = 0; qd < 4; ++qd) {
;           const int n = nt_ * 256 + wn * 128 + nt * 32 + 8 * qd + 4 * lh;
;           float a = fmaxf(acc[nt][mt][4 * qd] * rs, 0.f), b = fmaxf(acc[nt][mt][4 * qd + 1] * rs, 0.f);
;           float c = fmaxf(acc[nt][mt][4 * qd + 2] * rs, 0.f), d = fmaxf(acc[nt][mt][4 * qd + 3] * rs, 0.f);
;           *(uint2*)(stg + (mt * 32 + lr) * 136 + nt * 32 + 8 * qd + 4 * lh) = make_uint2(pack2(a * a, b * b), pack2(c * c, d * d));
;         }
;     }
	v_mul_f32_e32 v0, v198, v8
	v_mul_f32_e32 v1, v198, v9
	v_mul_f32_e32 v2, v198, v10
	v_mul_f32_e32 v3, v198, v11
	ds_write2_b64 v219, v[112:113], v[114:115] offset1:2
	v_mul_f32_e32 v112, v199, v120
	v_mul_f32_e32 v113, v199, v121
	v_mul_f32_e32 v114, v199, v122
	v_mul_f32_e32 v115, v199, v123
	ds_write2_b64 v219, v[96:97], v[98:99] offset0:8 offset1:10
	v_mul_f32_e32 v96, v199, v104
	v_mul_f32_e32 v97, v199, v105
	v_mul_f32_e32 v98, v199, v106
	v_mul_f32_e32 v99, v199, v107
	ds_write2_b64 v219, v[80:81], v[82:83] offset0:16 offset1:18
	v_mul_f32_e32 v80, v199, v88
	v_mul_f32_e32 v81, v199, v89
	v_mul_f32_e32 v82, v199, v90
	v_mul_f32_e32 v83, v199, v91
	ds_write2_b64 v54, v[48:49], v[50:51] offset0:64 offset1:66
	v_mul_f32_e32 v48, v198, v72
	v_mul_f32_e32 v49, v198, v73
	v_mul_f32_e32 v50, v198, v74
	v_mul_f32_e32 v51, v198, v75
	ds_write2_b64 v54, v[32:33], v[34:35] offset0:72 offset1:74
	v_mul_f32_e32 v32, v198, v40
	v_mul_f32_e32 v33, v198, v41
	v_mul_f32_e32 v34, v198, v42
	v_mul_f32_e32 v35, v198, v43
	ds_write2_b64 v54, v[16:17], v[18:19] offset0:80 offset1:82
	v_mul_f32_e32 v16, v198, v24
	v_mul_f32_e32 v17, v198, v25
	v_mul_f32_e32 v18, v198, v26
	v_mul_f32_e32 v19, v198, v27
	v_max_f32_e32 v0, 0, v0
	v_max_f32_e32 v1, 0, v1
	v_max_f32_e32 v2, 0, v2
	v_max_f32_e32 v3, 0, v3
	v_max_f32_e32 v112, 0, v112
	v_max_f32_e32 v113, 0, v113
	v_max_f32_e32 v114, 0, v114
	v_max_f32_e32 v115, 0, v115
	v_max_f32_e32 v96, 0, v96
	v_max_f32_e32 v97, 0, v97
	v_max_f32_e32 v98, 0, v98
	v_max_f32_e32 v99, 0, v99
	v_max_f32_e32 v80, 0, v80
	v_max_f32_e32 v81, 0, v81
	v_max_f32_e32 v82, 0, v82
	v_max_f32_e32 v83, 0, v83
	v_max_f32_e32 v48, 0, v48
	v_max_f32_e32 v49, 0, v49
	v_max_f32_e32 v50, 0, v50
	v_max_f32_e32 v51, 0, v51
	v_max_f32_e32 v32, 0, v32
	v_max_f32_e32 v33, 0, v33
	v_max_f32_e32 v34, 0, v34
	v_max_f32_e32 v35, 0, v35
	v_max_f32_e32 v16, 0, v16
	v_max_f32_e32 v17, 0, v17
	v_max_f32_e32 v18, 0, v18
	v_max_f32_e32 v19, 0, v19
	v_pk_mul_f32 v[0:1], v[0:1], v[0:1]
	v_pk_mul_f32 v[2:3], v[2:3], v[2:3]
	v_pk_mul_f32 v[112:113], v[112:113], v[112:113]
	v_pk_mul_f32 v[114:115], v[114:115], v[114:115]
	v_pk_mul_f32 v[96:97], v[96:97], v[96:97]
	v_pk_mul_f32 v[98:99], v[98:99], v[98:99]
	v_pk_mul_f32 v[80:81], v[80:81], v[80:81]
	v_pk_mul_f32 v[82:83], v[82:83], v[82:83]
	v_pk_mul_f32 v[48:49], v[48:49], v[48:49]
	v_pk_mul_f32 v[50:51], v[50:51], v[50:51]
	v_pk_mul_f32 v[32:33], v[32:33], v[32:33]
	v_pk_mul_f32 v[34:35], v[34:35], v[34:35]
	v_pk_mul_f32 v[16:17], v[16:17], v[16:17]
	v_pk_mul_f32 v[18:19], v[18:19], v[18:19]
	v_cvt_pk_bf16_f32 v0, v0, v1
	v_cvt_pk_bf16_f32 v1, v2, v3
	v_mul_f32_e32 v2, v198, v12
	v_mul_f32_e32 v3, v198, v13
	v_mul_f32_e32 v4, v198, v14
	v_mul_f32_e32 v5, v198, v15
	v_cvt_pk_bf16_f32 v112, v112, v113
	v_cvt_pk_bf16_f32 v113, v114, v115
	v_mul_f32_e32 v114, v199, v124
	v_mul_f32_e32 v115, v199, v125
	v_mul_f32_e32 v116, v199, v126
	v_mul_f32_e32 v117, v199, v127
	v_cvt_pk_bf16_f32 v96, v96, v97
	v_cvt_pk_bf16_f32 v97, v98, v99
	v_mul_f32_e32 v98, v199, v108
	v_mul_f32_e32 v99, v199, v109
	v_mul_f32_e32 v100, v199, v110
	v_mul_f32_e32 v101, v199, v111
	v_cvt_pk_bf16_f32 v80, v80, v81
	v_cvt_pk_bf16_f32 v81, v82, v83
	v_mul_f32_e32 v82, v199, v92
	v_mul_f32_e32 v83, v199, v93
	v_mul_f32_e32 v84, v199, v94
	v_mul_f32_e32 v85, v199, v95
	v_cvt_pk_bf16_f32 v48, v48, v49
	v_cvt_pk_bf16_f32 v49, v50, v51
	v_mul_f32_e32 v50, v198, v76
	v_mul_f32_e32 v51, v198, v77
	v_mul_f32_e32 v52, v198, v78
	v_mul_f32_e32 v53, v198, v79
	v_cvt_pk_bf16_f32 v32, v32, v33
	v_cvt_pk_bf16_f32 v33, v34, v35
	v_mul_f32_e32 v34, v198, v44
	v_mul_f32_e32 v35, v198, v45
	v_mul_f32_e32 v36, v198, v46
	v_mul_f32_e32 v37, v198, v47
	v_cvt_pk_bf16_f32 v16, v16, v17
	v_cvt_pk_bf16_f32 v17, v18, v19
	v_mul_f32_e32 v18, v198, v28
	v_mul_f32_e32 v19, v198, v29
	v_mul_f32_e32 v20, v198, v30
	v_mul_f32_e32 v21, v198, v31
	v_max_f32_e32 v2, 0, v2
	v_max_f32_e32 v3, 0, v3
	v_max_f32_e32 v4, 0, v4
	v_max_f32_e32 v5, 0, v5
	v_max_f32_e32 v114, 0, v114
	v_max_f32_e32 v115, 0, v115
	v_max_f32_e32 v116, 0, v116
	v_max_f32_e32 v117, 0, v117
	v_max_f32_e32 v98, 0, v98
	v_max_f32_e32 v99, 0, v99
	v_max_f32_e32 v100, 0, v100
	v_max_f32_e32 v101, 0, v101
	v_max_f32_e32 v82, 0, v82
	v_max_f32_e32 v83, 0, v83
	v_max_f32_e32 v84, 0, v84
	v_max_f32_e32 v85, 0, v85
	v_max_f32_e32 v50, 0, v50
	v_max_f32_e32 v51, 0, v51
	v_max_f32_e32 v52, 0, v52
	v_max_f32_e32 v53, 0, v53
	v_max_f32_e32 v34, 0, v34
	v_max_f32_e32 v35, 0, v35
	v_max_f32_e32 v36, 0, v36
	v_max_f32_e32 v37, 0, v37
	v_max_f32_e32 v18, 0, v18
	v_max_f32_e32 v19, 0, v19
	v_max_f32_e32 v20, 0, v20
	v_max_f32_e32 v21, 0, v21
	v_pk_mul_f32 v[2:3], v[2:3], v[2:3]
	v_pk_mul_f32 v[4:5], v[4:5], v[4:5]
	v_pk_mul_f32 v[114:115], v[114:115], v[114:115]
	v_pk_mul_f32 v[116:117], v[116:117], v[116:117]
	v_pk_mul_f32 v[98:99], v[98:99], v[98:99]
	v_pk_mul_f32 v[100:101], v[100:101], v[100:101]
	v_pk_mul_f32 v[82:83], v[82:83], v[82:83]
	v_pk_mul_f32 v[84:85], v[84:85], v[84:85]
	v_pk_mul_f32 v[50:51], v[50:51], v[50:51]
	v_pk_mul_f32 v[52:53], v[52:53], v[52:53]
	v_pk_mul_f32 v[34:35], v[34:35], v[34:35]
	v_pk_mul_f32 v[36:37], v[36:37], v[36:37]
	v_pk_mul_f32 v[18:19], v[18:19], v[18:19]
	v_pk_mul_f32 v[20:21], v[20:21], v[20:21]
	v_cvt_pk_bf16_f32 v2, v2, v3
	v_cvt_pk_bf16_f32 v3, v4, v5
	v_cvt_pk_bf16_f32 v114, v114, v115
	v_cvt_pk_bf16_f32 v115, v116, v117
	v_cvt_pk_bf16_f32 v98, v98, v99
	v_cvt_pk_bf16_f32 v99, v100, v101
	v_cvt_pk_bf16_f32 v82, v82, v83
	v_cvt_pk_bf16_f32 v83, v84, v85
	v_cvt_pk_bf16_f32 v50, v50, v51
	v_cvt_pk_bf16_f32 v51, v52, v53
	v_cvt_pk_bf16_f32 v34, v34, v35
	v_cvt_pk_bf16_f32 v35, v36, v37
	v_cvt_pk_bf16_f32 v18, v18, v19
	v_cvt_pk_bf16_f32 v19, v20, v21
	ds_write2_b64 v54, v[0:1], v[2:3] offset0:92 offset1:94
	v_mov_b32_e32 v2, v195
	ds_write2_b64 v219, v[112:113], v[114:115] offset0:4 offset1:6
	ds_write2_b64 v219, v[96:97], v[98:99] offset0:12 offset1:14
	ds_write2_b64 v219, v[80:81], v[82:83] offset0:20 offset1:22
	ds_write2_b64 v54, v[48:49], v[50:51] offset0:68 offset1:70
	ds_write2_b64 v54, v[32:33], v[34:35] offset0:76 offset1:78
	ds_write2_b64 v54, v[16:17], v[18:19] offset0:84 offset1:86
	s_lshl_b32 s0, s0, 8
	s_ashr_i32 s1, s0, 31
	v_bfe_u32 v5, v2, 4, 2
	v_lshlrev_b32_e32 v2, 4, v2
	v_lshl_add_u64 v[0:1], s[0:1], 1, v[196:197]
	v_and_b32_e32 v192, 0xf0, v2
	v_lshl_add_u64 v[8:9], v[0:1], 0, v[192:193]
	v_mul_u32_u24_e32 v0, 0x110, v5
	v_add3_u32 v12, v218, v192, v0
	ds_read_b128 v[0:3], v12
	v_lshl_add_u32 v4, s6, 8, v216
	v_or_b32_e32 v13, v5, v4
	ds_read_b128 v[4:7], v12 offset:1088
	v_mad_i64_i32 v[10:11], s[0:1], v13, s24, v[8:9]
	s_waitcnt lgkmcnt(1)
; DI int tidx() { int t = threadIdx.x; asm volatile("" : "+v"(t)); return t; }
; template <bool NT = false>
; DI void stage_rows_store(const bf16_t* stg, bf16_t* dst, size_t ldd, int m0w) {
;   const int lane = tidx() & 63;
; #pragma unroll
;   for (int it = 0; it < 16; ++it) {
;     const int row = it * 4 + (lane >> 4), c16 = lane & 15;
;     const u32x4 v = *(const u32x4*)(stg + row * 136 + c16 * 8);
;     u32x4* d = (u32x4*)(dst + (size_t)(m0w + row) * ldd + c16 * 8);
;     if (NT) __builtin_nontemporal_store(v, d);
;     else *d = v;
;   }
	global_store_dwordx4 v[10:11], v[0:3], off
	s_add_i32 s5, s5, s10
	s_nop 0
	v_or_b32_e32 v0, 4, v13
	v_mad_i64_i32 v[0:1], s[0:1], v0, s24, v[8:9]
	s_waitcnt lgkmcnt(0)
	global_store_dwordx4 v[0:1], v[4:7], off
	ds_read_b128 v[0:3], v12 offset:2176
	s_nop 0
	v_or_b32_e32 v4, 8, v13
	v_mad_i64_i32 v[10:11], s[0:1], v4, s24, v[8:9]
	ds_read_b128 v[4:7], v12 offset:3264
	s_waitcnt lgkmcnt(1)
	global_store_dwordx4 v[10:11], v[0:3], off
	s_nop 1
	v_or_b32_e32 v0, 12, v13
	v_mad_i64_i32 v[0:1], s[0:1], v0, s24, v[8:9]
	s_waitcnt lgkmcnt(0)
	global_store_dwordx4 v[0:1], v[4:7], off
	ds_read_b128 v[0:3], v12 offset:4352
	s_nop 0
	v_or_b32_e32 v4, 16, v13
	v_mad_i64_i32 v[10:11], s[0:1], v4, s24, v[8:9]
	ds_read_b128 v[4:7], v12 offset:5440
	s_waitcnt lgkmcnt(1)
	global_store_dwordx4 v[10:11], v[0:3], off
	s_nop 1
	v_or_b32_e32 v0, 20, v13
	v_mad_i64_i32 v[0:1], s[0:1], v0, s24, v[8:9]
	s_waitcnt lgkmcnt(0)
	global_store_dwordx4 v[0:1], v[4:7], off
	ds_read_b128 v[0:3], v12 offset:6528
	s_nop 0
	v_or_b32_e32 v4, 24, v13
	v_mad_i64_i32 v[10:11], s[0:1], v4, s24, v[8:9]
	ds_read_b128 v[4:7], v12 offset:7616
	s_waitcnt lgkmcnt(1)
	global_store_dwordx4 v[10:11], v[0:3], off
	s_nop 1
	v_or_b32_e32 v0, 28, v13
	v_mad_i64_i32 v[0:1], s[0:1], v0, s24, v[8:9]
	s_waitcnt lgkmcnt(0)
	global_store_dwordx4 v[0:1], v[4:7], off
	ds_read_b128 v[0:3], v12 offset:8704
	s_nop 0
	v_or_b32_e32 v4, 32, v13
	v_mad_i64_i32 v[10:11], s[0:1], v4, s24, v[8:9]
	ds_read_b128 v[4:7], v12 offset:9792
	s_waitcnt lgkmcnt(1)
	global_store_dwordx4 v[10:11], v[0:3], off
	s_nop 1
	v_or_b32_e32 v0, 36, v13
	v_mad_i64_i32 v[0:1], s[0:1], v0, s24, v[8:9]
	s_waitcnt lgkmcnt(0)
	global_store_dwordx4 v[0:1], v[4:7], off
	ds_read_b128 v[0:3], v12 offset:10880
	s_nop 0
	v_or_b32_e32 v4, 40, v13
	v_mad_i64_i32 v[10:11], s[0:1], v4, s24, v[8:9]
	ds_read_b128 v[4:7], v12 offset:11968
	s_waitcnt lgkmcnt(1)
	global_store_dwordx4 v[10:11], v[0:3], off
	s_nop 1
	v_or_b32_e32 v0, 44, v13
	v_mad_i64_i32 v[0:1], s[0:1], v0, s24, v[8:9]
	s_waitcnt lgkmcnt(0)
	global_store_dwordx4 v[0:1], v[4:7], off
	ds_read_b128 v[0:3], v12 offset:13056
	s_nop 0
	v_or_b32_e32 v4, 48, v13
	v_mad_i64_i32 v[10:11], s[0:1], v4, s24, v[8:9]
	ds_read_b128 v[4:7], v12 offset:14144
	s_waitcnt lgkmcnt(1)
	global_store_dwordx4 v[10:11], v[0:3], off
	s_nop 1
	v_or_b32_e32 v0, 52, v13
	v_mad_i64_i32 v[0:1], s[0:1], v0, s24, v[8:9]
	s_waitcnt lgkmcnt(0)
	global_store_dwordx4 v[0:1], v[4:7], off
	ds_read_b128 v[0:3], v12 offset:15232
	s_nop 0
	v_or_b32_e32 v4, 56, v13
	v_mad_i64_i32 v[10:11], s[0:1], v4, s24, v[8:9]
	ds_read_b128 v[4:7], v12 offset:16320
	s_waitcnt lgkmcnt(1)
	global_store_dwordx4 v[10:11], v[0:3], off
	s_nop 1
	v_or_b32_e32 v0, 60, v13
	v_mad_i64_i32 v[0:1], s[0:1], v0, s24, v[8:9]
	s_waitcnt lgkmcnt(0)
	global_store_dwordx4 v[0:1], v[4:7], off
	s_branch .LBB0_1140

; DI int tidx() { int t = threadIdx.x; asm volatile("" : "+v"(t)); return t; }
; DI void gemm_wide(const bf16_t* __restrict__ W, int ldw, const bf16_t* __restrict__ X, int ldx, int nkt,
;                   f32x16 (&acc)[4][2], bf16_t* lds) {
;   const int tid = tidx(), lane = tid & 63, wv = tid >> 6, wn = wv & 1, wm = wv >> 1;
;   const int lr = lane & 31, lh = lane >> 5;
;   const int lrow = tid >> 3, lkc = (tid & 7) * 8;
;   const bf16_t* wp = W + (size_t)lrow * ldw + lkc;
;   const bf16_t* xp = X + (size_t)lrow * ldx + lkc;
;   const size_t wst = (size_t)64 * ldw, xst = (size_t)64 * ldx;
;   u32x4 rw0, rw1, rw2, rw3, rx0, rx1, rx2, rx3;
;     ...
;   u32x4 sw0, sw1, sw2, sw3, sx0, sx1, sx2, sx3;
;     ...
;   __syncthreads();
;   GW_GLOAD(0)
;   GW_LSTORE(0)
;   GW_GLOAD(1)
;   GW_GLOAD_B(nkt > 2 ? 2 : nkt - 1)
;   __syncthreads();
; DI void phase_resid(const P& p, const bf16_t* W, const bf16_t* X, int K, bf16_t* sm, const Geo& ge, bool last) {
;     ...
;   while (tw.next(mt_, nt_)) {
;     f32x16 acc[4][2]; zero_acc8(acc);
;     const int ldk = K + 64;
;     gemm_wide(W + (size_t)nt_ * 256 * ldk, ldk, X + (size_t)mt_ * 256 * ldk, ldk, K / 64, acc, sm);
.LBB0_1161:
	s_cmp_gt_i32 s27, 63
	s_cselect_b64 s[6:7], -1, 0
	s_cmp_lt_i32 s27, 64
	s_mov_b64 s[4:5], -1
	s_mov_b32 s8, s54
	s_cbranch_scc0 .LBB0_1181
	s_ashr_i32 s8, s27, 3
	s_cmp_lt_i32 s8, 4
	s_cbranch_scc0 .LBB0_1199
	s_and_b32 s5, s27, 7
	s_or_b32 s4, s5, s55
	s_mul_i32 s28, s8, 0x208000
	s_mul_hi_i32 s9, s8, 0x208000
	s_add_u32 s28, s25, s28
	s_addc_u32 s29, s26, s9
	s_mul_i32 s9, s4, 0x208000
	s_add_u32 s30, s58, s9
	s_addc_u32 s31, s59, 0
	v_and_b32_e32 v128, 63, v195
	v_lshrrev_b32_e32 v129, 6, v195
	v_and_b32_e32 v130, 31, v128
	v_lshrrev_b32_e32 v131, 5, v128
	v_bfe_u32 v132, v130, 1, 3
	v_lshlrev_b32_e32 v133, 7, v130
	v_xor_b32_e32 v134, v131, v132
	v_lshl_add_u32 v135, v134, 4, v133
	v_and_b32_e32 v136, 1, v129
	v_lshlrev_b32_e32 v136, 14, v136
	v_lshrrev_b32_e32 v137, 1, v129
	v_lshlrev_b32_e32 v137, 13, v137
	v_add_u32_e32 v137, 0x10000, v137
	v_readfirstlane_b32 s98, v129
	v_add_u32_e32 v176, v136, v135
	v_xor_b32_e32 v177, 32, v176
	v_xor_b32_e32 v178, 64, v176
	v_xor_b32_e32 v179, 0x60, v176
	v_add_u32_e32 v180, v137, v135
	v_xor_b32_e32 v181, 32, v180
	v_xor_b32_e32 v182, 64, v180
	v_xor_b32_e32 v183, 0x60, v180
	s_lshl_b32 s98, s98, 12
	s_movk_i32 s100, 8320
	v_lshrrev_b32_e32 v138, 3, v128
	v_lshl_add_u32 v138, v129, 5, v138
	v_mul_lo_u32 v139, v138, s100
	v_and_b32_e32 v140, 7, v128
	v_lshrrev_b32_e32 v141, 4, v128
	v_xor_b32_e32 v142, v140, v141
	v_xor_b32_e32 v143, 4, v142
	v_lshl_add_u32 v184, v142, 4, v139
	v_lshl_add_u32 v185, v143, 4, v139
	v_add_u32_e32 v185, 0x10400, v185
	v_add_u32_e32 v186, 0x20800, v184
	v_add_u32_e32 v187, 0x20800, v185
	v_and_b32_e32 v140, 3, v129
	v_lshl_add_u32 v140, v140, 6, v128
	v_mul_lo_u32 v189, v140, s100
	s_cmp_lt_u32 s98, 0x4000
	s_cselect_b32 s100, s28, s30
	s_cselect_b32 s101, s29, s31
	s_add_u32 s100, s100, 0x100
	s_addc_u32 s101, s101, 0
	s_barrier
	s_mov_b32 m0, s98
	s_nop 0
	global_load_lds_dwordx4 v184, s[28:29]
	s_add_u32 m0, s98, 0x400
	s_nop 0
	global_load_lds_dwordx4 v185, s[28:29]
	s_add_u32 m0, s98, 0x800
	s_nop 0
	global_load_lds_dwordx4 v186, s[28:29]
	s_add_u32 m0, s98, 0xc00
	s_nop 0
	global_load_lds_dwordx4 v187, s[28:29]
	s_add_u32 s28, s28, 0x80
	s_addc_u32 s29, s29, 0
	s_add_u32 m0, s98, 0x10000
	s_nop 0
	global_load_lds_dwordx4 v184, s[30:31]
	s_add_u32 m0, s98, 0x10400
	s_nop 0
	global_load_lds_dwordx4 v185, s[30:31]
	s_add_u32 m0, s98, 0x10800
	s_nop 0
	global_load_lds_dwordx4 v186, s[30:31]
	s_add_u32 m0, s98, 0x10c00
	s_nop 0
	global_load_lds_dwordx4 v187, s[30:31]
	s_add_u32 s30, s30, 0x80
	s_addc_u32 s31, s31, 0
	s_add_u32 m0, s98, 0x8000
	s_nop 0
	global_load_lds_dwordx4 v184, s[28:29]
	s_add_u32 m0, s98, 0x8400
	s_nop 0
	global_load_lds_dwordx4 v185, s[28:29]
	s_add_u32 m0, s98, 0x8800
	s_nop 0
	global_load_lds_dwordx4 v186, s[28:29]
	s_add_u32 m0, s98, 0x8c00
	s_nop 0
	global_load_lds_dwordx4 v187, s[28:29]
	s_add_u32 s28, s28, 0x80
	s_addc_u32 s29, s29, 0
	v_mov_b64_e32 v[112:113], 0
	v_mov_b64_e32 v[114:115], 0
	v_mov_b64_e32 v[116:117], 0
	v_mov_b64_e32 v[118:119], 0
	v_mov_b64_e32 v[120:121], 0
	v_mov_b64_e32 v[122:123], 0
	v_mov_b64_e32 v[124:125], 0
	v_mov_b64_e32 v[126:127], 0
	v_mov_b64_e32 v[80:81], 0
	v_mov_b64_e32 v[82:83], 0
	v_mov_b64_e32 v[84:85], 0
	v_mov_b64_e32 v[86:87], 0
	v_mov_b64_e32 v[88:89], 0
	v_mov_b64_e32 v[90:91], 0
	v_mov_b64_e32 v[92:93], 0
	v_mov_b64_e32 v[94:95], 0
	v_mov_b64_e32 v[96:97], 0
	v_mov_b64_e32 v[98:99], 0
	v_mov_b64_e32 v[100:101], 0
	v_mov_b64_e32 v[102:103], 0
	v_mov_b64_e32 v[104:105], 0
	v_mov_b64_e32 v[106:107], 0
	v_mov_b64_e32 v[108:109], 0
	v_mov_b64_e32 v[110:111], 0
	v_mov_b64_e32 v[64:65], 0
	v_mov_b64_e32 v[66:67], 0
	v_mov_b64_e32 v[68:69], 0
	v_mov_b64_e32 v[70:71], 0
	v_mov_b64_e32 v[72:73], 0
	v_mov_b64_e32 v[74:75], 0
	v_mov_b64_e32 v[76:77], 0
	v_mov_b64_e32 v[78:79], 0
	v_mov_b64_e32 v[48:49], 0
	v_mov_b64_e32 v[50:51], 0
	v_mov_b64_e32 v[52:53], 0
	v_mov_b64_e32 v[54:55], 0
	v_mov_b64_e32 v[56:57], 0
	v_mov_b64_e32 v[58:59], 0
	v_mov_b64_e32 v[60:61], 0
	v_mov_b64_e32 v[62:63], 0
	v_mov_b64_e32 v[16:17], 0
	v_mov_b64_e32 v[18:19], 0
	v_mov_b64_e32 v[20:21], 0
	v_mov_b64_e32 v[22:23], 0
	v_mov_b64_e32 v[24:25], 0
	v_mov_b64_e32 v[26:27], 0
	v_mov_b64_e32 v[28:29], 0
	v_mov_b64_e32 v[30:31], 0
	v_mov_b64_e32 v[32:33], 0
	v_mov_b64_e32 v[34:35], 0
	v_mov_b64_e32 v[36:37], 0
	v_mov_b64_e32 v[38:39], 0
	v_mov_b64_e32 v[40:41], 0
	v_mov_b64_e32 v[42:43], 0
	v_mov_b64_e32 v[44:45], 0
	v_mov_b64_e32 v[46:47], 0
	v_mov_b64_e32 v[0:1], 0
	v_mov_b64_e32 v[2:3], 0
	v_mov_b64_e32 v[4:5], 0
	v_mov_b64_e32 v[6:7], 0
	v_mov_b64_e32 v[8:9], 0
	v_mov_b64_e32 v[10:11], 0
	v_mov_b64_e32 v[12:13], 0
	v_mov_b64_e32 v[14:15], 0
	s_waitcnt vmcnt(4)
	s_barrier
	ds_read_b128 v[144:147], v180 offset:0
	ds_read_b128 v[128:131], v176 offset:0
	ds_read_b128 v[148:151], v180 offset:4096
	ds_read_b128 v[132:135], v176 offset:4096
	ds_read_b128 v[136:139], v176 offset:8192
	ds_read_b128 v[140:143], v176 offset:12288
	s_movk_i32 s99, 31
; DI void gemm_wide(const bf16_t* __restrict__ W, int ldw, const bf16_t* __restrict__ X, int ldx, int nkt,
;                   f32x16 (&acc)[4][2], bf16_t* lds) {
;     ...
;   __syncthreads();
;   GW_GLOAD(0)
;   GW_LSTORE(0)
;   GW_GLOAD(1)
;   GW_GLOAD_B(nkt > 2 ? 2 : nkt - 1)
;   __syncthreads();
;   for (int kt = 0; kt < nkt; kt += 2) {
;     __builtin_amdgcn_sched_barrier(0);
;     GW_ST2(1, 0, rw0, rw1)                         GW_KS(kt, 0)
;     GW_ST2(1, 128 * LDT, rw2, rw3)                 GW_KS(kt, 1)
;     GW_ST2(1, WT_E, rx0, rx1)                      GW_KS(kt, 2)
;     GW_ST2(1, WT_E + 128 * LDT, rx2, rx3)          GW_KS(kt, 3)
;     __builtin_amdgcn_sched_barrier(0);
;     GW_GLOAD(kt + 3 < nkt ? kt + 3 : nkt - 1)
;     __syncthreads();
;     __builtin_amdgcn_sched_barrier(0);
;     GW_ST2(0, 0, sw0, sw1)                         GW_KS(kt + 1, 0)
;     GW_ST2(0, 128 * LDT, sw2, sw3)                 GW_KS(kt + 1, 1)
;     GW_ST2(0, WT_E, sx0, sx1)                      GW_KS(kt + 1, 2)
;     GW_ST2(0, WT_E + 128 * LDT, sx2, sx3)          GW_KS(kt + 1, 3)
;     __builtin_amdgcn_sched_barrier(0);
;     GW_GLOAD_B(kt + 4 < nkt ? kt + 4 : nkt - 1)
;     __syncthreads();
;   }
.Lgw_down_loop:
	s_waitcnt lgkmcnt(4)
	v_mfma_f32_32x32x16_bf16 v[112:127], v[128:131], v[144:147], v[112:127]
	s_add_u32 m0, s98, 0x18000
	ds_read_b128 v[168:171], v181 offset:0
	s_waitcnt lgkmcnt(4)
	v_mfma_f32_32x32x16_bf16 v[80:95], v[128:131], v[148:151], v[80:95]
	global_load_lds_dwordx4 v184, s[30:31]
	ds_read_b128 v[152:155], v177 offset:0
	s_waitcnt lgkmcnt(4)
	v_mfma_f32_32x32x16_bf16 v[96:111], v[132:135], v[144:147], v[96:111]
	s_add_u32 m0, s98, 0x18400
	ds_read_b128 v[172:175], v181 offset:4096
	v_mfma_f32_32x32x16_bf16 v[64:79], v[132:135], v[148:151], v[64:79]
	global_load_lds_dwordx4 v185, s[30:31]
	ds_read_b128 v[156:159], v177 offset:4096
	s_waitcnt lgkmcnt(5)
	v_mfma_f32_32x32x16_bf16 v[48:63], v[136:139], v[144:147], v[48:63]
	s_add_u32 m0, s98, 0x18800
	ds_read_b128 v[160:163], v177 offset:8192
	v_mfma_f32_32x32x16_bf16 v[16:31], v[136:139], v[148:151], v[16:31]
	global_load_lds_dwordx4 v186, s[30:31]
	ds_read_b128 v[164:167], v177 offset:12288
	s_waitcnt lgkmcnt(6)
	v_mfma_f32_32x32x16_bf16 v[32:47], v[140:143], v[144:147], v[32:47]
	s_add_u32 m0, s98, 0x18c00
	v_mfma_f32_32x32x16_bf16 v[0:15], v[140:143], v[148:151], v[0:15]
	global_load_lds_dwordx4 v187, s[30:31]
	s_add_u32 s30, s30, 0x80
	s_addc_u32 s31, s31, 0
	s_waitcnt lgkmcnt(4)
	v_mfma_f32_32x32x16_bf16 v[112:127], v[152:155], v[168:171], v[112:127]
	ds_read_b128 v[144:147], v182 offset:0
	s_waitcnt lgkmcnt(4)
	v_mfma_f32_32x32x16_bf16 v[80:95], v[152:155], v[172:175], v[80:95]
	ds_read_b128 v[128:131], v178 offset:0
	s_waitcnt lgkmcnt(4)
	v_mfma_f32_32x32x16_bf16 v[96:111], v[156:159], v[168:171], v[96:111]
	ds_read_b128 v[148:151], v182 offset:4096
	v_mfma_f32_32x32x16_bf16 v[64:79], v[156:159], v[172:175], v[64:79]
	ds_read_b128 v[132:135], v178 offset:4096
	s_waitcnt lgkmcnt(5)
	v_mfma_f32_32x32x16_bf16 v[48:63], v[160:163], v[168:171], v[48:63]
	ds_read_b128 v[136:139], v178 offset:8192
	v_mfma_f32_32x32x16_bf16 v[16:31], v[160:163], v[172:175], v[16:31]
	ds_read_b128 v[140:143], v178 offset:12288
	s_waitcnt lgkmcnt(6)
	v_mfma_f32_32x32x16_bf16 v[32:47], v[164:167], v[168:171], v[32:47]
	v_mfma_f32_32x32x16_bf16 v[0:15], v[164:167], v[172:175], v[0:15]
	s_waitcnt lgkmcnt(4)
	v_mfma_f32_32x32x16_bf16 v[112:127], v[128:131], v[144:147], v[112:127]
	ds_read_b128 v[168:171], v183 offset:0
	ds_read_b128 v[152:155], v179 offset:0
	s_waitcnt lgkmcnt(5)
	v_mfma_f32_32x32x16_bf16 v[80:95], v[128:131], v[148:151], v[80:95]
	ds_read_b128 v[172:175], v183 offset:4096
	ds_read_b128 v[156:159], v179 offset:4096
	s_waitcnt lgkmcnt(6)
	v_mfma_f32_32x32x16_bf16 v[96:111], v[132:135], v[144:147], v[96:111]
	ds_read_b128 v[160:163], v179 offset:8192
	ds_read_b128 v[164:167], v179 offset:12288
	v_mfma_f32_32x32x16_bf16 v[64:79], v[132:135], v[148:151], v[64:79]
	s_waitcnt lgkmcnt(7)
	v_mfma_f32_32x32x16_bf16 v[48:63], v[136:139], v[144:147], v[48:63]
	v_mfma_f32_32x32x16_bf16 v[16:31], v[136:139], v[148:151], v[16:31]
	s_waitcnt lgkmcnt(6)
	v_mfma_f32_32x32x16_bf16 v[32:47], v[140:143], v[144:147], v[32:47]
	v_mfma_f32_32x32x16_bf16 v[0:15], v[140:143], v[148:151], v[0:15]
	s_waitcnt vmcnt(0) lgkmcnt(0)
	s_barrier
	v_mfma_f32_32x32x16_bf16 v[112:127], v[152:155], v[168:171], v[112:127]
	s_mov_b32 m0, s98
	ds_read_b128 v[144:147], v180 offset:32768
	v_mfma_f32_32x32x16_bf16 v[80:95], v[152:155], v[172:175], v[80:95]
	ds_read_b128 v[128:131], v176 offset:32768
	global_load_lds_dwordx4 v184, s[28:29]
	v_mfma_f32_32x32x16_bf16 v[96:111], v[156:159], v[168:171], v[96:111]
	s_add_u32 m0, s98, 0x400
	ds_read_b128 v[148:151], v180 offset:36864
	v_mfma_f32_32x32x16_bf16 v[64:79], v[156:159], v[172:175], v[64:79]
	ds_read_b128 v[132:135], v176 offset:36864
	global_load_lds_dwordx4 v185, s[28:29]
	v_mfma_f32_32x32x16_bf16 v[48:63], v[160:163], v[168:171], v[48:63]
	s_add_u32 m0, s98, 0x800
	ds_read_b128 v[136:139], v176 offset:40960
	v_mfma_f32_32x32x16_bf16 v[16:31], v[160:163], v[172:175], v[16:31]
	ds_read_b128 v[140:143], v176 offset:45056
	global_load_lds_dwordx4 v186, s[28:29]
	v_mfma_f32_32x32x16_bf16 v[32:47], v[164:167], v[168:171], v[32:47]
	s_add_u32 m0, s98, 0xc00
	v_mfma_f32_32x32x16_bf16 v[0:15], v[164:167], v[172:175], v[0:15]
	global_load_lds_dwordx4 v187, s[28:29]
	s_add_u32 s28, s28, 0x80
	s_addc_u32 s29, s29, 0
	s_waitcnt lgkmcnt(4)
	v_mfma_f32_32x32x16_bf16 v[112:127], v[128:131], v[144:147], v[112:127]
	s_add_u32 m0, s98, 0x10000
	ds_read_b128 v[168:171], v181 offset:32768
	s_waitcnt lgkmcnt(4)
	v_mfma_f32_32x32x16_bf16 v[80:95], v[128:131], v[148:151], v[80:95]
	global_load_lds_dwordx4 v184, s[30:31]
	ds_read_b128 v[152:155], v177 offset:32768
	s_waitcnt lgkmcnt(4)
	v_mfma_f32_32x32x16_bf16 v[96:111], v[132:135], v[144:147], v[96:111]
	s_add_u32 m0, s98, 0x10400
	ds_read_b128 v[172:175], v181 offset:36864
	v_mfma_f32_32x32x16_bf16 v[64:79], v[132:135], v[148:151], v[64:79]
	global_load_lds_dwordx4 v185, s[30:31]
	ds_read_b128 v[156:159], v177 offset:36864
	s_waitcnt lgkmcnt(5)
	v_mfma_f32_32x32x16_bf16 v[48:63], v[136:139], v[144:147], v[48:63]
	s_add_u32 m0, s98, 0x10800
	ds_read_b128 v[160:163], v177 offset:40960
	v_mfma_f32_32x32x16_bf16 v[16:31], v[136:139], v[148:151], v[16:31]
	global_load_lds_dwordx4 v186, s[30:31]
	ds_read_b128 v[164:167], v177 offset:45056
	s_waitcnt lgkmcnt(6)
	v_mfma_f32_32x32x16_bf16 v[32:47], v[140:143], v[144:147], v[32:47]
	s_add_u32 m0, s98, 0x10c00
	v_mfma_f32_32x32x16_bf16 v[0:15], v[140:143], v[148:151], v[0:15]
	global_load_lds_dwordx4 v187, s[30:31]
	s_add_u32 s30, s30, 0x80
	s_addc_u32 s31, s31, 0
	s_waitcnt lgkmcnt(4)
	v_mfma_f32_32x32x16_bf16 v[112:127], v[152:155], v[168:171], v[112:127]
	ds_read_b128 v[144:147], v182 offset:32768
	s_waitcnt lgkmcnt(4)
; DI void gemm_wide(const bf16_t* __restrict__ W, int ldw, const bf16_t* __restrict__ X, int ldx, int nkt,
;                   f32x16 (&acc)[4][2], bf16_t* lds) {
;     ...
;   __syncthreads();
;   GW_GLOAD(0)
;   GW_LSTORE(0)
;   GW_GLOAD(1)
;   GW_GLOAD_B(nkt > 2 ? 2 : nkt - 1)
;   __syncthreads();
;   for (int kt = 0; kt < nkt; kt += 2) {
;     __builtin_amdgcn_sched_barrier(0);
;     GW_ST2(1, 0, rw0, rw1)                         GW_KS(kt, 0)
;     GW_ST2(1, 128 * LDT, rw2, rw3)                 GW_KS(kt, 1)
;     GW_ST2(1, WT_E, rx0, rx1)                      GW_KS(kt, 2)
;     GW_ST2(1, WT_E + 128 * LDT, rx2, rx3)          GW_KS(kt, 3)
;     __builtin_amdgcn_sched_barrier(0);
;     GW_GLOAD(kt + 3 < nkt ? kt + 3 : nkt - 1)
;     __syncthreads();
;     __builtin_amdgcn_sched_barrier(0);
;     GW_ST2(0, 0, sw0, sw1)                         GW_KS(kt + 1, 0)
;     GW_ST2(0, 128 * LDT, sw2, sw3)                 GW_KS(kt + 1, 1)
;     GW_ST2(0, WT_E, sx0, sx1)                      GW_KS(kt + 1, 2)
;     GW_ST2(0, WT_E + 128 * LDT, sx2, sx3)          GW_KS(kt + 1, 3)
;     __builtin_amdgcn_sched_barrier(0);
;     GW_GLOAD_B(kt + 4 < nkt ? kt + 4 : nkt - 1)
;     __syncthreads();
;   }
	v_mfma_f32_32x32x16_bf16 v[80:95], v[152:155], v[172:175], v[80:95]
	ds_read_b128 v[128:131], v178 offset:32768
	s_waitcnt lgkmcnt(4)
	v_mfma_f32_32x32x16_bf16 v[96:111], v[156:159], v[168:171], v[96:111]
	ds_read_b128 v[148:151], v182 offset:36864
	v_mfma_f32_32x32x16_bf16 v[64:79], v[156:159], v[172:175], v[64:79]
	ds_read_b128 v[132:135], v178 offset:36864
	s_waitcnt lgkmcnt(5)
	v_mfma_f32_32x32x16_bf16 v[48:63], v[160:163], v[168:171], v[48:63]
	ds_read_b128 v[136:139], v178 offset:40960
	v_mfma_f32_32x32x16_bf16 v[16:31], v[160:163], v[172:175], v[16:31]
	ds_read_b128 v[140:143], v178 offset:45056
	s_waitcnt lgkmcnt(6)
	v_mfma_f32_32x32x16_bf16 v[32:47], v[164:167], v[168:171], v[32:47]
	v_mfma_f32_32x32x16_bf16 v[0:15], v[164:167], v[172:175], v[0:15]
	s_waitcnt lgkmcnt(4)
	v_mfma_f32_32x32x16_bf16 v[112:127], v[128:131], v[144:147], v[112:127]
	ds_read_b128 v[168:171], v183 offset:32768
	ds_read_b128 v[152:155], v179 offset:32768
	s_waitcnt lgkmcnt(5)
	v_mfma_f32_32x32x16_bf16 v[80:95], v[128:131], v[148:151], v[80:95]
	ds_read_b128 v[172:175], v183 offset:36864
	ds_read_b128 v[156:159], v179 offset:36864
	s_waitcnt lgkmcnt(6)
	v_mfma_f32_32x32x16_bf16 v[96:111], v[132:135], v[144:147], v[96:111]
	ds_read_b128 v[160:163], v179 offset:40960
	ds_read_b128 v[164:167], v179 offset:45056
	v_mfma_f32_32x32x16_bf16 v[64:79], v[132:135], v[148:151], v[64:79]
	s_waitcnt lgkmcnt(7)
	v_mfma_f32_32x32x16_bf16 v[48:63], v[136:139], v[144:147], v[48:63]
	v_mfma_f32_32x32x16_bf16 v[16:31], v[136:139], v[148:151], v[16:31]
	s_waitcnt lgkmcnt(6)
	v_mfma_f32_32x32x16_bf16 v[32:47], v[140:143], v[144:147], v[32:47]
	v_mfma_f32_32x32x16_bf16 v[0:15], v[140:143], v[148:151], v[0:15]
	s_waitcnt vmcnt(0) lgkmcnt(0)
	s_barrier
	v_mfma_f32_32x32x16_bf16 v[112:127], v[152:155], v[168:171], v[112:127]
	s_add_u32 m0, s98, 0x8000
	ds_read_b128 v[144:147], v180 offset:0
	v_mfma_f32_32x32x16_bf16 v[80:95], v[152:155], v[172:175], v[80:95]
	ds_read_b128 v[128:131], v176 offset:0
	global_load_lds_dwordx4 v184, s[28:29]
	v_mfma_f32_32x32x16_bf16 v[96:111], v[156:159], v[168:171], v[96:111]
	s_add_u32 m0, s98, 0x8400
	ds_read_b128 v[148:151], v180 offset:4096
	v_mfma_f32_32x32x16_bf16 v[64:79], v[156:159], v[172:175], v[64:79]
	ds_read_b128 v[132:135], v176 offset:4096
	global_load_lds_dwordx4 v185, s[28:29]
	v_mfma_f32_32x32x16_bf16 v[48:63], v[160:163], v[168:171], v[48:63]
	s_add_u32 m0, s98, 0x8800
	ds_read_b128 v[136:139], v176 offset:8192
	v_mfma_f32_32x32x16_bf16 v[16:31], v[160:163], v[172:175], v[16:31]
	ds_read_b128 v[140:143], v176 offset:12288
	global_load_lds_dwordx4 v186, s[28:29]
	v_mfma_f32_32x32x16_bf16 v[32:47], v[164:167], v[168:171], v[32:47]
	s_add_u32 m0, s98, 0x8c00
	v_mfma_f32_32x32x16_bf16 v[0:15], v[164:167], v[172:175], v[0:15]
	global_load_lds_dwordx4 v187, s[28:29]
	s_add_u32 s28, s28, 0x80
	s_addc_u32 s29, s29, 0
	s_sub_u32 s99, s99, 1
	s_cmp_lg_u32 s99, 0
	s_cbranch_scc1 .Lgw_down_loop
	s_waitcnt lgkmcnt(4)
	v_mfma_f32_32x32x16_bf16 v[112:127], v[128:131], v[144:147], v[112:127]
	s_add_u32 m0, s98, 0x18000
	ds_read_b128 v[168:171], v181 offset:0
	s_waitcnt lgkmcnt(4)
	v_mfma_f32_32x32x16_bf16 v[80:95], v[128:131], v[148:151], v[80:95]
	global_load_lds_dwordx4 v184, s[30:31]
	ds_read_b128 v[152:155], v177 offset:0
	s_waitcnt lgkmcnt(4)
	v_mfma_f32_32x32x16_bf16 v[96:111], v[132:135], v[144:147], v[96:111]
	s_add_u32 m0, s98, 0x18400
	ds_read_b128 v[172:175], v181 offset:4096
	v_mfma_f32_32x32x16_bf16 v[64:79], v[132:135], v[148:151], v[64:79]
	global_load_lds_dwordx4 v185, s[30:31]
	ds_read_b128 v[156:159], v177 offset:4096
	s_waitcnt lgkmcnt(5)
	v_mfma_f32_32x32x16_bf16 v[48:63], v[136:139], v[144:147], v[48:63]
	s_add_u32 m0, s98, 0x18800
	ds_read_b128 v[160:163], v177 offset:8192
	v_mfma_f32_32x32x16_bf16 v[16:31], v[136:139], v[148:151], v[16:31]
	global_load_lds_dwordx4 v186, s[30:31]
	ds_read_b128 v[164:167], v177 offset:12288
	s_waitcnt lgkmcnt(6)
	v_mfma_f32_32x32x16_bf16 v[32:47], v[140:143], v[144:147], v[32:47]
	s_add_u32 m0, s98, 0x18c00
	v_mfma_f32_32x32x16_bf16 v[0:15], v[140:143], v[148:151], v[0:15]
	global_load_lds_dwordx4 v187, s[30:31]
	s_add_u32 s30, s30, 0x80
	s_addc_u32 s31, s31, 0
	s_waitcnt lgkmcnt(4)
	v_mfma_f32_32x32x16_bf16 v[112:127], v[152:155], v[168:171], v[112:127]
	ds_read_b128 v[144:147], v182 offset:0
	s_waitcnt lgkmcnt(4)
	v_mfma_f32_32x32x16_bf16 v[80:95], v[152:155], v[172:175], v[80:95]
	ds_read_b128 v[128:131], v178 offset:0
	s_waitcnt lgkmcnt(4)
	v_mfma_f32_32x32x16_bf16 v[96:111], v[156:159], v[168:171], v[96:111]
	ds_read_b128 v[148:151], v182 offset:4096
	v_mfma_f32_32x32x16_bf16 v[64:79], v[156:159], v[172:175], v[64:79]
	ds_read_b128 v[132:135], v178 offset:4096
	s_waitcnt lgkmcnt(5)
	v_mfma_f32_32x32x16_bf16 v[48:63], v[160:163], v[168:171], v[48:63]
	ds_read_b128 v[136:139], v178 offset:8192
	v_mfma_f32_32x32x16_bf16 v[16:31], v[160:163], v[172:175], v[16:31]
	ds_read_b128 v[140:143], v178 offset:12288
	s_waitcnt lgkmcnt(6)
	v_mfma_f32_32x32x16_bf16 v[32:47], v[164:167], v[168:171], v[32:47]
	v_mfma_f32_32x32x16_bf16 v[0:15], v[164:167], v[172:175], v[0:15]
	s_waitcnt lgkmcnt(4)
	v_mfma_f32_32x32x16_bf16 v[112:127], v[128:131], v[144:147], v[112:127]
	ds_read_b128 v[168:171], v183 offset:0
	ds_read_b128 v[152:155], v179 offset:0
	s_waitcnt lgkmcnt(5)
	v_mfma_f32_32x32x16_bf16 v[80:95], v[128:131], v[148:151], v[80:95]
	ds_read_b128 v[172:175], v183 offset:4096
	ds_read_b128 v[156:159], v179 offset:4096
	s_waitcnt lgkmcnt(6)
	v_mfma_f32_32x32x16_bf16 v[96:111], v[132:135], v[144:147], v[96:111]
	ds_read_b128 v[160:163], v179 offset:8192
	ds_read_b128 v[164:167], v179 offset:12288
	v_mfma_f32_32x32x16_bf16 v[64:79], v[132:135], v[148:151], v[64:79]
	s_waitcnt lgkmcnt(7)
	v_mfma_f32_32x32x16_bf16 v[48:63], v[136:139], v[144:147], v[48:63]
	v_mfma_f32_32x32x16_bf16 v[16:31], v[136:139], v[148:151], v[16:31]
	s_waitcnt lgkmcnt(6)
	v_mfma_f32_32x32x16_bf16 v[32:47], v[140:143], v[144:147], v[32:47]
	v_mfma_f32_32x32x16_bf16 v[0:15], v[140:143], v[148:151], v[0:15]
	s_waitcnt vmcnt(0) lgkmcnt(0)
	s_barrier
; DI void gemm_wide(const bf16_t* __restrict__ W, int ldw, const bf16_t* __restrict__ X, int ldx, int nkt,
;                   f32x16 (&acc)[4][2], bf16_t* lds) {
;     ...
;   for (int kt = 0; kt < nkt; kt += 2) {
;     __builtin_amdgcn_sched_barrier(0);
;     GW_ST2(1, 0, rw0, rw1)                         GW_KS(kt, 0)
;     GW_ST2(1, 128 * LDT, rw2, rw3)                 GW_KS(kt, 1)
;     GW_ST2(1, WT_E, rx0, rx1)                      GW_KS(kt, 2)
;     GW_ST2(1, WT_E + 128 * LDT, rx2, rx3)          GW_KS(kt, 3)
;     __builtin_amdgcn_sched_barrier(0);
;     GW_GLOAD(kt + 3 < nkt ? kt + 3 : nkt - 1)
;     __syncthreads();
;     __builtin_amdgcn_sched_barrier(0);
;     GW_ST2(0, 0, sw0, sw1)                         GW_KS(kt + 1, 0)
;     GW_ST2(0, 128 * LDT, sw2, sw3)                 GW_KS(kt + 1, 1)
;     GW_ST2(0, WT_E, sx0, sx1)                      GW_KS(kt + 1, 2)
;     GW_ST2(0, WT_E + 128 * LDT, sx2, sx3)          GW_KS(kt + 1, 3)
;     __builtin_amdgcn_sched_barrier(0);
;     GW_GLOAD_B(kt + 4 < nkt ? kt + 4 : nkt - 1)
;     __syncthreads();
;   }
; DI void phase_resid(const P& p, const bf16_t* W, const bf16_t* X, int K, bf16_t* sm, const Geo& ge, bool last) {
;     ...
;     float* stg = (float*)sm + wv * (64 * 68);
;     const int m0w = mt_ * 256 + wm * 64, n0w = nt_ * 256 + wn * 128;
; #pragma unroll
;     for (int cp = 0; cp < 2; ++cp) {
; #pragma unroll 4
;       for (int it = 0; it < 8; ++it) {
;         const int row = it * 8 + (lane >> 3), c8 = (lane & 7) * 8;
;         const u32x4 raw = *(const u32x4*)(xb + (size_t)(m0w + row) * LDK1 + n0w + cp * 64 + c8);
	v_mfma_f32_32x32x16_bf16 v[112:127], v[152:155], v[168:171], v[112:127]
	ds_read_b128 v[144:147], v180 offset:32768
	v_mfma_f32_32x32x16_bf16 v[80:95], v[152:155], v[172:175], v[80:95]
	ds_read_b128 v[128:131], v176 offset:32768
	v_mfma_f32_32x32x16_bf16 v[96:111], v[156:159], v[168:171], v[96:111]
	ds_read_b128 v[148:151], v180 offset:36864
	v_mfma_f32_32x32x16_bf16 v[64:79], v[156:159], v[172:175], v[64:79]
	ds_read_b128 v[132:135], v176 offset:36864
	v_mfma_f32_32x32x16_bf16 v[48:63], v[160:163], v[168:171], v[48:63]
	ds_read_b128 v[136:139], v176 offset:40960
	v_mfma_f32_32x32x16_bf16 v[16:31], v[160:163], v[172:175], v[16:31]
	ds_read_b128 v[140:143], v176 offset:45056
	v_mfma_f32_32x32x16_bf16 v[32:47], v[164:167], v[168:171], v[32:47]
	v_mfma_f32_32x32x16_bf16 v[0:15], v[164:167], v[172:175], v[0:15]
	s_waitcnt lgkmcnt(4)
	v_mfma_f32_32x32x16_bf16 v[112:127], v[128:131], v[144:147], v[112:127]
	ds_read_b128 v[168:171], v181 offset:32768
	s_waitcnt lgkmcnt(4)
	v_mfma_f32_32x32x16_bf16 v[80:95], v[128:131], v[148:151], v[80:95]
	ds_read_b128 v[152:155], v177 offset:32768
	s_waitcnt lgkmcnt(4)
	v_mfma_f32_32x32x16_bf16 v[96:111], v[132:135], v[144:147], v[96:111]
	ds_read_b128 v[172:175], v181 offset:36864
	v_mfma_f32_32x32x16_bf16 v[64:79], v[132:135], v[148:151], v[64:79]
	ds_read_b128 v[156:159], v177 offset:36864
	s_waitcnt lgkmcnt(5)
	v_mfma_f32_32x32x16_bf16 v[48:63], v[136:139], v[144:147], v[48:63]
	ds_read_b128 v[160:163], v177 offset:40960
	v_mfma_f32_32x32x16_bf16 v[16:31], v[136:139], v[148:151], v[16:31]
	ds_read_b128 v[164:167], v177 offset:45056
	s_waitcnt lgkmcnt(6)
	v_mfma_f32_32x32x16_bf16 v[32:47], v[140:143], v[144:147], v[32:47]
	v_mfma_f32_32x32x16_bf16 v[0:15], v[140:143], v[148:151], v[0:15]
	s_waitcnt lgkmcnt(4)
	v_mfma_f32_32x32x16_bf16 v[112:127], v[152:155], v[168:171], v[112:127]
	ds_read_b128 v[144:147], v182 offset:32768
	s_waitcnt lgkmcnt(4)
	v_mfma_f32_32x32x16_bf16 v[80:95], v[152:155], v[172:175], v[80:95]
	ds_read_b128 v[128:131], v178 offset:32768
	s_waitcnt lgkmcnt(4)
	v_mfma_f32_32x32x16_bf16 v[96:111], v[156:159], v[168:171], v[96:111]
	ds_read_b128 v[148:151], v182 offset:36864
	v_mfma_f32_32x32x16_bf16 v[64:79], v[156:159], v[172:175], v[64:79]
	ds_read_b128 v[132:135], v178 offset:36864
	s_waitcnt lgkmcnt(5)
	v_mfma_f32_32x32x16_bf16 v[48:63], v[160:163], v[168:171], v[48:63]
	ds_read_b128 v[136:139], v178 offset:40960
	v_mfma_f32_32x32x16_bf16 v[16:31], v[160:163], v[172:175], v[16:31]
	ds_read_b128 v[140:143], v178 offset:45056
	s_waitcnt lgkmcnt(6)
	v_mfma_f32_32x32x16_bf16 v[32:47], v[164:167], v[168:171], v[32:47]
	v_mfma_f32_32x32x16_bf16 v[0:15], v[164:167], v[172:175], v[0:15]
	s_waitcnt lgkmcnt(4)
	v_mfma_f32_32x32x16_bf16 v[112:127], v[128:131], v[144:147], v[112:127]
	ds_read_b128 v[168:171], v183 offset:32768
	ds_read_b128 v[152:155], v179 offset:32768
	s_waitcnt lgkmcnt(5)
	v_mfma_f32_32x32x16_bf16 v[80:95], v[128:131], v[148:151], v[80:95]
	ds_read_b128 v[172:175], v183 offset:36864
	ds_read_b128 v[156:159], v179 offset:36864
	s_waitcnt lgkmcnt(6)
	v_mfma_f32_32x32x16_bf16 v[96:111], v[132:135], v[144:147], v[96:111]
	ds_read_b128 v[160:163], v179 offset:40960
	ds_read_b128 v[164:167], v179 offset:45056
	v_mfma_f32_32x32x16_bf16 v[64:79], v[132:135], v[148:151], v[64:79]
	s_waitcnt lgkmcnt(7)
	v_mfma_f32_32x32x16_bf16 v[48:63], v[136:139], v[144:147], v[48:63]
	v_mfma_f32_32x32x16_bf16 v[16:31], v[136:139], v[148:151], v[16:31]
	s_waitcnt lgkmcnt(6)
	v_mfma_f32_32x32x16_bf16 v[32:47], v[140:143], v[144:147], v[32:47]
	v_mfma_f32_32x32x16_bf16 v[0:15], v[140:143], v[148:151], v[0:15]
	s_waitcnt vmcnt(0) lgkmcnt(0)
	s_barrier
	v_mfma_f32_32x32x16_bf16 v[112:127], v[152:155], v[168:171], v[112:127]
	v_mfma_f32_32x32x16_bf16 v[80:95], v[152:155], v[172:175], v[80:95]
	v_mfma_f32_32x32x16_bf16 v[96:111], v[156:159], v[168:171], v[96:111]
	v_mfma_f32_32x32x16_bf16 v[64:79], v[156:159], v[172:175], v[64:79]
	v_mfma_f32_32x32x16_bf16 v[48:63], v[160:163], v[168:171], v[48:63]
	v_mfma_f32_32x32x16_bf16 v[16:31], v[160:163], v[172:175], v[16:31]
	v_mfma_f32_32x32x16_bf16 v[32:47], v[164:167], v[168:171], v[32:47]
	v_mfma_f32_32x32x16_bf16 v[0:15], v[164:167], v[172:175], v[0:15]
	s_nop 15
	s_waitcnt vmcnt(9)
	v_lshl_or_b32 v128, s8, 8, v237
	v_ashrrev_i32_e32 v129, 31, v128
	s_lshl_b32 s9, s5, 8
	s_waitcnt vmcnt(1)
	v_lshl_add_u64 v[132:133], v[128:129], 1, v[196:197]
	v_add_u32_e32 v137, s9, v240
	s_mov_b32 s5, 0
	v_mov_b32_e32 v130, v239

; __global__ void __launch_bounds__(512, 2) mega(P p) {
	.amdhsa_kernel _Z4mega1P
		.amdhsa_group_segment_fixed_size 0
		.amdhsa_private_segment_fixed_size 0
		.amdhsa_kernarg_size 400
		.amdhsa_user_sgpr_count 2
		.amdhsa_user_sgpr_dispatch_ptr 0
		.amdhsa_user_sgpr_queue_ptr 0
		.amdhsa_user_sgpr_kernarg_segment_ptr 1
		.amdhsa_user_sgpr_dispatch_id 0
		.amdhsa_user_sgpr_kernarg_preload_length 0
		.amdhsa_user_sgpr_kernarg_preload_offset 0
		.amdhsa_user_sgpr_private_segment_size 0
		.amdhsa_uses_dynamic_stack 0
		.amdhsa_enable_private_segment 0
		.amdhsa_system_sgpr_workgroup_id_x 1
		.amdhsa_system_sgpr_workgroup_id_y 0
		.amdhsa_system_sgpr_workgroup_id_z 0
		.amdhsa_system_sgpr_workgroup_info 0
		.amdhsa_system_vgpr_workitem_id 2
		.amdhsa_next_free_vgpr 256
		.amdhsa_next_free_sgpr 102
		.amdhsa_accum_offset 256
		.amdhsa_reserve_vcc 1
		.amdhsa_float_round_mode_32 0
		.amdhsa_float_round_mode_16_64 0
		.amdhsa_float_denorm_mode_32 3
		.amdhsa_float_denorm_mode_16_64 3
		.amdhsa_dx10_clamp 1
		.amdhsa_ieee_mode 1
		.amdhsa_fp16_overflow 0
		.amdhsa_tg_split 0
		.amdhsa_exception_fp_ieee_invalid_op 0
		.amdhsa_exception_fp_denorm_src 0
		.amdhsa_exception_fp_ieee_div_zero 0
		.amdhsa_exception_fp_ieee_overflow 0
		.amdhsa_exception_fp_ieee_underflow 0
		.amdhsa_exception_fp_ieee_inexact 0
		.amdhsa_exception_int_div_zero 0
	.end_amdhsa_kernel

; __global__ void __launch_bounds__(512, 2) mega(P p) {
amdhsa.kernels:
  - .agpr_count:     0
    .args:
      - .offset:         0
        .size:           144
        .value_kind:     by_value
      - .offset:         144
        .size:           4
        .value_kind:     hidden_block_count_x
      - .offset:         148
        .size:           4
        .value_kind:     hidden_block_count_y
      - .offset:         152
        .size:           4
        .value_kind:     hidden_block_count_z
      - .offset:         156
        .size:           2
        .value_kind:     hidden_group_size_x
      - .offset:         158
        .size:           2
        .value_kind:     hidden_group_size_y
      - .offset:         160
        .size:           2
        .value_kind:     hidden_group_size_z
      - .offset:         162
        .size:           2
        .value_kind:     hidden_remainder_x
      - .offset:         164
        .size:           2
        .value_kind:     hidden_remainder_y
      - .offset:         166
        .size:           2
        .value_kind:     hidden_remainder_z
      - .offset:         184
        .size:           8
        .value_kind:     hidden_global_offset_x
      - .offset:         192
        .size:           8
        .value_kind:     hidden_global_offset_y
      - .offset:         200
        .size:           8
        .value_kind:     hidden_global_offset_z
      - .offset:         208
        .size:           2
        .value_kind:     hidden_grid_dims
      - .offset:         232
        .size:           8
        .value_kind:     hidden_multigrid_sync_arg
      - .offset:         264
        .size:           4
        .value_kind:     hidden_dynamic_lds_size
    .group_segment_fixed_size: 0
    .kernarg_segment_align: 8
    .kernarg_segment_size: 400
    .language:       OpenCL C
    .language_version:
      - 2
      - 0
    .max_flat_workgroup_size: 512
    .name:           _Z4mega1P
    .private_segment_fixed_size: 0
    .sgpr_count:     108
    .sgpr_spill_count: 169
    .symbol:         _Z4mega1P.kd
    .uniform_work_group_size: 1
    .uses_dynamic_stack: false
    .vgpr_count:     256
    .vgpr_spill_count: 0
    .wavefront_size: 64
